# A/B: all s_setprio removed from the GEMM K-loops (age-based arbitration only), otherwise as the priority-swap version
# baseline (speedup 1.0000x reference)
; #define PG8_STAGE(bufoff, gbase, voff) do { _Pragma("unroll") for (int _i = 0; _i < 2; ++_i) \
;         __builtin_amdgcn_global_load_lds((const unsigned*)((const char*)(gbase) + (voff)[_i]), (PG8_LAS unsigned*)(lds + (bufoff) + ldsw + _i * 8192), 16, 0, 0); } while (0)
; #define PG8_LDA(dst, b, h) do { _Pragma("unroll") for (int m = 0; m < 4; ++m) _Pragma("unroll") for (int k = 0; k < 2; ++k) dst[m][k] = *(const PG8_LAS bf16x8*)(lds + PG8_SA(b, h) + aoff + m * 2048 + k * 1024); } while (0)
; #define PG8_LDB(dst, b, h) do { _Pragma("unroll") for (int n = 0; n < 2; ++n) _Pragma("unroll") for (int k = 0; k < 2; ++k) dst[n][k] = *(const PG8_LAS bf16x8*)(lds + PG8_SB(b, h) + boff + n * 2048 + k * 1024); } while (0)
; #define PG8_MMA(ai, bj, At, Bt) do { __builtin_amdgcn_s_setprio(1); _Pragma("unroll") for (int m = 0; m < 4; ++m) _Pragma("unroll") for (int n = 0; n < 2; ++n) _Pragma("unroll") for (int k = 0; k < 2; ++k) \
;         acc[ai][bj][m][n] = __builtin_amdgcn_mfma_f32_16x16x32_bf16(Bt[n][k], At[m][k], acc[ai][bj][m][n], 0, 0, 0); __builtin_amdgcn_s_setprio(0); } while (0)
; #define PG8_WAIT_V(n) asm volatile("s_waitcnt vmcnt(" #n ")" ::: "memory")
; #define PG8_WAIT_L(n) asm volatile("s_waitcnt lgkmcnt(" #n ")" ::: "memory")
; template <class Epi, class Sched, bool ALIGN_EPI = false, bool SP2 = false>
; __device__ __forceinline__ void gemm_phase(PG8_LAS unsigned char* lds, const Gemm g, const Sched& S, const Epi& E) {
;     ...
;             const bool last = (t == nt - 2);
;             const char* a1 = cA + (size_t)(t + 1) * kstep;
;             const char* a2 = last ? nA : cA + (size_t)(t + 2) * kstep; const char* b2 = last ? nB : cB + (size_t)(t + 2) * kstep;
;             const char* a3 = a2 + kstep; const char* b3 = b2 + kstep;
;             if (last && has_next) S.a_ready(nxt);
;             if constexpr (SP2) {
;             PG8_LDB(B0, 0, 0); PG8_LDB(B1, 0, 1); PG8_SCHED; PG8_LDA(At, 0, 0); PG8_STAGE(PG8_SA(1, 1), a1 + hstepA, voffA);
;             PG8_WAIT_V(8); PG8_WAIT_L(0); PG8_BAR; PG8_MMA(0, 0, At, B0); PG8_MMA(0, 1, At, B1); PG8_BAR; PG8_SCHED;
;             PG8_LDA(At, 0, 1); PG8_STAGE(PG8_SB(0, 0), b2, voffB); PG8_STAGE(PG8_SB(0, 1), b2 + hstepB, voffB); PG8_STAGE(PG8_SA(0, 0), a2, voffA);
;             PG8_WAIT_V(8); PG8_WAIT_L(0); PG8_BAR; PG8_MMA(1, 0, At, B0); PG8_MMA(1, 1, At, B1); PG8_BAR; PG8_SCHED;
.LBB0_311:
	ds_read_b128 v[148:151], v176
	ds_read_b128 v[152:155], v176 offset:1024
	ds_read_b128 v[156:159], v176 offset:2048
	ds_read_b128 v[180:183], v176 offset:3072
	ds_read_b128 v[184:187], v177
	ds_read_b128 v[188:191], v177 offset:1024
	ds_read_b128 v[192:195], v177 offset:2048
	ds_read_b128 v[196:199], v177 offset:3072
	s_add_u32 s68, s6, 0xfff80080
	s_addc_u32 s69, s7, -1
	s_cmp_eq_u32 s78, 28
	s_cselect_b32 s71, s20, s69
	s_cselect_b32 s70, s33, s68
	s_cselect_b32 s69, s55, s77
	s_cselect_b32 s68, s61, s76
	s_add_i32 m0, s9, 0xc000
	ds_read_b128 v[200:203], v178
	ds_read_b128 v[204:207], v178 offset:1024
	ds_read_b128 v[208:211], v178 offset:2048
	ds_read_b128 v[212:215], v178 offset:3072
	ds_read_b128 v[216:219], v178 offset:4096
	ds_read_b128 v[220:223], v178 offset:5120
	ds_read_b128 v[224:227], v178 offset:6144
	ds_read_b128 v[228:231], v178 offset:7168
	global_load_lds_dwordx4 v140, s[6:7]
	s_add_i32 m0, s9, 0xe000
	s_nop 0
	global_load_lds_dwordx4 v142, s[6:7]
	s_waitcnt vmcnt(8)
	s_waitcnt lgkmcnt(0)
	s_barrier
	s_waitcnt lgkmcnt(0)
	v_mfma_f32_16x16x32_bf16 v[124:127], v[148:151], v[200:203], v[124:127]
	v_mfma_f32_16x16x32_bf16 v[120:123], v[156:159], v[200:203], v[120:123]
	v_mfma_f32_16x16x32_bf16 v[108:111], v[148:151], v[208:211], v[108:111]
	v_mfma_f32_16x16x32_bf16 v[104:107], v[156:159], v[208:211], v[104:107]
	v_mfma_f32_16x16x32_bf16 v[92:95], v[148:151], v[216:219], v[92:95]
	v_mfma_f32_16x16x32_bf16 v[88:91], v[156:159], v[216:219], v[88:91]
	v_mfma_f32_16x16x32_bf16 v[76:79], v[148:151], v[224:227], v[76:79]
	v_mfma_f32_16x16x32_bf16 v[72:75], v[156:159], v[224:227], v[72:75]
	v_mfma_f32_16x16x32_bf16 v[124:127], v[152:155], v[204:207], v[124:127]
	v_mfma_f32_16x16x32_bf16 v[120:123], v[180:183], v[204:207], v[120:123]
	v_mfma_f32_16x16x32_bf16 v[108:111], v[152:155], v[212:215], v[108:111]
	v_mfma_f32_16x16x32_bf16 v[104:107], v[180:183], v[212:215], v[104:107]
	v_mfma_f32_16x16x32_bf16 v[92:95], v[152:155], v[220:223], v[92:95]
	v_mfma_f32_16x16x32_bf16 v[88:91], v[180:183], v[220:223], v[88:91]
	v_mfma_f32_16x16x32_bf16 v[76:79], v[152:155], v[228:231], v[76:79]
	v_mfma_f32_16x16x32_bf16 v[72:75], v[180:183], v[228:231], v[72:75]
	v_mfma_f32_16x16x32_bf16 v[116:119], v[184:187], v[200:203], v[116:119]
	v_mfma_f32_16x16x32_bf16 v[112:115], v[192:195], v[200:203], v[112:115]
	v_mfma_f32_16x16x32_bf16 v[100:103], v[184:187], v[208:211], v[100:103]
	v_mfma_f32_16x16x32_bf16 v[96:99], v[192:195], v[208:211], v[96:99]
	v_mfma_f32_16x16x32_bf16 v[84:87], v[184:187], v[216:219], v[84:87]
	v_mfma_f32_16x16x32_bf16 v[80:83], v[192:195], v[216:219], v[80:83]
	v_mfma_f32_16x16x32_bf16 v[68:71], v[184:187], v[224:227], v[68:71]
	v_mfma_f32_16x16x32_bf16 v[64:67], v[192:195], v[224:227], v[64:67]
	v_mfma_f32_16x16x32_bf16 v[116:119], v[188:191], v[204:207], v[116:119]
	v_mfma_f32_16x16x32_bf16 v[112:115], v[196:199], v[204:207], v[112:115]
	v_mfma_f32_16x16x32_bf16 v[100:103], v[188:191], v[212:215], v[100:103]
	v_mfma_f32_16x16x32_bf16 v[96:99], v[196:199], v[212:215], v[96:99]
	v_mfma_f32_16x16x32_bf16 v[84:87], v[188:191], v[220:223], v[84:87]
	v_mfma_f32_16x16x32_bf16 v[80:83], v[196:199], v[220:223], v[80:83]
	v_mfma_f32_16x16x32_bf16 v[68:71], v[188:191], v[228:231], v[68:71]
	v_mfma_f32_16x16x32_bf16 v[64:67], v[196:199], v[228:231], v[64:67]
	s_barrier
	s_add_i32 s79, s72, s28
	v_lshl_add_u64 v[160:161], s[68:69], 0, v[130:131]
	s_mov_b32 m0, s79
	ds_read_b128 v[200:203], v178 offset:16384
	ds_read_b128 v[204:207], v178 offset:17408
	ds_read_b128 v[208:211], v178 offset:18432
	ds_read_b128 v[212:215], v178 offset:19456
	ds_read_b128 v[216:219], v178 offset:20480
	ds_read_b128 v[220:223], v178 offset:21504
	ds_read_b128 v[224:227], v178 offset:22528
	ds_read_b128 v[228:231], v178 offset:23552
	global_load_lds_dwordx4 v130, s[68:69]
	s_add_i32 m0, s79, 0x2000
	s_add_u32 s80, s68, 0x80000
	v_lshl_add_u64 v[232:233], s[68:69], 0, v[134:135]
	s_addc_u32 s81, s69, 0
	s_add_i32 s79, s73, s28
	global_load_lds_dwordx4 v134, s[68:69]
	s_mov_b32 m0, s79
	v_lshl_add_u64 v[236:237], s[70:71], 0, v[132:133]
	global_load_lds_dwordx4 v130, s[80:81]
	s_add_i32 m0, s79, 0x2000
	s_nop 0
	global_load_lds_dwordx4 v134, s[80:81]
	v_lshl_add_u64 v[234:235], s[70:71], 0, v[128:129]
	s_mov_b32 m0, s9
	s_nop 0
	global_load_lds_dwordx4 v128, s[70:71]
	s_mov_b32 m0, s19
	s_nop 0
	global_load_lds_dwordx4 v132, s[70:71]
	s_waitcnt vmcnt(8)
	s_waitcnt lgkmcnt(0)
	s_barrier
	s_waitcnt lgkmcnt(0)
	v_mfma_f32_16x16x32_bf16 v[60:63], v[148:151], v[200:203], v[60:63]
	v_mfma_f32_16x16x32_bf16 v[56:59], v[156:159], v[200:203], v[56:59]
	v_mfma_f32_16x16x32_bf16 v[44:47], v[148:151], v[208:211], v[44:47]
	v_mfma_f32_16x16x32_bf16 v[40:43], v[156:159], v[208:211], v[40:43]
	v_mfma_f32_16x16x32_bf16 v[28:31], v[148:151], v[216:219], v[28:31]
	v_mfma_f32_16x16x32_bf16 v[24:27], v[156:159], v[216:219], v[24:27]
	v_mfma_f32_16x16x32_bf16 v[12:15], v[148:151], v[224:227], v[12:15]
	v_mfma_f32_16x16x32_bf16 v[8:11], v[156:159], v[224:227], v[8:11]
	v_mfma_f32_16x16x32_bf16 v[60:63], v[152:155], v[204:207], v[60:63]
	v_mfma_f32_16x16x32_bf16 v[56:59], v[180:183], v[204:207], v[56:59]
	v_mfma_f32_16x16x32_bf16 v[44:47], v[152:155], v[212:215], v[44:47]
	v_mfma_f32_16x16x32_bf16 v[40:43], v[180:183], v[212:215], v[40:43]
	v_mfma_f32_16x16x32_bf16 v[28:31], v[152:155], v[220:223], v[28:31]
	v_mfma_f32_16x16x32_bf16 v[24:27], v[180:183], v[220:223], v[24:27]
	v_mfma_f32_16x16x32_bf16 v[12:15], v[152:155], v[228:231], v[12:15]
	v_mfma_f32_16x16x32_bf16 v[8:11], v[180:183], v[228:231], v[8:11]
	v_mfma_f32_16x16x32_bf16 v[52:55], v[184:187], v[200:203], v[52:55]
	v_mfma_f32_16x16x32_bf16 v[48:51], v[192:195], v[200:203], v[48:51]
	v_mfma_f32_16x16x32_bf16 v[36:39], v[184:187], v[208:211], v[36:39]
	v_mfma_f32_16x16x32_bf16 v[32:35], v[192:195], v[208:211], v[32:35]
	v_mfma_f32_16x16x32_bf16 v[20:23], v[184:187], v[216:219], v[20:23]
	v_mfma_f32_16x16x32_bf16 v[16:19], v[192:195], v[216:219], v[16:19]
	v_mfma_f32_16x16x32_bf16 v[4:7], v[184:187], v[224:227], v[4:7]
	v_mfma_f32_16x16x32_bf16 v[0:3], v[192:195], v[224:227], v[0:3]
	v_mfma_f32_16x16x32_bf16 v[52:55], v[188:191], v[204:207], v[52:55]
	v_mfma_f32_16x16x32_bf16 v[48:51], v[196:199], v[204:207], v[48:51]
	v_mfma_f32_16x16x32_bf16 v[36:39], v[188:191], v[212:215], v[36:39]
	v_mfma_f32_16x16x32_bf16 v[32:35], v[196:199], v[212:215], v[32:35]
	v_mfma_f32_16x16x32_bf16 v[20:23], v[188:191], v[220:223], v[20:23]
	v_mfma_f32_16x16x32_bf16 v[16:19], v[196:199], v[220:223], v[16:19]
	v_mfma_f32_16x16x32_bf16 v[4:7], v[188:191], v[228:231], v[4:7]
	v_mfma_f32_16x16x32_bf16 v[0:3], v[196:199], v[228:231], v[0:3]
	s_barrier
; #define PG8_STAGE(bufoff, gbase, voff) do { _Pragma("unroll") for (int _i = 0; _i < 2; ++_i) \
;         __builtin_amdgcn_global_load_lds((const unsigned*)((const char*)(gbase) + (voff)[_i]), (PG8_LAS unsigned*)(lds + (bufoff) + ldsw + _i * 8192), 16, 0, 0); } while (0)
; #define PG8_LDA(dst, b, h) do { _Pragma("unroll") for (int m = 0; m < 4; ++m) _Pragma("unroll") for (int k = 0; k < 2; ++k) dst[m][k] = *(const PG8_LAS bf16x8*)(lds + PG8_SA(b, h) + aoff + m * 2048 + k * 1024); } while (0)
; #define PG8_LDB(dst, b, h) do { _Pragma("unroll") for (int n = 0; n < 2; ++n) _Pragma("unroll") for (int k = 0; k < 2; ++k) dst[n][k] = *(const PG8_LAS bf16x8*)(lds + PG8_SB(b, h) + boff + n * 2048 + k * 1024); } while (0)
; #define PG8_MMA(ai, bj, At, Bt) do { __builtin_amdgcn_s_setprio(1); _Pragma("unroll") for (int m = 0; m < 4; ++m) _Pragma("unroll") for (int n = 0; n < 2; ++n) _Pragma("unroll") for (int k = 0; k < 2; ++k) \
;         acc[ai][bj][m][n] = __builtin_amdgcn_mfma_f32_16x16x32_bf16(Bt[n][k], At[m][k], acc[ai][bj][m][n], 0, 0, 0); __builtin_amdgcn_s_setprio(0); } while (0)
; #define PG8_WAIT_V(n) asm volatile("s_waitcnt vmcnt(" #n ")" ::: "memory")
; #define PG8_WAIT_L(n) asm volatile("s_waitcnt lgkmcnt(" #n ")" ::: "memory")
; #define PG8_BAR __builtin_amdgcn_s_barrier()
; #define PG8_SCHED __builtin_amdgcn_sched_barrier(0)
; template <class Epi, class Sched, bool ALIGN_EPI = false, bool SP2 = false>
; __device__ __forceinline__ void gemm_phase(PG8_LAS unsigned char* lds, const Gemm g, const Sched& S, const Epi& E) {
;     ...
;             PG8_LDB(B0, 1, 0); PG8_LDB(B1, 1, 1); PG8_SCHED; PG8_LDA(At, 1, 0); PG8_STAGE(PG8_SA(0, 1), a2 + hstepA, voffA);
;             PG8_WAIT_V(8); PG8_WAIT_L(0); PG8_BAR; PG8_MMA(0, 0, At, B0); PG8_MMA(0, 1, At, B1); PG8_BAR; PG8_SCHED;
;             PG8_LDA(At, 1, 1); PG8_STAGE(PG8_SB(1, 0), b3, voffB); PG8_STAGE(PG8_SB(1, 1), b3 + hstepB, voffB); PG8_STAGE(PG8_SA(1, 0), a3, voffA);
;             PG8_WAIT_V(8); PG8_WAIT_L(0); PG8_BAR; PG8_MMA(1, 0, At, B0); PG8_MMA(1, 1, At, B1); PG8_BAR; PG8_SCHED;
	s_add_i32 s79, 0, 0x18000
	v_add_u32_e32 v138, s79, v174
	s_add_i32 s80, 0, 0x1c000
	ds_read_b128 v[148:151], v138
	ds_read_b128 v[152:155], v138 offset:1024
	ds_read_b128 v[156:159], v138 offset:2048
	ds_read_b128 v[180:183], v138 offset:3072
	v_add_u32_e32 v138, s80, v174
	ds_read_b128 v[184:187], v138
	ds_read_b128 v[188:191], v138 offset:1024
	ds_read_b128 v[192:195], v138 offset:2048
	ds_read_b128 v[196:199], v138 offset:3072
	s_add_u32 s70, s70, 0x80000
	s_addc_u32 s71, s71, 0
	s_mov_b32 m0, s29
	ds_read_b128 v[200:203], v178 offset:32768
	ds_read_b128 v[204:207], v178 offset:33792
	ds_read_b128 v[208:211], v178 offset:34816
	ds_read_b128 v[212:215], v178 offset:35840
	ds_read_b128 v[216:219], v178 offset:36864
	ds_read_b128 v[220:223], v178 offset:37888
	ds_read_b128 v[224:227], v178 offset:38912
	ds_read_b128 v[228:231], v178 offset:39936
	global_load_lds_dwordx4 v128, s[70:71]
	s_mov_b32 m0, s30
	s_nop 0
	global_load_lds_dwordx4 v132, s[70:71]
	s_waitcnt vmcnt(8)
	s_waitcnt lgkmcnt(0)
	s_barrier
	s_waitcnt lgkmcnt(0)
	v_mfma_f32_16x16x32_bf16 v[124:127], v[148:151], v[200:203], v[124:127]
	v_mfma_f32_16x16x32_bf16 v[120:123], v[156:159], v[200:203], v[120:123]
	v_mfma_f32_16x16x32_bf16 v[108:111], v[148:151], v[208:211], v[108:111]
	v_mfma_f32_16x16x32_bf16 v[104:107], v[156:159], v[208:211], v[104:107]
	v_mfma_f32_16x16x32_bf16 v[92:95], v[148:151], v[216:219], v[92:95]
	v_mfma_f32_16x16x32_bf16 v[88:91], v[156:159], v[216:219], v[88:91]
	v_mfma_f32_16x16x32_bf16 v[76:79], v[148:151], v[224:227], v[76:79]
	v_mfma_f32_16x16x32_bf16 v[72:75], v[156:159], v[224:227], v[72:75]
	v_mfma_f32_16x16x32_bf16 v[124:127], v[152:155], v[204:207], v[124:127]
	v_mfma_f32_16x16x32_bf16 v[120:123], v[180:183], v[204:207], v[120:123]
	v_mfma_f32_16x16x32_bf16 v[108:111], v[152:155], v[212:215], v[108:111]
	v_mfma_f32_16x16x32_bf16 v[104:107], v[180:183], v[212:215], v[104:107]
	v_mfma_f32_16x16x32_bf16 v[92:95], v[152:155], v[220:223], v[92:95]
	v_mfma_f32_16x16x32_bf16 v[88:91], v[180:183], v[220:223], v[88:91]
	v_mfma_f32_16x16x32_bf16 v[76:79], v[152:155], v[228:231], v[76:79]
	v_mfma_f32_16x16x32_bf16 v[72:75], v[180:183], v[228:231], v[72:75]
	v_mfma_f32_16x16x32_bf16 v[116:119], v[184:187], v[200:203], v[116:119]
	v_mfma_f32_16x16x32_bf16 v[112:115], v[192:195], v[200:203], v[112:115]
	v_mfma_f32_16x16x32_bf16 v[100:103], v[184:187], v[208:211], v[100:103]
	v_mfma_f32_16x16x32_bf16 v[96:99], v[192:195], v[208:211], v[96:99]
	v_mfma_f32_16x16x32_bf16 v[84:87], v[184:187], v[216:219], v[84:87]
	v_mfma_f32_16x16x32_bf16 v[80:83], v[192:195], v[216:219], v[80:83]
	v_mfma_f32_16x16x32_bf16 v[68:71], v[184:187], v[224:227], v[68:71]
	v_mfma_f32_16x16x32_bf16 v[64:67], v[192:195], v[224:227], v[64:67]
	v_mfma_f32_16x16x32_bf16 v[116:119], v[188:191], v[204:207], v[116:119]
	v_mfma_f32_16x16x32_bf16 v[112:115], v[196:199], v[204:207], v[112:115]
	v_mfma_f32_16x16x32_bf16 v[100:103], v[188:191], v[212:215], v[100:103]
	v_mfma_f32_16x16x32_bf16 v[96:99], v[196:199], v[212:215], v[96:99]
	v_mfma_f32_16x16x32_bf16 v[84:87], v[188:191], v[220:223], v[84:87]
	v_mfma_f32_16x16x32_bf16 v[80:83], v[196:199], v[220:223], v[80:83]
	v_mfma_f32_16x16x32_bf16 v[68:71], v[188:191], v[228:231], v[68:71]
	v_mfma_f32_16x16x32_bf16 v[64:67], v[196:199], v[228:231], v[64:67]
	s_barrier
	s_add_i32 s70, s79, s28
	v_lshl_add_u64 v[160:161], v[160:161], 0, s[46:47]
	s_mov_b32 m0, s70
	ds_read_b128 v[200:203], v178 offset:49152
	ds_read_b128 v[204:207], v178 offset:50176
	ds_read_b128 v[208:211], v178 offset:51200
	ds_read_b128 v[212:215], v178 offset:52224
	ds_read_b128 v[216:219], v178 offset:53248
	ds_read_b128 v[220:223], v178 offset:54272
	ds_read_b128 v[224:227], v178 offset:55296
	ds_read_b128 v[228:231], v178 offset:56320
	global_load_lds_dwordx4 v[160:161], off
	s_add_i32 m0, s70, 0x2000
	s_add_u32 s68, s68, 0x80080
	v_lshl_add_u64 v[160:161], v[232:233], 0, s[46:47]
	s_addc_u32 s69, s69, 0
	s_add_i32 s70, s80, s28
	global_load_lds_dwordx4 v[160:161], off
	s_mov_b32 m0, s70
	s_nop 0
	global_load_lds_dwordx4 v130, s[68:69]
	s_add_i32 m0, s70, 0x2000
	s_nop 0
	global_load_lds_dwordx4 v134, s[68:69]
	v_lshl_add_u64 v[160:161], v[234:235], 0, s[46:47]
	s_mov_b32 m0, s34
	s_nop 0
	global_load_lds_dwordx4 v[160:161], off
	v_lshl_add_u64 v[160:161], v[236:237], 0, s[46:47]
	s_mov_b32 m0, s35
	s_nop 0
	global_load_lds_dwordx4 v[160:161], off
	s_waitcnt vmcnt(8)
	s_waitcnt lgkmcnt(0)
	s_barrier
	s_waitcnt lgkmcnt(0)
	v_mfma_f32_16x16x32_bf16 v[60:63], v[148:151], v[200:203], v[60:63]
	v_mfma_f32_16x16x32_bf16 v[56:59], v[156:159], v[200:203], v[56:59]
	v_mfma_f32_16x16x32_bf16 v[44:47], v[148:151], v[208:211], v[44:47]
	v_mfma_f32_16x16x32_bf16 v[40:43], v[156:159], v[208:211], v[40:43]
	v_mfma_f32_16x16x32_bf16 v[28:31], v[148:151], v[216:219], v[28:31]
	v_mfma_f32_16x16x32_bf16 v[24:27], v[156:159], v[216:219], v[24:27]
	v_mfma_f32_16x16x32_bf16 v[12:15], v[148:151], v[224:227], v[12:15]
	v_mfma_f32_16x16x32_bf16 v[8:11], v[156:159], v[224:227], v[8:11]
	v_mfma_f32_16x16x32_bf16 v[60:63], v[152:155], v[204:207], v[60:63]
	v_mfma_f32_16x16x32_bf16 v[56:59], v[180:183], v[204:207], v[56:59]
	v_mfma_f32_16x16x32_bf16 v[44:47], v[152:155], v[212:215], v[44:47]
	v_mfma_f32_16x16x32_bf16 v[40:43], v[180:183], v[212:215], v[40:43]
	v_mfma_f32_16x16x32_bf16 v[28:31], v[152:155], v[220:223], v[28:31]
	v_mfma_f32_16x16x32_bf16 v[24:27], v[180:183], v[220:223], v[24:27]
	v_mfma_f32_16x16x32_bf16 v[12:15], v[152:155], v[228:231], v[12:15]
	v_mfma_f32_16x16x32_bf16 v[8:11], v[180:183], v[228:231], v[8:11]
	v_mfma_f32_16x16x32_bf16 v[52:55], v[184:187], v[200:203], v[52:55]
	v_mfma_f32_16x16x32_bf16 v[48:51], v[192:195], v[200:203], v[48:51]
	v_mfma_f32_16x16x32_bf16 v[36:39], v[184:187], v[208:211], v[36:39]
	v_mfma_f32_16x16x32_bf16 v[32:35], v[192:195], v[208:211], v[32:35]
	v_mfma_f32_16x16x32_bf16 v[20:23], v[184:187], v[216:219], v[20:23]
	v_mfma_f32_16x16x32_bf16 v[16:19], v[192:195], v[216:219], v[16:19]
	v_mfma_f32_16x16x32_bf16 v[4:7], v[184:187], v[224:227], v[4:7]
	v_mfma_f32_16x16x32_bf16 v[0:3], v[192:195], v[224:227], v[0:3]
	v_mfma_f32_16x16x32_bf16 v[52:55], v[188:191], v[204:207], v[52:55]
	v_mfma_f32_16x16x32_bf16 v[48:51], v[196:199], v[204:207], v[48:51]
	v_mfma_f32_16x16x32_bf16 v[36:39], v[188:191], v[212:215], v[36:39]
	v_mfma_f32_16x16x32_bf16 v[32:35], v[196:199], v[212:215], v[32:35]
	v_mfma_f32_16x16x32_bf16 v[20:23], v[188:191], v[220:223], v[20:23]
	v_mfma_f32_16x16x32_bf16 v[16:19], v[196:199], v[220:223], v[16:19]
	v_mfma_f32_16x16x32_bf16 v[4:7], v[188:191], v[228:231], v[4:7]
	v_mfma_f32_16x16x32_bf16 v[0:3], v[196:199], v[228:231], v[0:3]
	s_barrier
	s_add_i32 s78, s78, 2
	s_add_u32 s6, s6, 0x100
	s_addc_u32 s7, s7, 0
	s_add_u32 s76, s76, 0x100
	s_addc_u32 s77, s77, 0
	s_cmp_gt_u32 s78, 29
	s_cbranch_scc0 .LBB0_311
	s_and_b64 vcc, exec, s[48:49]
	s_cbranch_vccz .LBB0_314
	s_barrier

; #define PG8_STAGE(bufoff, gbase, voff) do { _Pragma("unroll") for (int _i = 0; _i < 2; ++_i) \
;         __builtin_amdgcn_global_load_lds((const unsigned*)((const char*)(gbase) + (voff)[_i]), (PG8_LAS unsigned*)(lds + (bufoff) + ldsw + _i * 8192), 16, 0, 0); } while (0)
; #define PG8_LDA(dst, b, h) do { _Pragma("unroll") for (int m = 0; m < 4; ++m) _Pragma("unroll") for (int k = 0; k < 2; ++k) dst[m][k] = *(const PG8_LAS bf16x8*)(lds + PG8_SA(b, h) + aoff + m * 2048 + k * 1024); } while (0)
; #define PG8_LDB(dst, b, h) do { _Pragma("unroll") for (int n = 0; n < 2; ++n) _Pragma("unroll") for (int k = 0; k < 2; ++k) dst[n][k] = *(const PG8_LAS bf16x8*)(lds + PG8_SB(b, h) + boff + n * 2048 + k * 1024); } while (0)
; #define PG8_MMA(ai, bj, At, Bt) do { __builtin_amdgcn_s_setprio(1); _Pragma("unroll") for (int m = 0; m < 4; ++m) _Pragma("unroll") for (int n = 0; n < 2; ++n) _Pragma("unroll") for (int k = 0; k < 2; ++k) \
;         acc[ai][bj][m][n] = __builtin_amdgcn_mfma_f32_16x16x32_bf16(Bt[n][k], At[m][k], acc[ai][bj][m][n], 0, 0, 0); __builtin_amdgcn_s_setprio(0); } while (0)
; #define PG8_WAIT_V(n) asm volatile("s_waitcnt vmcnt(" #n ")" ::: "memory")
; #define PG8_WAIT_L(n) asm volatile("s_waitcnt lgkmcnt(" #n ")" ::: "memory")
; template <class Epi, class Sched, bool ALIGN_EPI = false, bool SP2 = false>
; __device__ __forceinline__ void gemm_phase(PG8_LAS unsigned char* lds, const Gemm g, const Sched& S, const Epi& E) {
;     ...
;             const bool last = (t == nt - 2);
;             const char* a1 = cA + (size_t)(t + 1) * kstep;
;             const char* a2 = last ? nA : cA + (size_t)(t + 2) * kstep; const char* b2 = last ? nB : cB + (size_t)(t + 2) * kstep;
;             const char* a3 = a2 + kstep; const char* b3 = b2 + kstep;
;             if (last && has_next) S.a_ready(nxt);
;             if constexpr (SP2) {
;             PG8_LDB(B0, 0, 0); PG8_LDB(B1, 0, 1); PG8_SCHED; PG8_LDA(At, 0, 0); PG8_STAGE(PG8_SA(1, 1), a1 + hstepA, voffA);
;             PG8_WAIT_V(8); PG8_WAIT_L(0); PG8_BAR; PG8_MMA(0, 0, At, B0); PG8_MMA(0, 1, At, B1); PG8_BAR; PG8_SCHED;
;             PG8_LDA(At, 0, 1); PG8_STAGE(PG8_SB(0, 0), b2, voffB); PG8_STAGE(PG8_SB(0, 1), b2 + hstepB, voffB); PG8_STAGE(PG8_SA(0, 0), a2, voffA);
;             PG8_WAIT_V(8); PG8_WAIT_L(0); PG8_BAR; PG8_MMA(1, 0, At, B0); PG8_MMA(1, 1, At, B1); PG8_BAR; PG8_SCHED;
.LBB0_497:
	ds_read_b128 v[146:149], v155
	ds_read_b128 v[158:161], v155 offset:1024
	ds_read_b128 v[168:171], v155 offset:2048
	ds_read_b128 v[172:175], v155 offset:3072
	ds_read_b128 v[176:179], v156
	ds_read_b128 v[180:183], v156 offset:1024
	ds_read_b128 v[184:187], v156 offset:2048
	ds_read_b128 v[188:191], v156 offset:3072
	s_add_u32 s41, s54, 0xfff80080
	s_addc_u32 s43, s55, -1
	s_cmp_eq_u32 s34, 28
	s_cselect_b32 s63, s7, s43
	s_cselect_b32 s62, s28, s41
	s_cselect_b32 s61, s29, s33
	s_cselect_b32 s60, s30, s31
	s_add_i32 m0, s69, 0xc000
	ds_read_b128 v[192:195], v157
	ds_read_b128 v[196:199], v157 offset:1024
	ds_read_b128 v[200:203], v157 offset:2048
	ds_read_b128 v[204:207], v157 offset:3072
	ds_read_b128 v[208:211], v157 offset:4096
	ds_read_b128 v[212:215], v157 offset:5120
	ds_read_b128 v[216:219], v157 offset:6144
	ds_read_b128 v[220:223], v157 offset:7168
	global_load_lds_dwordx4 v138, s[54:55]
	s_add_i32 m0, s69, 0xe000
	s_nop 0
	global_load_lds_dwordx4 v140, s[54:55]
	s_waitcnt vmcnt(8)
	s_waitcnt lgkmcnt(0)
	s_barrier
	s_waitcnt lgkmcnt(0)
	v_mfma_f32_16x16x32_bf16 v[124:127], v[146:149], v[192:195], v[124:127]
	v_mfma_f32_16x16x32_bf16 v[120:123], v[168:171], v[192:195], v[120:123]
	v_mfma_f32_16x16x32_bf16 v[108:111], v[146:149], v[200:203], v[108:111]
	v_mfma_f32_16x16x32_bf16 v[104:107], v[168:171], v[200:203], v[104:107]
	v_mfma_f32_16x16x32_bf16 v[92:95], v[146:149], v[208:211], v[92:95]
	v_mfma_f32_16x16x32_bf16 v[88:91], v[168:171], v[208:211], v[88:91]
	v_mfma_f32_16x16x32_bf16 v[76:79], v[146:149], v[216:219], v[76:79]
	v_mfma_f32_16x16x32_bf16 v[72:75], v[168:171], v[216:219], v[72:75]
	v_mfma_f32_16x16x32_bf16 v[124:127], v[158:161], v[196:199], v[124:127]
	v_mfma_f32_16x16x32_bf16 v[120:123], v[172:175], v[196:199], v[120:123]
	v_mfma_f32_16x16x32_bf16 v[108:111], v[158:161], v[204:207], v[108:111]
	v_mfma_f32_16x16x32_bf16 v[104:107], v[172:175], v[204:207], v[104:107]
	v_mfma_f32_16x16x32_bf16 v[92:95], v[158:161], v[212:215], v[92:95]
	v_mfma_f32_16x16x32_bf16 v[88:91], v[172:175], v[212:215], v[88:91]
	v_mfma_f32_16x16x32_bf16 v[76:79], v[158:161], v[220:223], v[76:79]
	v_mfma_f32_16x16x32_bf16 v[72:75], v[172:175], v[220:223], v[72:75]
	v_mfma_f32_16x16x32_bf16 v[116:119], v[176:179], v[192:195], v[116:119]
	v_mfma_f32_16x16x32_bf16 v[112:115], v[184:187], v[192:195], v[112:115]
	v_mfma_f32_16x16x32_bf16 v[100:103], v[176:179], v[200:203], v[100:103]
	v_mfma_f32_16x16x32_bf16 v[96:99], v[184:187], v[200:203], v[96:99]
	v_mfma_f32_16x16x32_bf16 v[84:87], v[176:179], v[208:211], v[84:87]
	v_mfma_f32_16x16x32_bf16 v[80:83], v[184:187], v[208:211], v[80:83]
	v_mfma_f32_16x16x32_bf16 v[68:71], v[176:179], v[216:219], v[68:71]
	v_mfma_f32_16x16x32_bf16 v[64:67], v[184:187], v[216:219], v[64:67]
	v_mfma_f32_16x16x32_bf16 v[116:119], v[180:183], v[196:199], v[116:119]
	v_mfma_f32_16x16x32_bf16 v[112:115], v[188:191], v[196:199], v[112:115]
	v_mfma_f32_16x16x32_bf16 v[100:103], v[180:183], v[204:207], v[100:103]
	v_mfma_f32_16x16x32_bf16 v[96:99], v[188:191], v[204:207], v[96:99]
	v_mfma_f32_16x16x32_bf16 v[84:87], v[180:183], v[212:215], v[84:87]
	v_mfma_f32_16x16x32_bf16 v[80:83], v[188:191], v[212:215], v[80:83]
	v_mfma_f32_16x16x32_bf16 v[68:71], v[180:183], v[220:223], v[68:71]
	v_mfma_f32_16x16x32_bf16 v[64:67], v[188:191], v[220:223], v[64:67]
	s_barrier
	s_add_i32 s41, s81, s68
	v_lshl_add_u64 v[150:151], s[60:61], 0, v[130:131]
	s_mov_b32 m0, s41
	ds_read_b128 v[192:195], v157 offset:16384
	ds_read_b128 v[196:199], v157 offset:17408
	ds_read_b128 v[200:203], v157 offset:18432
	ds_read_b128 v[204:207], v157 offset:19456
	ds_read_b128 v[208:211], v157 offset:20480
	ds_read_b128 v[212:215], v157 offset:21504
	ds_read_b128 v[216:219], v157 offset:22528
	ds_read_b128 v[220:223], v157 offset:23552
	global_load_lds_dwordx4 v130, s[60:61]
	s_add_i32 m0, s41, 0x2000
	s_add_u32 s84, s60, 0x80000
	v_lshl_add_u64 v[224:225], s[60:61], 0, v[134:135]
	s_addc_u32 s85, s61, 0
	s_add_i32 s41, s82, s68
	global_load_lds_dwordx4 v134, s[60:61]
	s_mov_b32 m0, s41
	v_lshl_add_u64 v[228:229], s[62:63], 0, v[132:133]
	global_load_lds_dwordx4 v130, s[84:85]
	s_add_i32 m0, s41, 0x2000
	s_nop 0
	global_load_lds_dwordx4 v134, s[84:85]
	v_lshl_add_u64 v[226:227], s[62:63], 0, v[128:129]
	s_mov_b32 m0, s69
	s_nop 0
	global_load_lds_dwordx4 v128, s[62:63]
	s_mov_b32 m0, s70
	s_nop 0
	global_load_lds_dwordx4 v132, s[62:63]
	s_waitcnt vmcnt(8)
	s_waitcnt lgkmcnt(0)
	s_barrier
	s_waitcnt lgkmcnt(0)
	v_mfma_f32_16x16x32_bf16 v[60:63], v[146:149], v[192:195], v[60:63]
	v_mfma_f32_16x16x32_bf16 v[56:59], v[168:171], v[192:195], v[56:59]
	v_mfma_f32_16x16x32_bf16 v[44:47], v[146:149], v[200:203], v[44:47]
	v_mfma_f32_16x16x32_bf16 v[40:43], v[168:171], v[200:203], v[40:43]
	v_mfma_f32_16x16x32_bf16 v[28:31], v[146:149], v[208:211], v[28:31]
	v_mfma_f32_16x16x32_bf16 v[24:27], v[168:171], v[208:211], v[24:27]
	v_mfma_f32_16x16x32_bf16 v[12:15], v[146:149], v[216:219], v[12:15]
	v_mfma_f32_16x16x32_bf16 v[8:11], v[168:171], v[216:219], v[8:11]
	v_mfma_f32_16x16x32_bf16 v[60:63], v[158:161], v[196:199], v[60:63]
	v_mfma_f32_16x16x32_bf16 v[56:59], v[172:175], v[196:199], v[56:59]
	v_mfma_f32_16x16x32_bf16 v[44:47], v[158:161], v[204:207], v[44:47]
	v_mfma_f32_16x16x32_bf16 v[40:43], v[172:175], v[204:207], v[40:43]
	v_mfma_f32_16x16x32_bf16 v[28:31], v[158:161], v[212:215], v[28:31]
	v_mfma_f32_16x16x32_bf16 v[24:27], v[172:175], v[212:215], v[24:27]
	v_mfma_f32_16x16x32_bf16 v[12:15], v[158:161], v[220:223], v[12:15]
	v_mfma_f32_16x16x32_bf16 v[8:11], v[172:175], v[220:223], v[8:11]
	v_mfma_f32_16x16x32_bf16 v[52:55], v[176:179], v[192:195], v[52:55]
	v_mfma_f32_16x16x32_bf16 v[48:51], v[184:187], v[192:195], v[48:51]
	v_mfma_f32_16x16x32_bf16 v[36:39], v[176:179], v[200:203], v[36:39]
	v_mfma_f32_16x16x32_bf16 v[32:35], v[184:187], v[200:203], v[32:35]
	v_mfma_f32_16x16x32_bf16 v[20:23], v[176:179], v[208:211], v[20:23]
	v_mfma_f32_16x16x32_bf16 v[16:19], v[184:187], v[208:211], v[16:19]
	v_mfma_f32_16x16x32_bf16 v[4:7], v[176:179], v[216:219], v[4:7]
	v_mfma_f32_16x16x32_bf16 v[0:3], v[184:187], v[216:219], v[0:3]
	v_mfma_f32_16x16x32_bf16 v[52:55], v[180:183], v[196:199], v[52:55]
	v_mfma_f32_16x16x32_bf16 v[48:51], v[188:191], v[196:199], v[48:51]
	v_mfma_f32_16x16x32_bf16 v[36:39], v[180:183], v[204:207], v[36:39]
	v_mfma_f32_16x16x32_bf16 v[32:35], v[188:191], v[204:207], v[32:35]
	v_mfma_f32_16x16x32_bf16 v[20:23], v[180:183], v[212:215], v[20:23]
	v_mfma_f32_16x16x32_bf16 v[16:19], v[188:191], v[212:215], v[16:19]
	v_mfma_f32_16x16x32_bf16 v[4:7], v[180:183], v[220:223], v[4:7]
	v_mfma_f32_16x16x32_bf16 v[0:3], v[188:191], v[220:223], v[0:3]
	s_barrier
; #define PG8_STAGE(bufoff, gbase, voff) do { _Pragma("unroll") for (int _i = 0; _i < 2; ++_i) \
;         __builtin_amdgcn_global_load_lds((const unsigned*)((const char*)(gbase) + (voff)[_i]), (PG8_LAS unsigned*)(lds + (bufoff) + ldsw + _i * 8192), 16, 0, 0); } while (0)
; #define PG8_LDA(dst, b, h) do { _Pragma("unroll") for (int m = 0; m < 4; ++m) _Pragma("unroll") for (int k = 0; k < 2; ++k) dst[m][k] = *(const PG8_LAS bf16x8*)(lds + PG8_SA(b, h) + aoff + m * 2048 + k * 1024); } while (0)
; #define PG8_LDB(dst, b, h) do { _Pragma("unroll") for (int n = 0; n < 2; ++n) _Pragma("unroll") for (int k = 0; k < 2; ++k) dst[n][k] = *(const PG8_LAS bf16x8*)(lds + PG8_SB(b, h) + boff + n * 2048 + k * 1024); } while (0)
; #define PG8_MMA(ai, bj, At, Bt) do { __builtin_amdgcn_s_setprio(1); _Pragma("unroll") for (int m = 0; m < 4; ++m) _Pragma("unroll") for (int n = 0; n < 2; ++n) _Pragma("unroll") for (int k = 0; k < 2; ++k) \
;         acc[ai][bj][m][n] = __builtin_amdgcn_mfma_f32_16x16x32_bf16(Bt[n][k], At[m][k], acc[ai][bj][m][n], 0, 0, 0); __builtin_amdgcn_s_setprio(0); } while (0)
; #define PG8_WAIT_V(n) asm volatile("s_waitcnt vmcnt(" #n ")" ::: "memory")
; #define PG8_WAIT_L(n) asm volatile("s_waitcnt lgkmcnt(" #n ")" ::: "memory")
; #define PG8_BAR __builtin_amdgcn_s_barrier()
; #define PG8_SCHED __builtin_amdgcn_sched_barrier(0)
; template <class Epi, class Sched, bool ALIGN_EPI = false, bool SP2 = false>
; __device__ __forceinline__ void gemm_phase(PG8_LAS unsigned char* lds, const Gemm g, const Sched& S, const Epi& E) {
;     ...
;             PG8_LDB(B0, 1, 0); PG8_LDB(B1, 1, 1); PG8_SCHED; PG8_LDA(At, 1, 0); PG8_STAGE(PG8_SA(0, 1), a2 + hstepA, voffA);
;             PG8_WAIT_V(8); PG8_WAIT_L(0); PG8_BAR; PG8_MMA(0, 0, At, B0); PG8_MMA(0, 1, At, B1); PG8_BAR; PG8_SCHED;
;             PG8_LDA(At, 1, 1); PG8_STAGE(PG8_SB(1, 0), b3, voffB); PG8_STAGE(PG8_SB(1, 1), b3 + hstepB, voffB); PG8_STAGE(PG8_SA(1, 0), a3, voffA);
;             PG8_WAIT_V(8); PG8_WAIT_L(0); PG8_BAR; PG8_MMA(1, 0, At, B0); PG8_MMA(1, 1, At, B1); PG8_BAR; PG8_SCHED;
	s_add_i32 s41, 0, 0x18000
	v_add_u32_e32 v136, s41, v153
	s_add_i32 s43, 0, 0x1c000
	ds_read_b128 v[146:149], v136
	ds_read_b128 v[158:161], v136 offset:1024
	ds_read_b128 v[168:171], v136 offset:2048
	ds_read_b128 v[172:175], v136 offset:3072
	v_add_u32_e32 v136, s43, v153
	ds_read_b128 v[176:179], v136
	ds_read_b128 v[180:183], v136 offset:1024
	ds_read_b128 v[184:187], v136 offset:2048
	ds_read_b128 v[188:191], v136 offset:3072
	s_add_u32 s62, s62, 0x80000
	s_addc_u32 s63, s63, 0
	s_mov_b32 m0, s71
	ds_read_b128 v[192:195], v157 offset:32768
	ds_read_b128 v[196:199], v157 offset:33792
	ds_read_b128 v[200:203], v157 offset:34816
	ds_read_b128 v[204:207], v157 offset:35840
	ds_read_b128 v[208:211], v157 offset:36864
	ds_read_b128 v[212:215], v157 offset:37888
	ds_read_b128 v[216:219], v157 offset:38912
	ds_read_b128 v[220:223], v157 offset:39936
	global_load_lds_dwordx4 v128, s[62:63]
	s_mov_b32 m0, s72
	s_nop 0
	global_load_lds_dwordx4 v132, s[62:63]
	s_waitcnt vmcnt(8)
	s_waitcnt lgkmcnt(0)
	s_barrier
	s_waitcnt lgkmcnt(0)
	v_mfma_f32_16x16x32_bf16 v[124:127], v[146:149], v[192:195], v[124:127]
	v_mfma_f32_16x16x32_bf16 v[120:123], v[168:171], v[192:195], v[120:123]
	v_mfma_f32_16x16x32_bf16 v[108:111], v[146:149], v[200:203], v[108:111]
	v_mfma_f32_16x16x32_bf16 v[104:107], v[168:171], v[200:203], v[104:107]
	v_mfma_f32_16x16x32_bf16 v[92:95], v[146:149], v[208:211], v[92:95]
	v_mfma_f32_16x16x32_bf16 v[88:91], v[168:171], v[208:211], v[88:91]
	v_mfma_f32_16x16x32_bf16 v[76:79], v[146:149], v[216:219], v[76:79]
	v_mfma_f32_16x16x32_bf16 v[72:75], v[168:171], v[216:219], v[72:75]
	v_mfma_f32_16x16x32_bf16 v[124:127], v[158:161], v[196:199], v[124:127]
	v_mfma_f32_16x16x32_bf16 v[120:123], v[172:175], v[196:199], v[120:123]
	v_mfma_f32_16x16x32_bf16 v[108:111], v[158:161], v[204:207], v[108:111]
	v_mfma_f32_16x16x32_bf16 v[104:107], v[172:175], v[204:207], v[104:107]
	v_mfma_f32_16x16x32_bf16 v[92:95], v[158:161], v[212:215], v[92:95]
	v_mfma_f32_16x16x32_bf16 v[88:91], v[172:175], v[212:215], v[88:91]
	v_mfma_f32_16x16x32_bf16 v[76:79], v[158:161], v[220:223], v[76:79]
	v_mfma_f32_16x16x32_bf16 v[72:75], v[172:175], v[220:223], v[72:75]
	v_mfma_f32_16x16x32_bf16 v[116:119], v[176:179], v[192:195], v[116:119]
	v_mfma_f32_16x16x32_bf16 v[112:115], v[184:187], v[192:195], v[112:115]
	v_mfma_f32_16x16x32_bf16 v[100:103], v[176:179], v[200:203], v[100:103]
	v_mfma_f32_16x16x32_bf16 v[96:99], v[184:187], v[200:203], v[96:99]
	v_mfma_f32_16x16x32_bf16 v[84:87], v[176:179], v[208:211], v[84:87]
	v_mfma_f32_16x16x32_bf16 v[80:83], v[184:187], v[208:211], v[80:83]
	v_mfma_f32_16x16x32_bf16 v[68:71], v[176:179], v[216:219], v[68:71]
	v_mfma_f32_16x16x32_bf16 v[64:67], v[184:187], v[216:219], v[64:67]
	v_mfma_f32_16x16x32_bf16 v[116:119], v[180:183], v[196:199], v[116:119]
	v_mfma_f32_16x16x32_bf16 v[112:115], v[188:191], v[196:199], v[112:115]
	v_mfma_f32_16x16x32_bf16 v[100:103], v[180:183], v[204:207], v[100:103]
	v_mfma_f32_16x16x32_bf16 v[96:99], v[188:191], v[204:207], v[96:99]
	v_mfma_f32_16x16x32_bf16 v[84:87], v[180:183], v[212:215], v[84:87]
	v_mfma_f32_16x16x32_bf16 v[80:83], v[188:191], v[212:215], v[80:83]
	v_mfma_f32_16x16x32_bf16 v[68:71], v[180:183], v[220:223], v[68:71]
	v_mfma_f32_16x16x32_bf16 v[64:67], v[188:191], v[220:223], v[64:67]
	s_barrier
	s_add_i32 s41, s41, s68
	v_lshl_add_u64 v[150:151], v[150:151], 0, s[20:21]
	s_mov_b32 m0, s41
	ds_read_b128 v[192:195], v157 offset:49152
	ds_read_b128 v[196:199], v157 offset:50176
	ds_read_b128 v[200:203], v157 offset:51200
	ds_read_b128 v[204:207], v157 offset:52224
	ds_read_b128 v[208:211], v157 offset:53248
	ds_read_b128 v[212:215], v157 offset:54272
	ds_read_b128 v[216:219], v157 offset:55296
	ds_read_b128 v[220:223], v157 offset:56320
	global_load_lds_dwordx4 v[150:151], off
	s_add_i32 m0, s41, 0x2000
	s_add_u32 s60, s60, 0x80080
	v_lshl_add_u64 v[150:151], v[224:225], 0, s[20:21]
	s_addc_u32 s61, s61, 0
	s_add_i32 s41, s43, s68
	global_load_lds_dwordx4 v[150:151], off
	s_mov_b32 m0, s41
	s_nop 0
	global_load_lds_dwordx4 v130, s[60:61]
	s_add_i32 m0, s41, 0x2000
	s_nop 0
	global_load_lds_dwordx4 v134, s[60:61]
	v_lshl_add_u64 v[150:151], v[226:227], 0, s[20:21]
	s_mov_b32 m0, s78
	s_nop 0
	global_load_lds_dwordx4 v[150:151], off
	v_lshl_add_u64 v[150:151], v[228:229], 0, s[20:21]
	s_mov_b32 m0, s79
	s_nop 0
	global_load_lds_dwordx4 v[150:151], off
	s_waitcnt vmcnt(8)
	s_waitcnt lgkmcnt(0)
	s_barrier
	s_waitcnt lgkmcnt(0)
	v_mfma_f32_16x16x32_bf16 v[60:63], v[146:149], v[192:195], v[60:63]
	v_mfma_f32_16x16x32_bf16 v[56:59], v[168:171], v[192:195], v[56:59]
	v_mfma_f32_16x16x32_bf16 v[44:47], v[146:149], v[200:203], v[44:47]
	v_mfma_f32_16x16x32_bf16 v[40:43], v[168:171], v[200:203], v[40:43]
	v_mfma_f32_16x16x32_bf16 v[28:31], v[146:149], v[208:211], v[28:31]
	v_mfma_f32_16x16x32_bf16 v[24:27], v[168:171], v[208:211], v[24:27]
	v_mfma_f32_16x16x32_bf16 v[12:15], v[146:149], v[216:219], v[12:15]
	v_mfma_f32_16x16x32_bf16 v[8:11], v[168:171], v[216:219], v[8:11]
	v_mfma_f32_16x16x32_bf16 v[60:63], v[158:161], v[196:199], v[60:63]
	v_mfma_f32_16x16x32_bf16 v[56:59], v[172:175], v[196:199], v[56:59]
	v_mfma_f32_16x16x32_bf16 v[44:47], v[158:161], v[204:207], v[44:47]
	v_mfma_f32_16x16x32_bf16 v[40:43], v[172:175], v[204:207], v[40:43]
	v_mfma_f32_16x16x32_bf16 v[28:31], v[158:161], v[212:215], v[28:31]
	v_mfma_f32_16x16x32_bf16 v[24:27], v[172:175], v[212:215], v[24:27]
	v_mfma_f32_16x16x32_bf16 v[12:15], v[158:161], v[220:223], v[12:15]
	v_mfma_f32_16x16x32_bf16 v[8:11], v[172:175], v[220:223], v[8:11]
	v_mfma_f32_16x16x32_bf16 v[52:55], v[176:179], v[192:195], v[52:55]
	v_mfma_f32_16x16x32_bf16 v[48:51], v[184:187], v[192:195], v[48:51]
	v_mfma_f32_16x16x32_bf16 v[36:39], v[176:179], v[200:203], v[36:39]
	v_mfma_f32_16x16x32_bf16 v[32:35], v[184:187], v[200:203], v[32:35]
	v_mfma_f32_16x16x32_bf16 v[20:23], v[176:179], v[208:211], v[20:23]
	v_mfma_f32_16x16x32_bf16 v[16:19], v[184:187], v[208:211], v[16:19]
	v_mfma_f32_16x16x32_bf16 v[4:7], v[176:179], v[216:219], v[4:7]
	v_mfma_f32_16x16x32_bf16 v[0:3], v[184:187], v[216:219], v[0:3]
	v_mfma_f32_16x16x32_bf16 v[52:55], v[180:183], v[196:199], v[52:55]
	v_mfma_f32_16x16x32_bf16 v[48:51], v[188:191], v[196:199], v[48:51]
	v_mfma_f32_16x16x32_bf16 v[36:39], v[180:183], v[204:207], v[36:39]
	v_mfma_f32_16x16x32_bf16 v[32:35], v[188:191], v[204:207], v[32:35]
	v_mfma_f32_16x16x32_bf16 v[20:23], v[180:183], v[212:215], v[20:23]
	v_mfma_f32_16x16x32_bf16 v[16:19], v[188:191], v[212:215], v[16:19]
	v_mfma_f32_16x16x32_bf16 v[4:7], v[180:183], v[220:223], v[4:7]
	v_mfma_f32_16x16x32_bf16 v[0:3], v[188:191], v[220:223], v[0:3]
	s_barrier
	s_add_i32 s34, s34, 2
	s_add_u32 s54, s54, 0x100
	s_addc_u32 s55, s55, 0
	s_add_u32 s31, s31, 0x100
	s_addc_u32 s33, s33, 0
	s_cmp_gt_u32 s34, 29
	s_cbranch_scc0 .LBB0_497
	s_and_b64 vcc, exec, s[22:23]
	s_cbranch_vccz .LBB0_500
	s_barrier

; #define PG8_STAGE(bufoff, gbase, voff) do { _Pragma("unroll") for (int _i = 0; _i < 2; ++_i) \
;         __builtin_amdgcn_global_load_lds((const unsigned*)((const char*)(gbase) + (voff)[_i]), (PG8_LAS unsigned*)(lds + (bufoff) + ldsw + _i * 8192), 16, 0, 0); } while (0)
; #define PG8_LDA(dst, b, h) do { _Pragma("unroll") for (int m = 0; m < 4; ++m) _Pragma("unroll") for (int k = 0; k < 2; ++k) dst[m][k] = *(const PG8_LAS bf16x8*)(lds + PG8_SA(b, h) + aoff + m * 2048 + k * 1024); } while (0)
; #define PG8_LDB(dst, b, h) do { _Pragma("unroll") for (int n = 0; n < 2; ++n) _Pragma("unroll") for (int k = 0; k < 2; ++k) dst[n][k] = *(const PG8_LAS bf16x8*)(lds + PG8_SB(b, h) + boff + n * 2048 + k * 1024); } while (0)
; #define PG8_MMA(ai, bj, At, Bt) do { __builtin_amdgcn_s_setprio(1); _Pragma("unroll") for (int m = 0; m < 4; ++m) _Pragma("unroll") for (int n = 0; n < 2; ++n) _Pragma("unroll") for (int k = 0; k < 2; ++k) \
;         acc[ai][bj][m][n] = __builtin_amdgcn_mfma_f32_16x16x32_bf16(Bt[n][k], At[m][k], acc[ai][bj][m][n], 0, 0, 0); __builtin_amdgcn_s_setprio(0); } while (0)
; #define PG8_WAIT_V(n) asm volatile("s_waitcnt vmcnt(" #n ")" ::: "memory")
; #define PG8_WAIT_L(n) asm volatile("s_waitcnt lgkmcnt(" #n ")" ::: "memory")
; template <class Epi, class Sched, bool ALIGN_EPI = false, bool SP2 = false>
; __device__ __forceinline__ void gemm_phase(PG8_LAS unsigned char* lds, const Gemm g, const Sched& S, const Epi& E) {
;     ...
;             const bool last = (t == nt - 2);
;             const char* a1 = cA + (size_t)(t + 1) * kstep;
;             const char* a2 = last ? nA : cA + (size_t)(t + 2) * kstep; const char* b2 = last ? nB : cB + (size_t)(t + 2) * kstep;
;             const char* a3 = a2 + kstep; const char* b3 = b2 + kstep;
;             if (last && has_next) S.a_ready(nxt);
;             if constexpr (SP2) {
;             PG8_LDB(B0, 0, 0); PG8_LDB(B1, 0, 1); PG8_SCHED; PG8_LDA(At, 0, 0); PG8_STAGE(PG8_SA(1, 1), a1 + hstepA, voffA);
;             PG8_WAIT_V(8); PG8_WAIT_L(0); PG8_BAR; PG8_MMA(0, 0, At, B0); PG8_MMA(0, 1, At, B1); PG8_BAR; PG8_SCHED;
;             PG8_LDA(At, 0, 1); PG8_STAGE(PG8_SB(0, 0), b2, voffB); PG8_STAGE(PG8_SB(0, 1), b2 + hstepB, voffB); PG8_STAGE(PG8_SA(0, 0), a2, voffA);
;             PG8_WAIT_V(8); PG8_WAIT_L(0); PG8_BAR; PG8_MMA(1, 0, At, B0); PG8_MMA(1, 1, At, B1); PG8_BAR; PG8_SCHED;
.LBB0_829:
	ds_read_b128 v[144:147], v153
	ds_read_b128 v[158:161], v153 offset:1024
	ds_read_b128 v[166:169], v153 offset:2048
	ds_read_b128 v[170:173], v153 offset:3072
	ds_read_b128 v[174:177], v154
	ds_read_b128 v[178:181], v154 offset:1024
	ds_read_b128 v[182:185], v154 offset:2048
	ds_read_b128 v[186:189], v154 offset:3072
	s_add_u32 s40, s0, 0xffdc0080
	s_addc_u32 s41, s1, -1
	s_cmp_eq_u32 s58, 12
	s_cselect_b32 s43, s21, s41
	s_cselect_b32 s42, s20, s40
	s_cselect_b32 s41, s19, s57
	s_cselect_b32 s40, s55, s56
	s_add_i32 m0, s33, 0xc000
	ds_read_b128 v[190:193], v155
	ds_read_b128 v[194:197], v155 offset:1024
	ds_read_b128 v[198:201], v155 offset:2048
	ds_read_b128 v[202:205], v155 offset:3072
	ds_read_b128 v[206:209], v155 offset:4096
	ds_read_b128 v[210:213], v155 offset:5120
	ds_read_b128 v[214:217], v155 offset:6144
	ds_read_b128 v[218:221], v155 offset:7168
	global_load_lds_dwordx4 v136, s[0:1]
	s_add_i32 m0, s33, 0xe000
	s_nop 0
	global_load_lds_dwordx4 v138, s[0:1]
	s_waitcnt vmcnt(8)
	s_waitcnt lgkmcnt(0)
	s_barrier
	s_waitcnt lgkmcnt(0)
	v_mfma_f32_16x16x32_bf16 v[124:127], v[144:147], v[190:193], v[124:127]
	v_mfma_f32_16x16x32_bf16 v[120:123], v[166:169], v[190:193], v[120:123]
	v_mfma_f32_16x16x32_bf16 v[108:111], v[144:147], v[198:201], v[108:111]
	v_mfma_f32_16x16x32_bf16 v[104:107], v[166:169], v[198:201], v[104:107]
	v_mfma_f32_16x16x32_bf16 v[92:95], v[144:147], v[206:209], v[92:95]
	v_mfma_f32_16x16x32_bf16 v[88:91], v[166:169], v[206:209], v[88:91]
	v_mfma_f32_16x16x32_bf16 v[76:79], v[144:147], v[214:217], v[76:79]
	v_mfma_f32_16x16x32_bf16 v[72:75], v[166:169], v[214:217], v[72:75]
	v_mfma_f32_16x16x32_bf16 v[124:127], v[158:161], v[194:197], v[124:127]
	v_mfma_f32_16x16x32_bf16 v[120:123], v[170:173], v[194:197], v[120:123]
	v_mfma_f32_16x16x32_bf16 v[108:111], v[158:161], v[202:205], v[108:111]
	v_mfma_f32_16x16x32_bf16 v[104:107], v[170:173], v[202:205], v[104:107]
	v_mfma_f32_16x16x32_bf16 v[92:95], v[158:161], v[210:213], v[92:95]
	v_mfma_f32_16x16x32_bf16 v[88:91], v[170:173], v[210:213], v[88:91]
	v_mfma_f32_16x16x32_bf16 v[76:79], v[158:161], v[218:221], v[76:79]
	v_mfma_f32_16x16x32_bf16 v[72:75], v[170:173], v[218:221], v[72:75]
	v_mfma_f32_16x16x32_bf16 v[116:119], v[174:177], v[190:193], v[116:119]
	v_mfma_f32_16x16x32_bf16 v[112:115], v[182:185], v[190:193], v[112:115]
	v_mfma_f32_16x16x32_bf16 v[100:103], v[174:177], v[198:201], v[100:103]
	v_mfma_f32_16x16x32_bf16 v[96:99], v[182:185], v[198:201], v[96:99]
	v_mfma_f32_16x16x32_bf16 v[84:87], v[174:177], v[206:209], v[84:87]
	v_mfma_f32_16x16x32_bf16 v[80:83], v[182:185], v[206:209], v[80:83]
	v_mfma_f32_16x16x32_bf16 v[68:71], v[174:177], v[214:217], v[68:71]
	v_mfma_f32_16x16x32_bf16 v[64:67], v[182:185], v[214:217], v[64:67]
	v_mfma_f32_16x16x32_bf16 v[116:119], v[178:181], v[194:197], v[116:119]
	v_mfma_f32_16x16x32_bf16 v[112:115], v[186:189], v[194:197], v[112:115]
	v_mfma_f32_16x16x32_bf16 v[100:103], v[178:181], v[202:205], v[100:103]
	v_mfma_f32_16x16x32_bf16 v[96:99], v[186:189], v[202:205], v[96:99]
	v_mfma_f32_16x16x32_bf16 v[84:87], v[178:181], v[210:213], v[84:87]
	v_mfma_f32_16x16x32_bf16 v[80:83], v[186:189], v[210:213], v[80:83]
	v_mfma_f32_16x16x32_bf16 v[68:71], v[178:181], v[218:221], v[68:71]
	v_mfma_f32_16x16x32_bf16 v[64:67], v[186:189], v[218:221], v[64:67]
	s_barrier
	s_add_i32 s59, s49, s30
	v_lshl_add_u64 v[148:149], s[40:41], 0, v[132:133]
	s_mov_b32 m0, s59
	ds_read_b128 v[190:193], v155 offset:16384
	ds_read_b128 v[194:197], v155 offset:17408
	ds_read_b128 v[198:201], v155 offset:18432
	ds_read_b128 v[202:205], v155 offset:19456
	ds_read_b128 v[206:209], v155 offset:20480
	ds_read_b128 v[210:213], v155 offset:21504
	ds_read_b128 v[214:217], v155 offset:22528
	ds_read_b128 v[218:221], v155 offset:23552
	global_load_lds_dwordx4 v132, s[40:41]
	s_add_i32 m0, s59, 0x2000
	s_add_u32 s60, s40, 0x40000
	v_lshl_add_u64 v[222:223], s[40:41], 0, v[128:129]
	s_addc_u32 s61, s41, 0
	s_add_i32 s59, s50, s30
	global_load_lds_dwordx4 v128, s[40:41]
	s_mov_b32 m0, s59
	v_lshl_add_u64 v[226:227], s[42:43], 0, v[130:131]
	global_load_lds_dwordx4 v132, s[60:61]
	s_add_i32 m0, s59, 0x2000
	s_nop 0
	global_load_lds_dwordx4 v128, s[60:61]
	v_lshl_add_u64 v[224:225], s[42:43], 0, v[134:135]
	s_mov_b32 m0, s33
	s_nop 0
	global_load_lds_dwordx4 v134, s[42:43]
	s_mov_b32 m0, s34
	s_nop 0
	global_load_lds_dwordx4 v130, s[42:43]
	s_waitcnt vmcnt(8)
	s_waitcnt lgkmcnt(0)
	s_barrier
	s_waitcnt lgkmcnt(0)
	v_mfma_f32_16x16x32_bf16 v[60:63], v[144:147], v[190:193], v[60:63]
	v_mfma_f32_16x16x32_bf16 v[56:59], v[166:169], v[190:193], v[56:59]
	v_mfma_f32_16x16x32_bf16 v[44:47], v[144:147], v[198:201], v[44:47]
	v_mfma_f32_16x16x32_bf16 v[40:43], v[166:169], v[198:201], v[40:43]
	v_mfma_f32_16x16x32_bf16 v[28:31], v[144:147], v[206:209], v[28:31]
	v_mfma_f32_16x16x32_bf16 v[24:27], v[166:169], v[206:209], v[24:27]
	v_mfma_f32_16x16x32_bf16 v[12:15], v[144:147], v[214:217], v[12:15]
	v_mfma_f32_16x16x32_bf16 v[8:11], v[166:169], v[214:217], v[8:11]
	v_mfma_f32_16x16x32_bf16 v[60:63], v[158:161], v[194:197], v[60:63]
	v_mfma_f32_16x16x32_bf16 v[56:59], v[170:173], v[194:197], v[56:59]
	v_mfma_f32_16x16x32_bf16 v[44:47], v[158:161], v[202:205], v[44:47]
	v_mfma_f32_16x16x32_bf16 v[40:43], v[170:173], v[202:205], v[40:43]
	v_mfma_f32_16x16x32_bf16 v[28:31], v[158:161], v[210:213], v[28:31]
	v_mfma_f32_16x16x32_bf16 v[24:27], v[170:173], v[210:213], v[24:27]
	v_mfma_f32_16x16x32_bf16 v[12:15], v[158:161], v[218:221], v[12:15]
	v_mfma_f32_16x16x32_bf16 v[8:11], v[170:173], v[218:221], v[8:11]
	v_mfma_f32_16x16x32_bf16 v[52:55], v[174:177], v[190:193], v[52:55]
	v_mfma_f32_16x16x32_bf16 v[48:51], v[182:185], v[190:193], v[48:51]
	v_mfma_f32_16x16x32_bf16 v[36:39], v[174:177], v[198:201], v[36:39]
	v_mfma_f32_16x16x32_bf16 v[32:35], v[182:185], v[198:201], v[32:35]
	v_mfma_f32_16x16x32_bf16 v[20:23], v[174:177], v[206:209], v[20:23]
	v_mfma_f32_16x16x32_bf16 v[16:19], v[182:185], v[206:209], v[16:19]
	v_mfma_f32_16x16x32_bf16 v[4:7], v[174:177], v[214:217], v[4:7]
	v_mfma_f32_16x16x32_bf16 v[0:3], v[182:185], v[214:217], v[0:3]
	v_mfma_f32_16x16x32_bf16 v[52:55], v[178:181], v[194:197], v[52:55]
	v_mfma_f32_16x16x32_bf16 v[48:51], v[186:189], v[194:197], v[48:51]
	v_mfma_f32_16x16x32_bf16 v[36:39], v[178:181], v[202:205], v[36:39]
	v_mfma_f32_16x16x32_bf16 v[32:35], v[186:189], v[202:205], v[32:35]
	v_mfma_f32_16x16x32_bf16 v[20:23], v[178:181], v[210:213], v[20:23]
	v_mfma_f32_16x16x32_bf16 v[16:19], v[186:189], v[210:213], v[16:19]
	v_mfma_f32_16x16x32_bf16 v[4:7], v[178:181], v[218:221], v[4:7]
	v_mfma_f32_16x16x32_bf16 v[0:3], v[186:189], v[218:221], v[0:3]
	s_barrier
; #define PG8_STAGE(bufoff, gbase, voff) do { _Pragma("unroll") for (int _i = 0; _i < 2; ++_i) \
;         __builtin_amdgcn_global_load_lds((const unsigned*)((const char*)(gbase) + (voff)[_i]), (PG8_LAS unsigned*)(lds + (bufoff) + ldsw + _i * 8192), 16, 0, 0); } while (0)
; #define PG8_LDA(dst, b, h) do { _Pragma("unroll") for (int m = 0; m < 4; ++m) _Pragma("unroll") for (int k = 0; k < 2; ++k) dst[m][k] = *(const PG8_LAS bf16x8*)(lds + PG8_SA(b, h) + aoff + m * 2048 + k * 1024); } while (0)
; #define PG8_LDB(dst, b, h) do { _Pragma("unroll") for (int n = 0; n < 2; ++n) _Pragma("unroll") for (int k = 0; k < 2; ++k) dst[n][k] = *(const PG8_LAS bf16x8*)(lds + PG8_SB(b, h) + boff + n * 2048 + k * 1024); } while (0)
; #define PG8_MMA(ai, bj, At, Bt) do { __builtin_amdgcn_s_setprio(1); _Pragma("unroll") for (int m = 0; m < 4; ++m) _Pragma("unroll") for (int n = 0; n < 2; ++n) _Pragma("unroll") for (int k = 0; k < 2; ++k) \
;         acc[ai][bj][m][n] = __builtin_amdgcn_mfma_f32_16x16x32_bf16(Bt[n][k], At[m][k], acc[ai][bj][m][n], 0, 0, 0); __builtin_amdgcn_s_setprio(0); } while (0)
; #define PG8_WAIT_V(n) asm volatile("s_waitcnt vmcnt(" #n ")" ::: "memory")
; #define PG8_WAIT_L(n) asm volatile("s_waitcnt lgkmcnt(" #n ")" ::: "memory")
; #define PG8_BAR __builtin_amdgcn_s_barrier()
; #define PG8_SCHED __builtin_amdgcn_sched_barrier(0)
; template <class Epi, class Sched, bool ALIGN_EPI = false, bool SP2 = false>
; __device__ __forceinline__ void gemm_phase(PG8_LAS unsigned char* lds, const Gemm g, const Sched& S, const Epi& E) {
;     ...
;         for (int t = 0; t < nt; t += 2) {
;     ...
;             PG8_LDB(B0, 1, 0); PG8_LDB(B1, 1, 1); PG8_SCHED; PG8_LDA(At, 1, 0); PG8_STAGE(PG8_SA(0, 1), a2 + hstepA, voffA);
;             PG8_WAIT_V(8); PG8_WAIT_L(0); PG8_BAR; PG8_MMA(0, 0, At, B0); PG8_MMA(0, 1, At, B1); PG8_BAR; PG8_SCHED;
;             PG8_LDA(At, 1, 1); PG8_STAGE(PG8_SB(1, 0), b3, voffB); PG8_STAGE(PG8_SB(1, 1), b3 + hstepB, voffB); PG8_STAGE(PG8_SA(1, 0), a3, voffA);
;             PG8_WAIT_V(8); PG8_WAIT_L(0); PG8_BAR; PG8_MMA(1, 0, At, B0); PG8_MMA(1, 1, At, B1); PG8_BAR; PG8_SCHED;
	s_add_i32 s59, 0, 0x18000
	v_add_u32_e32 v157, s59, v151
	s_add_i32 s60, 0, 0x1c000
	ds_read_b128 v[144:147], v157
	ds_read_b128 v[158:161], v157 offset:1024
	ds_read_b128 v[166:169], v157 offset:2048
	ds_read_b128 v[170:173], v157 offset:3072
	v_add_u32_e32 v157, s60, v151
	ds_read_b128 v[174:177], v157
	ds_read_b128 v[178:181], v157 offset:1024
	ds_read_b128 v[182:185], v157 offset:2048
	ds_read_b128 v[186:189], v157 offset:3072
	s_add_u32 s42, s42, 0x240000
	s_addc_u32 s43, s43, 0
	s_mov_b32 m0, s35
	ds_read_b128 v[190:193], v155 offset:32768
	ds_read_b128 v[194:197], v155 offset:33792
	ds_read_b128 v[198:201], v155 offset:34816
	ds_read_b128 v[202:205], v155 offset:35840
	ds_read_b128 v[206:209], v155 offset:36864
	ds_read_b128 v[210:213], v155 offset:37888
	ds_read_b128 v[214:217], v155 offset:38912
	ds_read_b128 v[218:221], v155 offset:39936
	global_load_lds_dwordx4 v134, s[42:43]
	s_mov_b32 m0, s44
	s_nop 0
	global_load_lds_dwordx4 v130, s[42:43]
	s_waitcnt vmcnt(8)
	s_waitcnt lgkmcnt(0)
	s_barrier
	s_waitcnt lgkmcnt(0)
	v_mfma_f32_16x16x32_bf16 v[124:127], v[144:147], v[190:193], v[124:127]
	v_mfma_f32_16x16x32_bf16 v[120:123], v[166:169], v[190:193], v[120:123]
	v_mfma_f32_16x16x32_bf16 v[108:111], v[144:147], v[198:201], v[108:111]
	v_mfma_f32_16x16x32_bf16 v[104:107], v[166:169], v[198:201], v[104:107]
	v_mfma_f32_16x16x32_bf16 v[92:95], v[144:147], v[206:209], v[92:95]
	v_mfma_f32_16x16x32_bf16 v[88:91], v[166:169], v[206:209], v[88:91]
	v_mfma_f32_16x16x32_bf16 v[76:79], v[144:147], v[214:217], v[76:79]
	v_mfma_f32_16x16x32_bf16 v[72:75], v[166:169], v[214:217], v[72:75]
	v_mfma_f32_16x16x32_bf16 v[124:127], v[158:161], v[194:197], v[124:127]
	v_mfma_f32_16x16x32_bf16 v[120:123], v[170:173], v[194:197], v[120:123]
	v_mfma_f32_16x16x32_bf16 v[108:111], v[158:161], v[202:205], v[108:111]
	v_mfma_f32_16x16x32_bf16 v[104:107], v[170:173], v[202:205], v[104:107]
	v_mfma_f32_16x16x32_bf16 v[92:95], v[158:161], v[210:213], v[92:95]
	v_mfma_f32_16x16x32_bf16 v[88:91], v[170:173], v[210:213], v[88:91]
	v_mfma_f32_16x16x32_bf16 v[76:79], v[158:161], v[218:221], v[76:79]
	v_mfma_f32_16x16x32_bf16 v[72:75], v[170:173], v[218:221], v[72:75]
	v_mfma_f32_16x16x32_bf16 v[116:119], v[174:177], v[190:193], v[116:119]
	v_mfma_f32_16x16x32_bf16 v[112:115], v[182:185], v[190:193], v[112:115]
	v_mfma_f32_16x16x32_bf16 v[100:103], v[174:177], v[198:201], v[100:103]
	v_mfma_f32_16x16x32_bf16 v[96:99], v[182:185], v[198:201], v[96:99]
	v_mfma_f32_16x16x32_bf16 v[84:87], v[174:177], v[206:209], v[84:87]
	v_mfma_f32_16x16x32_bf16 v[80:83], v[182:185], v[206:209], v[80:83]
	v_mfma_f32_16x16x32_bf16 v[68:71], v[174:177], v[214:217], v[68:71]
	v_mfma_f32_16x16x32_bf16 v[64:67], v[182:185], v[214:217], v[64:67]
	v_mfma_f32_16x16x32_bf16 v[116:119], v[178:181], v[194:197], v[116:119]
	v_mfma_f32_16x16x32_bf16 v[112:115], v[186:189], v[194:197], v[112:115]
	v_mfma_f32_16x16x32_bf16 v[100:103], v[178:181], v[202:205], v[100:103]
	v_mfma_f32_16x16x32_bf16 v[96:99], v[186:189], v[202:205], v[96:99]
	v_mfma_f32_16x16x32_bf16 v[84:87], v[178:181], v[210:213], v[84:87]
	v_mfma_f32_16x16x32_bf16 v[80:83], v[186:189], v[210:213], v[80:83]
	v_mfma_f32_16x16x32_bf16 v[68:71], v[178:181], v[218:221], v[68:71]
	v_mfma_f32_16x16x32_bf16 v[64:67], v[186:189], v[218:221], v[64:67]
	s_barrier
	s_add_i32 s42, s59, s30
	v_lshl_add_u64 v[148:149], v[148:149], 0, s[10:11]
	s_mov_b32 m0, s42
	ds_read_b128 v[190:193], v155 offset:49152
	ds_read_b128 v[194:197], v155 offset:50176
	ds_read_b128 v[198:201], v155 offset:51200
	ds_read_b128 v[202:205], v155 offset:52224
	ds_read_b128 v[206:209], v155 offset:53248
	ds_read_b128 v[210:213], v155 offset:54272
	ds_read_b128 v[214:217], v155 offset:55296
	ds_read_b128 v[218:221], v155 offset:56320
	global_load_lds_dwordx4 v[148:149], off
	s_add_i32 m0, s42, 0x2000
	s_add_u32 s40, s40, 0x40080
	v_lshl_add_u64 v[148:149], v[222:223], 0, s[10:11]
	s_addc_u32 s41, s41, 0
	s_add_i32 s42, s60, s30
	global_load_lds_dwordx4 v[148:149], off
	s_mov_b32 m0, s42
	s_nop 0
	global_load_lds_dwordx4 v132, s[40:41]
	s_add_i32 m0, s42, 0x2000
	s_nop 0
	global_load_lds_dwordx4 v128, s[40:41]
	v_lshl_add_u64 v[148:149], v[224:225], 0, s[10:11]
	s_mov_b32 m0, s47
	s_nop 0
	global_load_lds_dwordx4 v[148:149], off
	v_lshl_add_u64 v[148:149], v[226:227], 0, s[10:11]
	s_mov_b32 m0, s48
	s_nop 0
	global_load_lds_dwordx4 v[148:149], off
	s_waitcnt vmcnt(8)
	s_waitcnt lgkmcnt(0)
	s_barrier
	s_waitcnt lgkmcnt(0)
	v_mfma_f32_16x16x32_bf16 v[60:63], v[144:147], v[190:193], v[60:63]
	v_mfma_f32_16x16x32_bf16 v[56:59], v[166:169], v[190:193], v[56:59]
	v_mfma_f32_16x16x32_bf16 v[44:47], v[144:147], v[198:201], v[44:47]
	v_mfma_f32_16x16x32_bf16 v[40:43], v[166:169], v[198:201], v[40:43]
	v_mfma_f32_16x16x32_bf16 v[28:31], v[144:147], v[206:209], v[28:31]
	v_mfma_f32_16x16x32_bf16 v[24:27], v[166:169], v[206:209], v[24:27]
	v_mfma_f32_16x16x32_bf16 v[12:15], v[144:147], v[214:217], v[12:15]
	v_mfma_f32_16x16x32_bf16 v[8:11], v[166:169], v[214:217], v[8:11]
	v_mfma_f32_16x16x32_bf16 v[60:63], v[158:161], v[194:197], v[60:63]
	v_mfma_f32_16x16x32_bf16 v[56:59], v[170:173], v[194:197], v[56:59]
	v_mfma_f32_16x16x32_bf16 v[44:47], v[158:161], v[202:205], v[44:47]
	v_mfma_f32_16x16x32_bf16 v[40:43], v[170:173], v[202:205], v[40:43]
	v_mfma_f32_16x16x32_bf16 v[28:31], v[158:161], v[210:213], v[28:31]
	v_mfma_f32_16x16x32_bf16 v[24:27], v[170:173], v[210:213], v[24:27]
	v_mfma_f32_16x16x32_bf16 v[12:15], v[158:161], v[218:221], v[12:15]
	v_mfma_f32_16x16x32_bf16 v[8:11], v[170:173], v[218:221], v[8:11]
	v_mfma_f32_16x16x32_bf16 v[52:55], v[174:177], v[190:193], v[52:55]
	v_mfma_f32_16x16x32_bf16 v[48:51], v[182:185], v[190:193], v[48:51]
	v_mfma_f32_16x16x32_bf16 v[36:39], v[174:177], v[198:201], v[36:39]
	v_mfma_f32_16x16x32_bf16 v[32:35], v[182:185], v[198:201], v[32:35]
	v_mfma_f32_16x16x32_bf16 v[20:23], v[174:177], v[206:209], v[20:23]
	v_mfma_f32_16x16x32_bf16 v[16:19], v[182:185], v[206:209], v[16:19]
	v_mfma_f32_16x16x32_bf16 v[4:7], v[174:177], v[214:217], v[4:7]
	v_mfma_f32_16x16x32_bf16 v[0:3], v[182:185], v[214:217], v[0:3]
	v_mfma_f32_16x16x32_bf16 v[52:55], v[178:181], v[194:197], v[52:55]
	v_mfma_f32_16x16x32_bf16 v[48:51], v[186:189], v[194:197], v[48:51]
	v_mfma_f32_16x16x32_bf16 v[36:39], v[178:181], v[202:205], v[36:39]
	v_mfma_f32_16x16x32_bf16 v[32:35], v[186:189], v[202:205], v[32:35]
	v_mfma_f32_16x16x32_bf16 v[20:23], v[178:181], v[210:213], v[20:23]
	v_mfma_f32_16x16x32_bf16 v[16:19], v[186:189], v[210:213], v[16:19]
	v_mfma_f32_16x16x32_bf16 v[4:7], v[178:181], v[218:221], v[4:7]
	v_mfma_f32_16x16x32_bf16 v[0:3], v[186:189], v[218:221], v[0:3]
	s_barrier
	s_add_i32 s58, s58, 2
	s_add_u32 s0, s0, 0x100
	s_addc_u32 s1, s1, 0
	s_add_u32 s56, s56, 0x100
	s_addc_u32 s57, s57, 0
	s_cmp_gt_u32 s58, 13
	s_cbranch_scc0 .LBB0_829
	s_and_b64 vcc, exec, s[16:17]
	s_cbranch_vccz .LBB0_832
	s_barrier

; #define PG8_STAGE(bufoff, gbase, voff) do { _Pragma("unroll") for (int _i = 0; _i < 2; ++_i) \
;         __builtin_amdgcn_global_load_lds((const unsigned*)((const char*)(gbase) + (voff)[_i]), (PG8_LAS unsigned*)(lds + (bufoff) + ldsw + _i * 8192), 16, 0, 0); } while (0)
; #define PG8_LDA(dst, b, h) do { _Pragma("unroll") for (int m = 0; m < 4; ++m) _Pragma("unroll") for (int k = 0; k < 2; ++k) dst[m][k] = *(const PG8_LAS bf16x8*)(lds + PG8_SA(b, h) + aoff + m * 2048 + k * 1024); } while (0)
; #define PG8_LDB(dst, b, h) do { _Pragma("unroll") for (int n = 0; n < 2; ++n) _Pragma("unroll") for (int k = 0; k < 2; ++k) dst[n][k] = *(const PG8_LAS bf16x8*)(lds + PG8_SB(b, h) + boff + n * 2048 + k * 1024); } while (0)
; #define PG8_MMA(ai, bj, At, Bt) do { __builtin_amdgcn_s_setprio(1); _Pragma("unroll") for (int m = 0; m < 4; ++m) _Pragma("unroll") for (int n = 0; n < 2; ++n) _Pragma("unroll") for (int k = 0; k < 2; ++k) \
;         acc[ai][bj][m][n] = __builtin_amdgcn_mfma_f32_16x16x32_bf16(Bt[n][k], At[m][k], acc[ai][bj][m][n], 0, 0, 0); __builtin_amdgcn_s_setprio(0); } while (0)
; #define PG8_WAIT_V(n) asm volatile("s_waitcnt vmcnt(" #n ")" ::: "memory")
; #define PG8_WAIT_L(n) asm volatile("s_waitcnt lgkmcnt(" #n ")" ::: "memory")
; template <class Epi, class Sched, bool ALIGN_EPI = false, bool SP2 = false>
; __device__ __forceinline__ void gemm_phase(PG8_LAS unsigned char* lds, const Gemm g, const Sched& S, const Epi& E) {
;     ...
;             const bool last = (t == nt - 2);
;             const char* a1 = cA + (size_t)(t + 1) * kstep;
;             const char* a2 = last ? nA : cA + (size_t)(t + 2) * kstep; const char* b2 = last ? nB : cB + (size_t)(t + 2) * kstep;
;             const char* a3 = a2 + kstep; const char* b3 = b2 + kstep;
;             if (last && has_next) S.a_ready(nxt);
;             if constexpr (SP2) {
;             PG8_LDB(B0, 0, 0); PG8_LDB(B1, 0, 1); PG8_SCHED; PG8_LDA(At, 0, 0); PG8_STAGE(PG8_SA(1, 1), a1 + hstepA, voffA);
;             PG8_WAIT_V(8); PG8_WAIT_L(0); PG8_BAR; PG8_MMA(0, 0, At, B0); PG8_MMA(0, 1, At, B1); PG8_BAR; PG8_SCHED;
;             PG8_LDA(At, 0, 1); PG8_STAGE(PG8_SB(0, 0), b2, voffB); PG8_STAGE(PG8_SB(0, 1), b2 + hstepB, voffB); PG8_STAGE(PG8_SA(0, 0), a2, voffA);
;             PG8_WAIT_V(8); PG8_WAIT_L(0); PG8_BAR; PG8_MMA(1, 0, At, B0); PG8_MMA(1, 1, At, B1); PG8_BAR; PG8_SCHED;
.LBB0_848:
	ds_read_b128 v[144:147], v155
	ds_read_b128 v[148:151], v155 offset:1024
	ds_read_b128 v[166:169], v155 offset:2048
	ds_read_b128 v[170:173], v155 offset:3072
	ds_read_b128 v[174:177], v156
	ds_read_b128 v[178:181], v156 offset:1024
	ds_read_b128 v[182:185], v156 offset:2048
	ds_read_b128 v[186:189], v156 offset:3072
	s_add_u32 s42, s0, 0xffdc0080
	s_addc_u32 s43, s1, -1
	s_cmp_eq_u32 s58, 12
	s_cselect_b32 s45, s23, s43
	s_cselect_b32 s44, s22, s42
	s_cselect_b32 s43, s21, s34
	s_cselect_b32 s42, s30, s31
	s_add_i32 m0, s46, 0xc000
	ds_read_b128 v[190:193], v157
	ds_read_b128 v[194:197], v157 offset:1024
	ds_read_b128 v[198:201], v157 offset:2048
	ds_read_b128 v[202:205], v157 offset:3072
	ds_read_b128 v[206:209], v157 offset:4096
	ds_read_b128 v[210:213], v157 offset:5120
	ds_read_b128 v[214:217], v157 offset:6144
	ds_read_b128 v[218:221], v157 offset:7168
	global_load_lds_dwordx4 v136, s[0:1]
	s_add_i32 m0, s46, 0xe000
	s_nop 0
	global_load_lds_dwordx4 v138, s[0:1]
	s_waitcnt vmcnt(8)
	s_waitcnt lgkmcnt(0)
	s_barrier
	s_waitcnt lgkmcnt(0)
	v_mfma_f32_16x16x32_bf16 v[124:127], v[144:147], v[190:193], v[124:127]
	v_mfma_f32_16x16x32_bf16 v[120:123], v[166:169], v[190:193], v[120:123]
	v_mfma_f32_16x16x32_bf16 v[108:111], v[144:147], v[198:201], v[108:111]
	v_mfma_f32_16x16x32_bf16 v[104:107], v[166:169], v[198:201], v[104:107]
	v_mfma_f32_16x16x32_bf16 v[92:95], v[144:147], v[206:209], v[92:95]
	v_mfma_f32_16x16x32_bf16 v[88:91], v[166:169], v[206:209], v[88:91]
	v_mfma_f32_16x16x32_bf16 v[76:79], v[144:147], v[214:217], v[76:79]
	v_mfma_f32_16x16x32_bf16 v[72:75], v[166:169], v[214:217], v[72:75]
	v_mfma_f32_16x16x32_bf16 v[124:127], v[148:151], v[194:197], v[124:127]
	v_mfma_f32_16x16x32_bf16 v[120:123], v[170:173], v[194:197], v[120:123]
	v_mfma_f32_16x16x32_bf16 v[108:111], v[148:151], v[202:205], v[108:111]
	v_mfma_f32_16x16x32_bf16 v[104:107], v[170:173], v[202:205], v[104:107]
	v_mfma_f32_16x16x32_bf16 v[92:95], v[148:151], v[210:213], v[92:95]
	v_mfma_f32_16x16x32_bf16 v[88:91], v[170:173], v[210:213], v[88:91]
	v_mfma_f32_16x16x32_bf16 v[76:79], v[148:151], v[218:221], v[76:79]
	v_mfma_f32_16x16x32_bf16 v[72:75], v[170:173], v[218:221], v[72:75]
	v_mfma_f32_16x16x32_bf16 v[116:119], v[174:177], v[190:193], v[116:119]
	v_mfma_f32_16x16x32_bf16 v[112:115], v[182:185], v[190:193], v[112:115]
	v_mfma_f32_16x16x32_bf16 v[100:103], v[174:177], v[198:201], v[100:103]
	v_mfma_f32_16x16x32_bf16 v[96:99], v[182:185], v[198:201], v[96:99]
	v_mfma_f32_16x16x32_bf16 v[84:87], v[174:177], v[206:209], v[84:87]
	v_mfma_f32_16x16x32_bf16 v[80:83], v[182:185], v[206:209], v[80:83]
	v_mfma_f32_16x16x32_bf16 v[68:71], v[174:177], v[214:217], v[68:71]
	v_mfma_f32_16x16x32_bf16 v[64:67], v[182:185], v[214:217], v[64:67]
	v_mfma_f32_16x16x32_bf16 v[116:119], v[178:181], v[194:197], v[116:119]
	v_mfma_f32_16x16x32_bf16 v[112:115], v[186:189], v[194:197], v[112:115]
	v_mfma_f32_16x16x32_bf16 v[100:103], v[178:181], v[202:205], v[100:103]
	v_mfma_f32_16x16x32_bf16 v[96:99], v[186:189], v[202:205], v[96:99]
	v_mfma_f32_16x16x32_bf16 v[84:87], v[178:181], v[210:213], v[84:87]
	v_mfma_f32_16x16x32_bf16 v[80:83], v[186:189], v[210:213], v[80:83]
	v_mfma_f32_16x16x32_bf16 v[68:71], v[178:181], v[218:221], v[68:71]
	v_mfma_f32_16x16x32_bf16 v[64:67], v[186:189], v[218:221], v[64:67]
	s_barrier
	s_add_i32 s59, s54, s33
	v_lshl_add_u64 v[160:161], s[42:43], 0, v[132:133]
	s_mov_b32 m0, s59
	ds_read_b128 v[190:193], v157 offset:16384
	ds_read_b128 v[194:197], v157 offset:17408
	ds_read_b128 v[198:201], v157 offset:18432
	ds_read_b128 v[202:205], v157 offset:19456
	ds_read_b128 v[206:209], v157 offset:20480
	ds_read_b128 v[210:213], v157 offset:21504
	ds_read_b128 v[214:217], v157 offset:22528
	ds_read_b128 v[218:221], v157 offset:23552
	global_load_lds_dwordx4 v132, s[42:43]
	s_add_i32 m0, s59, 0x2000
	s_add_u32 s60, s42, 0x40000
	v_lshl_add_u64 v[222:223], s[42:43], 0, v[128:129]
	s_addc_u32 s61, s43, 0
	s_add_i32 s59, s55, s33
	global_load_lds_dwordx4 v128, s[42:43]
	s_mov_b32 m0, s59
	v_lshl_add_u64 v[226:227], s[44:45], 0, v[130:131]
	global_load_lds_dwordx4 v132, s[60:61]
	s_add_i32 m0, s59, 0x2000
	s_nop 0
	global_load_lds_dwordx4 v128, s[60:61]
	v_lshl_add_u64 v[224:225], s[44:45], 0, v[134:135]
	s_mov_b32 m0, s46
	s_nop 0
	global_load_lds_dwordx4 v134, s[44:45]
	s_mov_b32 m0, s47
	s_nop 0
	global_load_lds_dwordx4 v130, s[44:45]
	s_waitcnt vmcnt(8)
	s_waitcnt lgkmcnt(0)
	s_barrier
	s_waitcnt lgkmcnt(0)
	v_mfma_f32_16x16x32_bf16 v[60:63], v[144:147], v[190:193], v[60:63]
	v_mfma_f32_16x16x32_bf16 v[56:59], v[166:169], v[190:193], v[56:59]
	v_mfma_f32_16x16x32_bf16 v[44:47], v[144:147], v[198:201], v[44:47]
	v_mfma_f32_16x16x32_bf16 v[40:43], v[166:169], v[198:201], v[40:43]
	v_mfma_f32_16x16x32_bf16 v[28:31], v[144:147], v[206:209], v[28:31]
	v_mfma_f32_16x16x32_bf16 v[24:27], v[166:169], v[206:209], v[24:27]
	v_mfma_f32_16x16x32_bf16 v[12:15], v[144:147], v[214:217], v[12:15]
	v_mfma_f32_16x16x32_bf16 v[8:11], v[166:169], v[214:217], v[8:11]
	v_mfma_f32_16x16x32_bf16 v[60:63], v[148:151], v[194:197], v[60:63]
	v_mfma_f32_16x16x32_bf16 v[56:59], v[170:173], v[194:197], v[56:59]
	v_mfma_f32_16x16x32_bf16 v[44:47], v[148:151], v[202:205], v[44:47]
	v_mfma_f32_16x16x32_bf16 v[40:43], v[170:173], v[202:205], v[40:43]
	v_mfma_f32_16x16x32_bf16 v[28:31], v[148:151], v[210:213], v[28:31]
	v_mfma_f32_16x16x32_bf16 v[24:27], v[170:173], v[210:213], v[24:27]
	v_mfma_f32_16x16x32_bf16 v[12:15], v[148:151], v[218:221], v[12:15]
	v_mfma_f32_16x16x32_bf16 v[8:11], v[170:173], v[218:221], v[8:11]
	v_mfma_f32_16x16x32_bf16 v[52:55], v[174:177], v[190:193], v[52:55]
	v_mfma_f32_16x16x32_bf16 v[48:51], v[182:185], v[190:193], v[48:51]
	v_mfma_f32_16x16x32_bf16 v[36:39], v[174:177], v[198:201], v[36:39]
	v_mfma_f32_16x16x32_bf16 v[32:35], v[182:185], v[198:201], v[32:35]
	v_mfma_f32_16x16x32_bf16 v[20:23], v[174:177], v[206:209], v[20:23]
	v_mfma_f32_16x16x32_bf16 v[16:19], v[182:185], v[206:209], v[16:19]
	v_mfma_f32_16x16x32_bf16 v[4:7], v[174:177], v[214:217], v[4:7]
	v_mfma_f32_16x16x32_bf16 v[0:3], v[182:185], v[214:217], v[0:3]
	v_mfma_f32_16x16x32_bf16 v[52:55], v[178:181], v[194:197], v[52:55]
	v_mfma_f32_16x16x32_bf16 v[48:51], v[186:189], v[194:197], v[48:51]
	v_mfma_f32_16x16x32_bf16 v[36:39], v[178:181], v[202:205], v[36:39]
	v_mfma_f32_16x16x32_bf16 v[32:35], v[186:189], v[202:205], v[32:35]
	v_mfma_f32_16x16x32_bf16 v[20:23], v[178:181], v[210:213], v[20:23]
	v_mfma_f32_16x16x32_bf16 v[16:19], v[186:189], v[210:213], v[16:19]
	v_mfma_f32_16x16x32_bf16 v[4:7], v[178:181], v[218:221], v[4:7]
	v_mfma_f32_16x16x32_bf16 v[0:3], v[186:189], v[218:221], v[0:3]
	s_barrier
; #define PG8_STAGE(bufoff, gbase, voff) do { _Pragma("unroll") for (int _i = 0; _i < 2; ++_i) \
;         __builtin_amdgcn_global_load_lds((const unsigned*)((const char*)(gbase) + (voff)[_i]), (PG8_LAS unsigned*)(lds + (bufoff) + ldsw + _i * 8192), 16, 0, 0); } while (0)
; #define PG8_LDA(dst, b, h) do { _Pragma("unroll") for (int m = 0; m < 4; ++m) _Pragma("unroll") for (int k = 0; k < 2; ++k) dst[m][k] = *(const PG8_LAS bf16x8*)(lds + PG8_SA(b, h) + aoff + m * 2048 + k * 1024); } while (0)
; #define PG8_LDB(dst, b, h) do { _Pragma("unroll") for (int n = 0; n < 2; ++n) _Pragma("unroll") for (int k = 0; k < 2; ++k) dst[n][k] = *(const PG8_LAS bf16x8*)(lds + PG8_SB(b, h) + boff + n * 2048 + k * 1024); } while (0)
; #define PG8_MMA(ai, bj, At, Bt) do { __builtin_amdgcn_s_setprio(1); _Pragma("unroll") for (int m = 0; m < 4; ++m) _Pragma("unroll") for (int n = 0; n < 2; ++n) _Pragma("unroll") for (int k = 0; k < 2; ++k) \
;         acc[ai][bj][m][n] = __builtin_amdgcn_mfma_f32_16x16x32_bf16(Bt[n][k], At[m][k], acc[ai][bj][m][n], 0, 0, 0); __builtin_amdgcn_s_setprio(0); } while (0)
; #define PG8_WAIT_V(n) asm volatile("s_waitcnt vmcnt(" #n ")" ::: "memory")
; #define PG8_WAIT_L(n) asm volatile("s_waitcnt lgkmcnt(" #n ")" ::: "memory")
; #define PG8_BAR __builtin_amdgcn_s_barrier()
; #define PG8_SCHED __builtin_amdgcn_sched_barrier(0)
; template <class Epi, class Sched, bool ALIGN_EPI = false, bool SP2 = false>
; __device__ __forceinline__ void gemm_phase(PG8_LAS unsigned char* lds, const Gemm g, const Sched& S, const Epi& E) {
;     ...
;         for (int t = 0; t < nt; t += 2) {
;     ...
;             PG8_LDB(B0, 1, 0); PG8_LDB(B1, 1, 1); PG8_SCHED; PG8_LDA(At, 1, 0); PG8_STAGE(PG8_SA(0, 1), a2 + hstepA, voffA);
;             PG8_WAIT_V(8); PG8_WAIT_L(0); PG8_BAR; PG8_MMA(0, 0, At, B0); PG8_MMA(0, 1, At, B1); PG8_BAR; PG8_SCHED;
;             PG8_LDA(At, 1, 1); PG8_STAGE(PG8_SB(1, 0), b3, voffB); PG8_STAGE(PG8_SB(1, 1), b3 + hstepB, voffB); PG8_STAGE(PG8_SA(1, 0), a3, voffA);
;             PG8_WAIT_V(8); PG8_WAIT_L(0); PG8_BAR; PG8_MMA(1, 0, At, B0); PG8_MMA(1, 1, At, B1); PG8_BAR; PG8_SCHED;
	s_add_i32 s59, 0, 0x18000
	v_add_u32_e32 v159, s59, v153
	s_add_i32 s60, 0, 0x1c000
	ds_read_b128 v[144:147], v159
	ds_read_b128 v[148:151], v159 offset:1024
	ds_read_b128 v[166:169], v159 offset:2048
	ds_read_b128 v[170:173], v159 offset:3072
	v_add_u32_e32 v159, s60, v153
	ds_read_b128 v[174:177], v159
	ds_read_b128 v[178:181], v159 offset:1024
	ds_read_b128 v[182:185], v159 offset:2048
	ds_read_b128 v[186:189], v159 offset:3072
	s_add_u32 s44, s44, 0x240000
	s_addc_u32 s45, s45, 0
	s_mov_b32 m0, s48
	ds_read_b128 v[190:193], v157 offset:32768
	ds_read_b128 v[194:197], v157 offset:33792
	ds_read_b128 v[198:201], v157 offset:34816
	ds_read_b128 v[202:205], v157 offset:35840
	ds_read_b128 v[206:209], v157 offset:36864
	ds_read_b128 v[210:213], v157 offset:37888
	ds_read_b128 v[214:217], v157 offset:38912
	ds_read_b128 v[218:221], v157 offset:39936
	global_load_lds_dwordx4 v134, s[44:45]
	s_mov_b32 m0, s49
	s_nop 0
	global_load_lds_dwordx4 v130, s[44:45]
	s_waitcnt vmcnt(8)
	s_waitcnt lgkmcnt(0)
	s_barrier
	s_waitcnt lgkmcnt(0)
	v_mfma_f32_16x16x32_bf16 v[124:127], v[144:147], v[190:193], v[124:127]
	v_mfma_f32_16x16x32_bf16 v[120:123], v[166:169], v[190:193], v[120:123]
	v_mfma_f32_16x16x32_bf16 v[108:111], v[144:147], v[198:201], v[108:111]
	v_mfma_f32_16x16x32_bf16 v[104:107], v[166:169], v[198:201], v[104:107]
	v_mfma_f32_16x16x32_bf16 v[92:95], v[144:147], v[206:209], v[92:95]
	v_mfma_f32_16x16x32_bf16 v[88:91], v[166:169], v[206:209], v[88:91]
	v_mfma_f32_16x16x32_bf16 v[76:79], v[144:147], v[214:217], v[76:79]
	v_mfma_f32_16x16x32_bf16 v[72:75], v[166:169], v[214:217], v[72:75]
	v_mfma_f32_16x16x32_bf16 v[124:127], v[148:151], v[194:197], v[124:127]
	v_mfma_f32_16x16x32_bf16 v[120:123], v[170:173], v[194:197], v[120:123]
	v_mfma_f32_16x16x32_bf16 v[108:111], v[148:151], v[202:205], v[108:111]
	v_mfma_f32_16x16x32_bf16 v[104:107], v[170:173], v[202:205], v[104:107]
	v_mfma_f32_16x16x32_bf16 v[92:95], v[148:151], v[210:213], v[92:95]
	v_mfma_f32_16x16x32_bf16 v[88:91], v[170:173], v[210:213], v[88:91]
	v_mfma_f32_16x16x32_bf16 v[76:79], v[148:151], v[218:221], v[76:79]
	v_mfma_f32_16x16x32_bf16 v[72:75], v[170:173], v[218:221], v[72:75]
	v_mfma_f32_16x16x32_bf16 v[116:119], v[174:177], v[190:193], v[116:119]
	v_mfma_f32_16x16x32_bf16 v[112:115], v[182:185], v[190:193], v[112:115]
	v_mfma_f32_16x16x32_bf16 v[100:103], v[174:177], v[198:201], v[100:103]
	v_mfma_f32_16x16x32_bf16 v[96:99], v[182:185], v[198:201], v[96:99]
	v_mfma_f32_16x16x32_bf16 v[84:87], v[174:177], v[206:209], v[84:87]
	v_mfma_f32_16x16x32_bf16 v[80:83], v[182:185], v[206:209], v[80:83]
	v_mfma_f32_16x16x32_bf16 v[68:71], v[174:177], v[214:217], v[68:71]
	v_mfma_f32_16x16x32_bf16 v[64:67], v[182:185], v[214:217], v[64:67]
	v_mfma_f32_16x16x32_bf16 v[116:119], v[178:181], v[194:197], v[116:119]
	v_mfma_f32_16x16x32_bf16 v[112:115], v[186:189], v[194:197], v[112:115]
	v_mfma_f32_16x16x32_bf16 v[100:103], v[178:181], v[202:205], v[100:103]
	v_mfma_f32_16x16x32_bf16 v[96:99], v[186:189], v[202:205], v[96:99]
	v_mfma_f32_16x16x32_bf16 v[84:87], v[178:181], v[210:213], v[84:87]
	v_mfma_f32_16x16x32_bf16 v[80:83], v[186:189], v[210:213], v[80:83]
	v_mfma_f32_16x16x32_bf16 v[68:71], v[178:181], v[218:221], v[68:71]
	v_mfma_f32_16x16x32_bf16 v[64:67], v[186:189], v[218:221], v[64:67]
	s_barrier
	s_add_i32 s44, s59, s33
	v_lshl_add_u64 v[160:161], v[160:161], 0, s[16:17]
	s_mov_b32 m0, s44
	ds_read_b128 v[190:193], v157 offset:49152
	ds_read_b128 v[194:197], v157 offset:50176
	ds_read_b128 v[198:201], v157 offset:51200
	ds_read_b128 v[202:205], v157 offset:52224
	ds_read_b128 v[206:209], v157 offset:53248
	ds_read_b128 v[210:213], v157 offset:54272
	ds_read_b128 v[214:217], v157 offset:55296
	ds_read_b128 v[218:221], v157 offset:56320
	global_load_lds_dwordx4 v[160:161], off
	s_add_i32 m0, s44, 0x2000
	s_add_u32 s42, s42, 0x40080
	v_lshl_add_u64 v[160:161], v[222:223], 0, s[16:17]
	s_addc_u32 s43, s43, 0
	s_add_i32 s44, s60, s33
	global_load_lds_dwordx4 v[160:161], off
	s_mov_b32 m0, s44
	s_nop 0
	global_load_lds_dwordx4 v132, s[42:43]
	s_add_i32 m0, s44, 0x2000
	s_nop 0
	global_load_lds_dwordx4 v128, s[42:43]
	v_lshl_add_u64 v[160:161], v[224:225], 0, s[16:17]
	s_mov_b32 m0, s52
	s_nop 0
	global_load_lds_dwordx4 v[160:161], off
	v_lshl_add_u64 v[160:161], v[226:227], 0, s[16:17]
	s_mov_b32 m0, s53
	s_nop 0
	global_load_lds_dwordx4 v[160:161], off
	s_waitcnt vmcnt(8)
	s_waitcnt lgkmcnt(0)
	s_barrier
	s_waitcnt lgkmcnt(0)
	v_mfma_f32_16x16x32_bf16 v[60:63], v[144:147], v[190:193], v[60:63]
	v_mfma_f32_16x16x32_bf16 v[56:59], v[166:169], v[190:193], v[56:59]
	v_mfma_f32_16x16x32_bf16 v[44:47], v[144:147], v[198:201], v[44:47]
	v_mfma_f32_16x16x32_bf16 v[40:43], v[166:169], v[198:201], v[40:43]
	v_mfma_f32_16x16x32_bf16 v[28:31], v[144:147], v[206:209], v[28:31]
	v_mfma_f32_16x16x32_bf16 v[24:27], v[166:169], v[206:209], v[24:27]
	v_mfma_f32_16x16x32_bf16 v[12:15], v[144:147], v[214:217], v[12:15]
	v_mfma_f32_16x16x32_bf16 v[8:11], v[166:169], v[214:217], v[8:11]
	v_mfma_f32_16x16x32_bf16 v[60:63], v[148:151], v[194:197], v[60:63]
	v_mfma_f32_16x16x32_bf16 v[56:59], v[170:173], v[194:197], v[56:59]
	v_mfma_f32_16x16x32_bf16 v[44:47], v[148:151], v[202:205], v[44:47]
	v_mfma_f32_16x16x32_bf16 v[40:43], v[170:173], v[202:205], v[40:43]
	v_mfma_f32_16x16x32_bf16 v[28:31], v[148:151], v[210:213], v[28:31]
	v_mfma_f32_16x16x32_bf16 v[24:27], v[170:173], v[210:213], v[24:27]
	v_mfma_f32_16x16x32_bf16 v[12:15], v[148:151], v[218:221], v[12:15]
	v_mfma_f32_16x16x32_bf16 v[8:11], v[170:173], v[218:221], v[8:11]
	v_mfma_f32_16x16x32_bf16 v[52:55], v[174:177], v[190:193], v[52:55]
	v_mfma_f32_16x16x32_bf16 v[48:51], v[182:185], v[190:193], v[48:51]
	v_mfma_f32_16x16x32_bf16 v[36:39], v[174:177], v[198:201], v[36:39]
	v_mfma_f32_16x16x32_bf16 v[32:35], v[182:185], v[198:201], v[32:35]
	v_mfma_f32_16x16x32_bf16 v[20:23], v[174:177], v[206:209], v[20:23]
	v_mfma_f32_16x16x32_bf16 v[16:19], v[182:185], v[206:209], v[16:19]
	v_mfma_f32_16x16x32_bf16 v[4:7], v[174:177], v[214:217], v[4:7]
	v_mfma_f32_16x16x32_bf16 v[0:3], v[182:185], v[214:217], v[0:3]
	v_mfma_f32_16x16x32_bf16 v[52:55], v[178:181], v[194:197], v[52:55]
	v_mfma_f32_16x16x32_bf16 v[48:51], v[186:189], v[194:197], v[48:51]
	v_mfma_f32_16x16x32_bf16 v[36:39], v[178:181], v[202:205], v[36:39]
	v_mfma_f32_16x16x32_bf16 v[32:35], v[186:189], v[202:205], v[32:35]
	v_mfma_f32_16x16x32_bf16 v[20:23], v[178:181], v[210:213], v[20:23]
	v_mfma_f32_16x16x32_bf16 v[16:19], v[186:189], v[210:213], v[16:19]
	v_mfma_f32_16x16x32_bf16 v[4:7], v[178:181], v[218:221], v[4:7]
	v_mfma_f32_16x16x32_bf16 v[0:3], v[186:189], v[218:221], v[0:3]
	s_barrier
	s_add_i32 s58, s58, 2
	s_add_u32 s0, s0, 0x100
	s_addc_u32 s1, s1, 0
	s_add_u32 s31, s31, 0x100
	s_addc_u32 s34, s34, 0
	s_cmp_gt_u32 s58, 13
	s_cbranch_scc0 .LBB0_848
	s_and_b64 vcc, exec, s[18:19]
	s_cbranch_vccz .LBB0_851
	s_barrier

; #define PG8_STAGE(bufoff, gbase, voff) do { _Pragma("unroll") for (int _i = 0; _i < 2; ++_i) \
;         __builtin_amdgcn_global_load_lds((const unsigned*)((const char*)(gbase) + (voff)[_i]), (PG8_LAS unsigned*)(lds + (bufoff) + ldsw + _i * 8192), 16, 0, 0); } while (0)
; #define PG8_LDA(dst, b, h) do { _Pragma("unroll") for (int m = 0; m < 4; ++m) _Pragma("unroll") for (int k = 0; k < 2; ++k) dst[m][k] = *(const PG8_LAS bf16x8*)(lds + PG8_SA(b, h) + aoff + m * 2048 + k * 1024); } while (0)
; #define PG8_LDB(dst, b, h) do { _Pragma("unroll") for (int n = 0; n < 2; ++n) _Pragma("unroll") for (int k = 0; k < 2; ++k) dst[n][k] = *(const PG8_LAS bf16x8*)(lds + PG8_SB(b, h) + boff + n * 2048 + k * 1024); } while (0)
; #define PG8_MMA(ai, bj, At, Bt) do { __builtin_amdgcn_s_setprio(1); _Pragma("unroll") for (int m = 0; m < 4; ++m) _Pragma("unroll") for (int n = 0; n < 2; ++n) _Pragma("unroll") for (int k = 0; k < 2; ++k) \
;         acc[ai][bj][m][n] = __builtin_amdgcn_mfma_f32_16x16x32_bf16(Bt[n][k], At[m][k], acc[ai][bj][m][n], 0, 0, 0); __builtin_amdgcn_s_setprio(0); } while (0)
; #define PG8_WAIT_V(n) asm volatile("s_waitcnt vmcnt(" #n ")" ::: "memory")
; #define PG8_WAIT_L(n) asm volatile("s_waitcnt lgkmcnt(" #n ")" ::: "memory")
; template <class Epi, class Sched, bool ALIGN_EPI = false, bool SP2 = false>
; __device__ __forceinline__ void gemm_phase(PG8_LAS unsigned char* lds, const Gemm g, const Sched& S, const Epi& E) {
;     ...
;             const bool last = (t == nt - 2);
;             const char* a1 = cA + (size_t)(t + 1) * kstep;
;             const char* a2 = last ? nA : cA + (size_t)(t + 2) * kstep; const char* b2 = last ? nB : cB + (size_t)(t + 2) * kstep;
;             const char* a3 = a2 + kstep; const char* b3 = b2 + kstep;
;             if (last && has_next) S.a_ready(nxt);
;             if constexpr (SP2) {
;             PG8_LDB(B0, 0, 0); PG8_LDB(B1, 0, 1); PG8_SCHED; PG8_LDA(At, 0, 0); PG8_STAGE(PG8_SA(1, 1), a1 + hstepA, voffA);
;             PG8_WAIT_V(8); PG8_WAIT_L(0); PG8_BAR; PG8_MMA(0, 0, At, B0); PG8_MMA(0, 1, At, B1); PG8_BAR; PG8_SCHED;
;             PG8_LDA(At, 0, 1); PG8_STAGE(PG8_SB(0, 0), b2, voffB); PG8_STAGE(PG8_SB(0, 1), b2 + hstepB, voffB); PG8_STAGE(PG8_SA(0, 0), a2, voffA);
;             PG8_WAIT_V(8); PG8_WAIT_L(0); PG8_BAR; PG8_MMA(1, 0, At, B0); PG8_MMA(1, 1, At, B1); PG8_BAR; PG8_SCHED;
.LBB0_927:
	ds_read_b128 v[156:159], v153
	ds_read_b128 v[166:169], v153 offset:1024
	ds_read_b128 v[170:173], v153 offset:2048
	ds_read_b128 v[174:177], v153 offset:3072
	ds_read_b128 v[178:181], v154
	ds_read_b128 v[182:185], v154 offset:1024
	ds_read_b128 v[186:189], v154 offset:2048
	ds_read_b128 v[190:193], v154 offset:3072
	s_add_u32 s54, s52, 0xfff80080
	s_addc_u32 s55, s53, -1
	s_cmp_eq_u32 s71, 28
	s_cselect_b32 s57, s45, s55
	s_cselect_b32 s56, s65, s54
	s_cselect_b32 s55, s43, s70
	s_cselect_b32 s54, s68, s69
	s_add_i32 m0, s29, 0xc000
	ds_read_b128 v[194:197], v155
	ds_read_b128 v[198:201], v155 offset:1024
	ds_read_b128 v[202:205], v155 offset:2048
	ds_read_b128 v[206:209], v155 offset:3072
	ds_read_b128 v[210:213], v155 offset:4096
	ds_read_b128 v[214:217], v155 offset:5120
	ds_read_b128 v[218:221], v155 offset:6144
	ds_read_b128 v[222:225], v155 offset:7168
	global_load_lds_dwordx4 v136, s[52:53]
	s_add_i32 m0, s29, 0xe000
	s_nop 0
	global_load_lds_dwordx4 v138, s[52:53]
	s_waitcnt vmcnt(8)
	s_waitcnt lgkmcnt(0)
	s_barrier
	s_waitcnt lgkmcnt(0)
	v_mfma_f32_16x16x32_bf16 v[124:127], v[156:159], v[194:197], v[124:127]
	v_mfma_f32_16x16x32_bf16 v[120:123], v[170:173], v[194:197], v[120:123]
	v_mfma_f32_16x16x32_bf16 v[116:119], v[156:159], v[202:205], v[116:119]
	v_mfma_f32_16x16x32_bf16 v[108:111], v[170:173], v[202:205], v[108:111]
	v_mfma_f32_16x16x32_bf16 v[100:103], v[156:159], v[210:213], v[100:103]
	v_mfma_f32_16x16x32_bf16 v[92:95], v[170:173], v[210:213], v[92:95]
	v_mfma_f32_16x16x32_bf16 v[84:87], v[156:159], v[218:221], v[84:87]
	v_mfma_f32_16x16x32_bf16 v[76:79], v[170:173], v[218:221], v[76:79]
	v_mfma_f32_16x16x32_bf16 v[124:127], v[166:169], v[198:201], v[124:127]
	v_mfma_f32_16x16x32_bf16 v[120:123], v[174:177], v[198:201], v[120:123]
	v_mfma_f32_16x16x32_bf16 v[116:119], v[166:169], v[206:209], v[116:119]
	v_mfma_f32_16x16x32_bf16 v[108:111], v[174:177], v[206:209], v[108:111]
	v_mfma_f32_16x16x32_bf16 v[100:103], v[166:169], v[214:217], v[100:103]
	v_mfma_f32_16x16x32_bf16 v[92:95], v[174:177], v[214:217], v[92:95]
	v_mfma_f32_16x16x32_bf16 v[84:87], v[166:169], v[222:225], v[84:87]
	v_mfma_f32_16x16x32_bf16 v[76:79], v[174:177], v[222:225], v[76:79]
	v_mfma_f32_16x16x32_bf16 v[112:115], v[178:181], v[194:197], v[112:115]
	v_mfma_f32_16x16x32_bf16 v[104:107], v[186:189], v[194:197], v[104:107]
	v_mfma_f32_16x16x32_bf16 v[96:99], v[178:181], v[202:205], v[96:99]
	v_mfma_f32_16x16x32_bf16 v[88:91], v[186:189], v[202:205], v[88:91]
	v_mfma_f32_16x16x32_bf16 v[80:83], v[178:181], v[210:213], v[80:83]
	v_mfma_f32_16x16x32_bf16 v[72:75], v[186:189], v[210:213], v[72:75]
	v_mfma_f32_16x16x32_bf16 v[68:71], v[178:181], v[218:221], v[68:71]
	v_mfma_f32_16x16x32_bf16 v[64:67], v[186:189], v[218:221], v[64:67]
	v_mfma_f32_16x16x32_bf16 v[112:115], v[182:185], v[198:201], v[112:115]
	v_mfma_f32_16x16x32_bf16 v[104:107], v[190:193], v[198:201], v[104:107]
	v_mfma_f32_16x16x32_bf16 v[96:99], v[182:185], v[206:209], v[96:99]
	v_mfma_f32_16x16x32_bf16 v[88:91], v[190:193], v[206:209], v[88:91]
	v_mfma_f32_16x16x32_bf16 v[80:83], v[182:185], v[214:217], v[80:83]
	v_mfma_f32_16x16x32_bf16 v[72:75], v[190:193], v[214:217], v[72:75]
	v_mfma_f32_16x16x32_bf16 v[68:71], v[182:185], v[222:225], v[68:71]
	v_mfma_f32_16x16x32_bf16 v[64:67], v[190:193], v[222:225], v[64:67]
	s_barrier
	s_add_i32 s72, s58, s28
	v_lshl_add_u64 v[144:145], s[54:55], 0, v[130:131]
	s_mov_b32 m0, s72
	ds_read_b128 v[194:197], v155 offset:16384
	ds_read_b128 v[198:201], v155 offset:17408
	ds_read_b128 v[202:205], v155 offset:18432
	ds_read_b128 v[206:209], v155 offset:19456
	ds_read_b128 v[210:213], v155 offset:20480
	ds_read_b128 v[214:217], v155 offset:21504
	ds_read_b128 v[218:221], v155 offset:22528
	ds_read_b128 v[222:225], v155 offset:23552
	global_load_lds_dwordx4 v130, s[54:55]
	s_add_i32 m0, s72, 0x2000
	s_add_u32 s72, s54, 0x80000
	v_lshl_add_u64 v[160:161], s[54:55], 0, v[134:135]
	s_addc_u32 s73, s55, 0
	s_add_i32 s74, s59, s28
	global_load_lds_dwordx4 v134, s[54:55]
	s_mov_b32 m0, s74
	v_lshl_add_u64 v[228:229], s[56:57], 0, v[132:133]
	global_load_lds_dwordx4 v130, s[72:73]
	s_add_i32 m0, s74, 0x2000
	s_nop 0
	global_load_lds_dwordx4 v134, s[72:73]
	v_lshl_add_u64 v[226:227], s[56:57], 0, v[128:129]
	s_mov_b32 m0, s29
	s_nop 0
	global_load_lds_dwordx4 v128, s[56:57]
	s_mov_b32 m0, s30
	s_nop 0
	global_load_lds_dwordx4 v132, s[56:57]
	s_waitcnt vmcnt(8)
	s_waitcnt lgkmcnt(0)
	s_barrier
	s_waitcnt lgkmcnt(0)
	v_mfma_f32_16x16x32_bf16 v[60:63], v[156:159], v[194:197], v[60:63]
	v_mfma_f32_16x16x32_bf16 v[56:59], v[170:173], v[194:197], v[56:59]
	v_mfma_f32_16x16x32_bf16 v[52:55], v[156:159], v[202:205], v[52:55]
	v_mfma_f32_16x16x32_bf16 v[44:47], v[170:173], v[202:205], v[44:47]
	v_mfma_f32_16x16x32_bf16 v[36:39], v[156:159], v[210:213], v[36:39]
	v_mfma_f32_16x16x32_bf16 v[28:31], v[170:173], v[210:213], v[28:31]
	v_mfma_f32_16x16x32_bf16 v[20:23], v[156:159], v[218:221], v[20:23]
	v_mfma_f32_16x16x32_bf16 v[12:15], v[170:173], v[218:221], v[12:15]
	v_mfma_f32_16x16x32_bf16 v[60:63], v[166:169], v[198:201], v[60:63]
	v_mfma_f32_16x16x32_bf16 v[56:59], v[174:177], v[198:201], v[56:59]
	v_mfma_f32_16x16x32_bf16 v[52:55], v[166:169], v[206:209], v[52:55]
	v_mfma_f32_16x16x32_bf16 v[44:47], v[174:177], v[206:209], v[44:47]
	v_mfma_f32_16x16x32_bf16 v[36:39], v[166:169], v[214:217], v[36:39]
	v_mfma_f32_16x16x32_bf16 v[28:31], v[174:177], v[214:217], v[28:31]
	v_mfma_f32_16x16x32_bf16 v[20:23], v[166:169], v[222:225], v[20:23]
	v_mfma_f32_16x16x32_bf16 v[12:15], v[174:177], v[222:225], v[12:15]
	v_mfma_f32_16x16x32_bf16 v[48:51], v[178:181], v[194:197], v[48:51]
	v_mfma_f32_16x16x32_bf16 v[40:43], v[186:189], v[194:197], v[40:43]
	v_mfma_f32_16x16x32_bf16 v[32:35], v[178:181], v[202:205], v[32:35]
	v_mfma_f32_16x16x32_bf16 v[24:27], v[186:189], v[202:205], v[24:27]
	v_mfma_f32_16x16x32_bf16 v[16:19], v[178:181], v[210:213], v[16:19]
	v_mfma_f32_16x16x32_bf16 v[8:11], v[186:189], v[210:213], v[8:11]
	v_mfma_f32_16x16x32_bf16 v[4:7], v[178:181], v[218:221], v[4:7]
	v_mfma_f32_16x16x32_bf16 v[0:3], v[186:189], v[218:221], v[0:3]
	v_mfma_f32_16x16x32_bf16 v[48:51], v[182:185], v[198:201], v[48:51]
	v_mfma_f32_16x16x32_bf16 v[40:43], v[190:193], v[198:201], v[40:43]
	v_mfma_f32_16x16x32_bf16 v[32:35], v[182:185], v[206:209], v[32:35]
	v_mfma_f32_16x16x32_bf16 v[24:27], v[190:193], v[206:209], v[24:27]
	v_mfma_f32_16x16x32_bf16 v[16:19], v[182:185], v[214:217], v[16:19]
	v_mfma_f32_16x16x32_bf16 v[8:11], v[190:193], v[214:217], v[8:11]
	v_mfma_f32_16x16x32_bf16 v[4:7], v[182:185], v[222:225], v[4:7]
	v_mfma_f32_16x16x32_bf16 v[0:3], v[190:193], v[222:225], v[0:3]
	s_barrier
; #define PG8_STAGE(bufoff, gbase, voff) do { _Pragma("unroll") for (int _i = 0; _i < 2; ++_i) \
;         __builtin_amdgcn_global_load_lds((const unsigned*)((const char*)(gbase) + (voff)[_i]), (PG8_LAS unsigned*)(lds + (bufoff) + ldsw + _i * 8192), 16, 0, 0); } while (0)
; #define PG8_LDA(dst, b, h) do { _Pragma("unroll") for (int m = 0; m < 4; ++m) _Pragma("unroll") for (int k = 0; k < 2; ++k) dst[m][k] = *(const PG8_LAS bf16x8*)(lds + PG8_SA(b, h) + aoff + m * 2048 + k * 1024); } while (0)
; #define PG8_LDB(dst, b, h) do { _Pragma("unroll") for (int n = 0; n < 2; ++n) _Pragma("unroll") for (int k = 0; k < 2; ++k) dst[n][k] = *(const PG8_LAS bf16x8*)(lds + PG8_SB(b, h) + boff + n * 2048 + k * 1024); } while (0)
; #define PG8_MMA(ai, bj, At, Bt) do { __builtin_amdgcn_s_setprio(1); _Pragma("unroll") for (int m = 0; m < 4; ++m) _Pragma("unroll") for (int n = 0; n < 2; ++n) _Pragma("unroll") for (int k = 0; k < 2; ++k) \
;         acc[ai][bj][m][n] = __builtin_amdgcn_mfma_f32_16x16x32_bf16(Bt[n][k], At[m][k], acc[ai][bj][m][n], 0, 0, 0); __builtin_amdgcn_s_setprio(0); } while (0)
; #define PG8_WAIT_V(n) asm volatile("s_waitcnt vmcnt(" #n ")" ::: "memory")
; #define PG8_WAIT_L(n) asm volatile("s_waitcnt lgkmcnt(" #n ")" ::: "memory")
; #define PG8_BAR __builtin_amdgcn_s_barrier()
; #define PG8_SCHED __builtin_amdgcn_sched_barrier(0)
; template <class Epi, class Sched, bool ALIGN_EPI = false, bool SP2 = false>
; __device__ __forceinline__ void gemm_phase(PG8_LAS unsigned char* lds, const Gemm g, const Sched& S, const Epi& E) {
;     ...
;         for (int t = 0; t < nt; t += 2) {
;     ...
;             PG8_LDB(B0, 1, 0); PG8_LDB(B1, 1, 1); PG8_SCHED; PG8_LDA(At, 1, 0); PG8_STAGE(PG8_SA(0, 1), a2 + hstepA, voffA);
;             PG8_WAIT_V(8); PG8_WAIT_L(0); PG8_BAR; PG8_MMA(0, 0, At, B0); PG8_MMA(0, 1, At, B1); PG8_BAR; PG8_SCHED;
;             PG8_LDA(At, 1, 1); PG8_STAGE(PG8_SB(1, 0), b3, voffB); PG8_STAGE(PG8_SB(1, 1), b3 + hstepB, voffB); PG8_STAGE(PG8_SA(1, 0), a3, voffA);
;             PG8_WAIT_V(8); PG8_WAIT_L(0); PG8_BAR; PG8_MMA(1, 0, At, B0); PG8_MMA(1, 1, At, B1); PG8_BAR; PG8_SCHED;
	s_add_i32 s72, 0, 0x18000
	v_add_u32_e32 v163, s72, v151
	s_add_i32 s73, 0, 0x1c000
	ds_read_b128 v[156:159], v163
	ds_read_b128 v[166:169], v163 offset:1024
	ds_read_b128 v[170:173], v163 offset:2048
	ds_read_b128 v[174:177], v163 offset:3072
	v_add_u32_e32 v163, s73, v151
	ds_read_b128 v[178:181], v163
	ds_read_b128 v[182:185], v163 offset:1024
	ds_read_b128 v[186:189], v163 offset:2048
	ds_read_b128 v[190:193], v163 offset:3072
	s_add_u32 s56, s56, 0x80000
	s_addc_u32 s57, s57, 0
	s_mov_b32 m0, s31
	ds_read_b128 v[194:197], v155 offset:32768
	ds_read_b128 v[198:201], v155 offset:33792
	ds_read_b128 v[202:205], v155 offset:34816
	ds_read_b128 v[206:209], v155 offset:35840
	ds_read_b128 v[210:213], v155 offset:36864
	ds_read_b128 v[214:217], v155 offset:37888
	ds_read_b128 v[218:221], v155 offset:38912
	ds_read_b128 v[222:225], v155 offset:39936
	global_load_lds_dwordx4 v128, s[56:57]
	s_mov_b32 m0, s33
	s_nop 0
	global_load_lds_dwordx4 v132, s[56:57]
	s_waitcnt vmcnt(8)
	s_waitcnt lgkmcnt(0)
	s_barrier
	s_waitcnt lgkmcnt(0)
	v_mfma_f32_16x16x32_bf16 v[124:127], v[156:159], v[194:197], v[124:127]
	v_mfma_f32_16x16x32_bf16 v[120:123], v[170:173], v[194:197], v[120:123]
	v_mfma_f32_16x16x32_bf16 v[116:119], v[156:159], v[202:205], v[116:119]
	v_mfma_f32_16x16x32_bf16 v[108:111], v[170:173], v[202:205], v[108:111]
	v_mfma_f32_16x16x32_bf16 v[100:103], v[156:159], v[210:213], v[100:103]
	v_mfma_f32_16x16x32_bf16 v[92:95], v[170:173], v[210:213], v[92:95]
	v_mfma_f32_16x16x32_bf16 v[84:87], v[156:159], v[218:221], v[84:87]
	v_mfma_f32_16x16x32_bf16 v[76:79], v[170:173], v[218:221], v[76:79]
	v_mfma_f32_16x16x32_bf16 v[124:127], v[166:169], v[198:201], v[124:127]
	v_mfma_f32_16x16x32_bf16 v[120:123], v[174:177], v[198:201], v[120:123]
	v_mfma_f32_16x16x32_bf16 v[116:119], v[166:169], v[206:209], v[116:119]
	v_mfma_f32_16x16x32_bf16 v[108:111], v[174:177], v[206:209], v[108:111]
	v_mfma_f32_16x16x32_bf16 v[100:103], v[166:169], v[214:217], v[100:103]
	v_mfma_f32_16x16x32_bf16 v[92:95], v[174:177], v[214:217], v[92:95]
	v_mfma_f32_16x16x32_bf16 v[84:87], v[166:169], v[222:225], v[84:87]
	v_mfma_f32_16x16x32_bf16 v[76:79], v[174:177], v[222:225], v[76:79]
	v_mfma_f32_16x16x32_bf16 v[112:115], v[178:181], v[194:197], v[112:115]
	v_mfma_f32_16x16x32_bf16 v[104:107], v[186:189], v[194:197], v[104:107]
	v_mfma_f32_16x16x32_bf16 v[96:99], v[178:181], v[202:205], v[96:99]
	v_mfma_f32_16x16x32_bf16 v[88:91], v[186:189], v[202:205], v[88:91]
	v_mfma_f32_16x16x32_bf16 v[80:83], v[178:181], v[210:213], v[80:83]
	v_mfma_f32_16x16x32_bf16 v[72:75], v[186:189], v[210:213], v[72:75]
	v_mfma_f32_16x16x32_bf16 v[68:71], v[178:181], v[218:221], v[68:71]
	v_mfma_f32_16x16x32_bf16 v[64:67], v[186:189], v[218:221], v[64:67]
	v_mfma_f32_16x16x32_bf16 v[112:115], v[182:185], v[198:201], v[112:115]
	v_mfma_f32_16x16x32_bf16 v[104:107], v[190:193], v[198:201], v[104:107]
	v_mfma_f32_16x16x32_bf16 v[96:99], v[182:185], v[206:209], v[96:99]
	v_mfma_f32_16x16x32_bf16 v[88:91], v[190:193], v[206:209], v[88:91]
	v_mfma_f32_16x16x32_bf16 v[80:83], v[182:185], v[214:217], v[80:83]
	v_mfma_f32_16x16x32_bf16 v[72:75], v[190:193], v[214:217], v[72:75]
	v_mfma_f32_16x16x32_bf16 v[68:71], v[182:185], v[222:225], v[68:71]
	v_mfma_f32_16x16x32_bf16 v[64:67], v[190:193], v[222:225], v[64:67]
	s_barrier
	s_add_i32 s56, s72, s28
	v_lshl_add_u64 v[144:145], v[144:145], 0, s[16:17]
	s_mov_b32 m0, s56
	ds_read_b128 v[194:197], v155 offset:49152
	ds_read_b128 v[198:201], v155 offset:50176
	ds_read_b128 v[202:205], v155 offset:51200
	ds_read_b128 v[206:209], v155 offset:52224
	ds_read_b128 v[210:213], v155 offset:53248
	ds_read_b128 v[214:217], v155 offset:54272
	ds_read_b128 v[218:221], v155 offset:55296
	ds_read_b128 v[222:225], v155 offset:56320
	global_load_lds_dwordx4 v[144:145], off
	s_add_i32 m0, s56, 0x2000
	s_add_u32 s54, s54, 0x80080
	v_lshl_add_u64 v[144:145], v[160:161], 0, s[16:17]
	s_addc_u32 s55, s55, 0
	s_add_i32 s56, s73, s28
	global_load_lds_dwordx4 v[144:145], off
	s_mov_b32 m0, s56
	s_nop 0
	global_load_lds_dwordx4 v130, s[54:55]
	s_add_i32 m0, s56, 0x2000
	s_nop 0
	global_load_lds_dwordx4 v134, s[54:55]
	v_lshl_add_u64 v[144:145], v[226:227], 0, s[16:17]
	s_mov_b32 m0, s35
	s_nop 0
	global_load_lds_dwordx4 v[144:145], off
	v_lshl_add_u64 v[144:145], v[228:229], 0, s[16:17]
	s_mov_b32 m0, s51
	s_nop 0
	global_load_lds_dwordx4 v[144:145], off
	s_waitcnt vmcnt(8)
	s_waitcnt lgkmcnt(0)
	s_barrier
	s_waitcnt lgkmcnt(0)
	v_mfma_f32_16x16x32_bf16 v[60:63], v[156:159], v[194:197], v[60:63]
	v_mfma_f32_16x16x32_bf16 v[56:59], v[170:173], v[194:197], v[56:59]
	v_mfma_f32_16x16x32_bf16 v[52:55], v[156:159], v[202:205], v[52:55]
	v_mfma_f32_16x16x32_bf16 v[44:47], v[170:173], v[202:205], v[44:47]
	v_mfma_f32_16x16x32_bf16 v[36:39], v[156:159], v[210:213], v[36:39]
	v_mfma_f32_16x16x32_bf16 v[28:31], v[170:173], v[210:213], v[28:31]
	v_mfma_f32_16x16x32_bf16 v[20:23], v[156:159], v[218:221], v[20:23]
	v_mfma_f32_16x16x32_bf16 v[12:15], v[170:173], v[218:221], v[12:15]
	v_mfma_f32_16x16x32_bf16 v[60:63], v[166:169], v[198:201], v[60:63]
	v_mfma_f32_16x16x32_bf16 v[56:59], v[174:177], v[198:201], v[56:59]
	v_mfma_f32_16x16x32_bf16 v[52:55], v[166:169], v[206:209], v[52:55]
	v_mfma_f32_16x16x32_bf16 v[44:47], v[174:177], v[206:209], v[44:47]
	v_mfma_f32_16x16x32_bf16 v[36:39], v[166:169], v[214:217], v[36:39]
	v_mfma_f32_16x16x32_bf16 v[28:31], v[174:177], v[214:217], v[28:31]
	v_mfma_f32_16x16x32_bf16 v[20:23], v[166:169], v[222:225], v[20:23]
	v_mfma_f32_16x16x32_bf16 v[12:15], v[174:177], v[222:225], v[12:15]
	v_mfma_f32_16x16x32_bf16 v[48:51], v[178:181], v[194:197], v[48:51]
	v_mfma_f32_16x16x32_bf16 v[40:43], v[186:189], v[194:197], v[40:43]
	v_mfma_f32_16x16x32_bf16 v[32:35], v[178:181], v[202:205], v[32:35]
	v_mfma_f32_16x16x32_bf16 v[24:27], v[186:189], v[202:205], v[24:27]
	v_mfma_f32_16x16x32_bf16 v[16:19], v[178:181], v[210:213], v[16:19]
	v_mfma_f32_16x16x32_bf16 v[8:11], v[186:189], v[210:213], v[8:11]
	v_mfma_f32_16x16x32_bf16 v[4:7], v[178:181], v[218:221], v[4:7]
	v_mfma_f32_16x16x32_bf16 v[0:3], v[186:189], v[218:221], v[0:3]
	v_mfma_f32_16x16x32_bf16 v[48:51], v[182:185], v[198:201], v[48:51]
	v_mfma_f32_16x16x32_bf16 v[40:43], v[190:193], v[198:201], v[40:43]
	v_mfma_f32_16x16x32_bf16 v[32:35], v[182:185], v[206:209], v[32:35]
	v_mfma_f32_16x16x32_bf16 v[24:27], v[190:193], v[206:209], v[24:27]
	v_mfma_f32_16x16x32_bf16 v[16:19], v[182:185], v[214:217], v[16:19]
	v_mfma_f32_16x16x32_bf16 v[8:11], v[190:193], v[214:217], v[8:11]
	v_mfma_f32_16x16x32_bf16 v[4:7], v[182:185], v[222:225], v[4:7]
	v_mfma_f32_16x16x32_bf16 v[0:3], v[190:193], v[222:225], v[0:3]
	s_barrier
	s_add_i32 s71, s71, 2
	s_add_u32 s52, s52, 0x100
	s_addc_u32 s53, s53, 0
	s_add_u32 s69, s69, 0x100
	s_addc_u32 s70, s70, 0
	s_cmp_gt_u32 s71, 29
	s_cbranch_scc0 .LBB0_927
	s_and_b64 vcc, exec, s[18:19]
	s_cbranch_vccz .LBB0_930
	s_barrier

; #define PG8_STAGE(bufoff, gbase, voff) do { _Pragma("unroll") for (int _i = 0; _i < 2; ++_i) \
;         __builtin_amdgcn_global_load_lds((const unsigned*)((const char*)(gbase) + (voff)[_i]), (PG8_LAS unsigned*)(lds + (bufoff) + ldsw + _i * 8192), 16, 0, 0); } while (0)
; #define PG8_LDA(dst, b, h) do { _Pragma("unroll") for (int m = 0; m < 4; ++m) _Pragma("unroll") for (int k = 0; k < 2; ++k) dst[m][k] = *(const PG8_LAS bf16x8*)(lds + PG8_SA(b, h) + aoff + m * 2048 + k * 1024); } while (0)
; #define PG8_LDB(dst, b, h) do { _Pragma("unroll") for (int n = 0; n < 2; ++n) _Pragma("unroll") for (int k = 0; k < 2; ++k) dst[n][k] = *(const PG8_LAS bf16x8*)(lds + PG8_SB(b, h) + boff + n * 2048 + k * 1024); } while (0)
; #define PG8_MMA(ai, bj, At, Bt) do { __builtin_amdgcn_s_setprio(1); _Pragma("unroll") for (int m = 0; m < 4; ++m) _Pragma("unroll") for (int n = 0; n < 2; ++n) _Pragma("unroll") for (int k = 0; k < 2; ++k) \
;         acc[ai][bj][m][n] = __builtin_amdgcn_mfma_f32_16x16x32_bf16(Bt[n][k], At[m][k], acc[ai][bj][m][n], 0, 0, 0); __builtin_amdgcn_s_setprio(0); } while (0)
; #define PG8_WAIT_V(n) asm volatile("s_waitcnt vmcnt(" #n ")" ::: "memory")
; #define PG8_WAIT_L(n) asm volatile("s_waitcnt lgkmcnt(" #n ")" ::: "memory")
; #define PG8_BAR __builtin_amdgcn_s_barrier()
; #define PG8_SCHED __builtin_amdgcn_sched_barrier(0)
; template <class Epi, class Sched, bool ALIGN_EPI = false, bool SP2 = false>
; __device__ __forceinline__ void gemm_phase(PG8_LAS unsigned char* lds, const Gemm g, const Sched& S, const Epi& E) {
;     ...
;             const bool last = (t == nt - 2);
;             const char* a1 = cA + (size_t)(t + 1) * kstep;
;             const char* a2 = last ? nA : cA + (size_t)(t + 2) * kstep; const char* b2 = last ? nB : cB + (size_t)(t + 2) * kstep;
;             const char* a3 = a2 + kstep; const char* b3 = b2 + kstep;
;             if (last && has_next) S.a_ready(nxt);
;             if constexpr (SP2) {
;             PG8_LDB(B0, 0, 0); PG8_LDB(B1, 0, 1); PG8_SCHED; PG8_LDA(At, 0, 0); PG8_STAGE(PG8_SA(1, 1), a1 + hstepA, voffA);
;             PG8_WAIT_V(8); PG8_WAIT_L(0); PG8_BAR; PG8_MMA(0, 0, At, B0); PG8_MMA(0, 1, At, B1); PG8_BAR; PG8_SCHED;
;             PG8_LDA(At, 0, 1); PG8_STAGE(PG8_SB(0, 0), b2, voffB); PG8_STAGE(PG8_SB(0, 1), b2 + hstepB, voffB); PG8_STAGE(PG8_SA(0, 0), a2, voffA);
.LBB0_947:
	s_add_u32 s45, s50, s19
	s_addc_u32 s47, s51, 0
	s_add_u32 s49, s45, 0x100
	s_addc_u32 s60, s47, 0
	s_and_b64 s[58:59], s[56:57], exec
	s_cselect_b32 s61, s1, s60
	s_cselect_b32 s60, s0, s49
	s_add_u32 s19, s42, s19
	s_addc_u32 s49, s43, 0
	s_add_u32 s19, s19, 0x100
	s_addc_u32 s49, s49, 0
	s_and_b64 s[56:57], s[56:57], exec
	s_cselect_b32 s63, s53, s49
	s_cselect_b32 s62, s52, s19
	s_add_u32 s68, s45, 0x80080
	ds_read_b128 v[146:149], v143
	ds_read_b128 v[150:153], v143 offset:1024
	ds_read_b128 v[154:157], v143 offset:2048
	ds_read_b128 v[158:161], v143 offset:3072
	ds_read_b128 v[166:169], v144
	ds_read_b128 v[170:173], v144 offset:1024
	ds_read_b128 v[174:177], v144 offset:2048
	ds_read_b128 v[178:181], v144 offset:3072
	s_addc_u32 s69, s47, 0
	s_add_u32 s64, s62, 0x80000
	s_addc_u32 s65, s63, 0
	s_add_i32 s79, s71, s30
	s_add_i32 s78, s79, 0x2000
	s_add_i32 s77, 0, 0x18000
	s_add_i32 s76, 0, 0x1c000
	s_add_u32 s58, s60, 0x80000
	s_addc_u32 s59, s61, 0
	s_add_i32 s49, s77, s30
	s_add_i32 s45, s49, 0x2000
	s_add_u32 s56, s62, 0x80080
	s_addc_u32 s57, s63, 0
	s_add_i32 s47, s76, s30
	s_add_i32 s19, s47, 0x2000
	s_mov_b32 m0, s72
	ds_read_b128 v[182:185], v145
	ds_read_b128 v[186:189], v145 offset:1024
	ds_read_b128 v[190:193], v145 offset:2048
	ds_read_b128 v[194:197], v145 offset:3072
	ds_read_b128 v[198:201], v145 offset:4096
	ds_read_b128 v[202:205], v145 offset:5120
	ds_read_b128 v[206:209], v145 offset:6144
	ds_read_b128 v[210:213], v145 offset:7168
	global_load_lds_dwordx4 v128, s[68:69]
	s_mov_b32 m0, s73
	s_nop 0
	global_load_lds_dwordx4 v132, s[68:69]
	s_waitcnt vmcnt(8)
	s_waitcnt lgkmcnt(0)
	s_barrier
	s_waitcnt lgkmcnt(0)
	v_mfma_f32_16x16x32_bf16 v[124:127], v[146:149], v[182:185], v[124:127]
	v_mfma_f32_16x16x32_bf16 v[120:123], v[154:157], v[182:185], v[120:123]
	v_mfma_f32_16x16x32_bf16 v[116:119], v[146:149], v[190:193], v[116:119]
	v_mfma_f32_16x16x32_bf16 v[112:115], v[154:157], v[190:193], v[112:115]
	v_mfma_f32_16x16x32_bf16 v[100:103], v[146:149], v[198:201], v[100:103]
	v_mfma_f32_16x16x32_bf16 v[96:99], v[154:157], v[198:201], v[96:99]
	v_mfma_f32_16x16x32_bf16 v[84:87], v[146:149], v[206:209], v[84:87]
	v_mfma_f32_16x16x32_bf16 v[80:83], v[154:157], v[206:209], v[80:83]
	v_mfma_f32_16x16x32_bf16 v[124:127], v[150:153], v[186:189], v[124:127]
	v_mfma_f32_16x16x32_bf16 v[120:123], v[158:161], v[186:189], v[120:123]
	v_mfma_f32_16x16x32_bf16 v[116:119], v[150:153], v[194:197], v[116:119]
	v_mfma_f32_16x16x32_bf16 v[112:115], v[158:161], v[194:197], v[112:115]
	v_mfma_f32_16x16x32_bf16 v[100:103], v[150:153], v[202:205], v[100:103]
	v_mfma_f32_16x16x32_bf16 v[96:99], v[158:161], v[202:205], v[96:99]
	v_mfma_f32_16x16x32_bf16 v[84:87], v[150:153], v[210:213], v[84:87]
	v_mfma_f32_16x16x32_bf16 v[80:83], v[158:161], v[210:213], v[80:83]
	v_mfma_f32_16x16x32_bf16 v[108:111], v[166:169], v[182:185], v[108:111]
	v_mfma_f32_16x16x32_bf16 v[104:107], v[174:177], v[182:185], v[104:107]
	v_mfma_f32_16x16x32_bf16 v[92:95], v[166:169], v[190:193], v[92:95]
	v_mfma_f32_16x16x32_bf16 v[88:91], v[174:177], v[190:193], v[88:91]
	v_mfma_f32_16x16x32_bf16 v[76:79], v[166:169], v[198:201], v[76:79]
	v_mfma_f32_16x16x32_bf16 v[72:75], v[174:177], v[198:201], v[72:75]
	v_mfma_f32_16x16x32_bf16 v[68:71], v[166:169], v[206:209], v[68:71]
	v_mfma_f32_16x16x32_bf16 v[64:67], v[174:177], v[206:209], v[64:67]
	v_mfma_f32_16x16x32_bf16 v[108:111], v[170:173], v[186:189], v[108:111]
	v_mfma_f32_16x16x32_bf16 v[104:107], v[178:181], v[186:189], v[104:107]
	v_mfma_f32_16x16x32_bf16 v[92:95], v[170:173], v[194:197], v[92:95]
	v_mfma_f32_16x16x32_bf16 v[88:91], v[178:181], v[194:197], v[88:91]
	v_mfma_f32_16x16x32_bf16 v[76:79], v[170:173], v[202:205], v[76:79]
	v_mfma_f32_16x16x32_bf16 v[72:75], v[178:181], v[202:205], v[72:75]
	v_mfma_f32_16x16x32_bf16 v[68:71], v[170:173], v[210:213], v[68:71]
	v_mfma_f32_16x16x32_bf16 v[64:67], v[178:181], v[210:213], v[64:67]
	s_barrier
	s_mov_b32 m0, s74
	v_lshl_add_u64 v[214:215], s[62:63], 0, v[130:131]
	ds_read_b128 v[182:185], v145 offset:16384
	ds_read_b128 v[186:189], v145 offset:17408
	ds_read_b128 v[190:193], v145 offset:18432
	ds_read_b128 v[194:197], v145 offset:19456
	ds_read_b128 v[198:201], v145 offset:20480
	ds_read_b128 v[202:205], v145 offset:21504
	ds_read_b128 v[206:209], v145 offset:22528
	ds_read_b128 v[210:213], v145 offset:23552
	global_load_lds_dwordx4 v130, s[62:63]
	v_lshl_add_u64 v[216:217], s[62:63], 0, v[134:135]
	s_mov_b32 m0, s75
	s_nop 0
	global_load_lds_dwordx4 v134, s[62:63]
	s_mov_b32 m0, s79
	v_lshl_add_u64 v[220:221], s[60:61], 0, v[132:133]
	global_load_lds_dwordx4 v130, s[64:65]
	s_mov_b32 m0, s78
	s_nop 0
	global_load_lds_dwordx4 v134, s[64:65]
	v_lshl_add_u64 v[218:219], s[60:61], 0, v[128:129]
	s_mov_b32 m0, s21
	s_nop 0
	global_load_lds_dwordx4 v128, s[60:61]
	s_mov_b32 m0, s23
	s_nop 0
	global_load_lds_dwordx4 v132, s[60:61]
	s_waitcnt vmcnt(8)
	s_waitcnt lgkmcnt(0)
	s_barrier
; #define PG8_STAGE(bufoff, gbase, voff) do { _Pragma("unroll") for (int _i = 0; _i < 2; ++_i) \
;         __builtin_amdgcn_global_load_lds((const unsigned*)((const char*)(gbase) + (voff)[_i]), (PG8_LAS unsigned*)(lds + (bufoff) + ldsw + _i * 8192), 16, 0, 0); } while (0)
; #define PG8_LDA(dst, b, h) do { _Pragma("unroll") for (int m = 0; m < 4; ++m) _Pragma("unroll") for (int k = 0; k < 2; ++k) dst[m][k] = *(const PG8_LAS bf16x8*)(lds + PG8_SA(b, h) + aoff + m * 2048 + k * 1024); } while (0)
; #define PG8_LDB(dst, b, h) do { _Pragma("unroll") for (int n = 0; n < 2; ++n) _Pragma("unroll") for (int k = 0; k < 2; ++k) dst[n][k] = *(const PG8_LAS bf16x8*)(lds + PG8_SB(b, h) + boff + n * 2048 + k * 1024); } while (0)
; #define PG8_MMA(ai, bj, At, Bt) do { __builtin_amdgcn_s_setprio(1); _Pragma("unroll") for (int m = 0; m < 4; ++m) _Pragma("unroll") for (int n = 0; n < 2; ++n) _Pragma("unroll") for (int k = 0; k < 2; ++k) \
;         acc[ai][bj][m][n] = __builtin_amdgcn_mfma_f32_16x16x32_bf16(Bt[n][k], At[m][k], acc[ai][bj][m][n], 0, 0, 0); __builtin_amdgcn_s_setprio(0); } while (0)
; #define PG8_WAIT_V(n) asm volatile("s_waitcnt vmcnt(" #n ")" ::: "memory")
; #define PG8_WAIT_L(n) asm volatile("s_waitcnt lgkmcnt(" #n ")" ::: "memory")
; #define PG8_BAR __builtin_amdgcn_s_barrier()
; #define PG8_SCHED __builtin_amdgcn_sched_barrier(0)
; template <class Epi, class Sched, bool ALIGN_EPI = false, bool SP2 = false>
; __device__ __forceinline__ void gemm_phase(PG8_LAS unsigned char* lds, const Gemm g, const Sched& S, const Epi& E) {
;     ...
;             PG8_WAIT_V(8); PG8_WAIT_L(0); PG8_BAR; PG8_MMA(1, 0, At, B0); PG8_MMA(1, 1, At, B1); PG8_BAR; PG8_SCHED;
;             PG8_LDB(B0, 1, 0); PG8_LDB(B1, 1, 1); PG8_SCHED; PG8_LDA(At, 1, 0); PG8_STAGE(PG8_SA(0, 1), a2 + hstepA, voffA);
;             PG8_WAIT_V(8); PG8_WAIT_L(0); PG8_BAR; PG8_MMA(0, 0, At, B0); PG8_MMA(0, 1, At, B1); PG8_BAR; PG8_SCHED;
	s_waitcnt lgkmcnt(0)
	v_mfma_f32_16x16x32_bf16 v[60:63], v[146:149], v[182:185], v[60:63]
	v_mfma_f32_16x16x32_bf16 v[56:59], v[154:157], v[182:185], v[56:59]
	v_mfma_f32_16x16x32_bf16 v[52:55], v[146:149], v[190:193], v[52:55]
	v_mfma_f32_16x16x32_bf16 v[48:51], v[154:157], v[190:193], v[48:51]
	v_mfma_f32_16x16x32_bf16 v[36:39], v[146:149], v[198:201], v[36:39]
	v_mfma_f32_16x16x32_bf16 v[32:35], v[154:157], v[198:201], v[32:35]
	v_mfma_f32_16x16x32_bf16 v[20:23], v[146:149], v[206:209], v[20:23]
	v_mfma_f32_16x16x32_bf16 v[16:19], v[154:157], v[206:209], v[16:19]
	v_mfma_f32_16x16x32_bf16 v[60:63], v[150:153], v[186:189], v[60:63]
	v_mfma_f32_16x16x32_bf16 v[56:59], v[158:161], v[186:189], v[56:59]
	v_mfma_f32_16x16x32_bf16 v[52:55], v[150:153], v[194:197], v[52:55]
	v_mfma_f32_16x16x32_bf16 v[48:51], v[158:161], v[194:197], v[48:51]
	v_mfma_f32_16x16x32_bf16 v[36:39], v[150:153], v[202:205], v[36:39]
	v_mfma_f32_16x16x32_bf16 v[32:35], v[158:161], v[202:205], v[32:35]
	v_mfma_f32_16x16x32_bf16 v[20:23], v[150:153], v[210:213], v[20:23]
	v_mfma_f32_16x16x32_bf16 v[16:19], v[158:161], v[210:213], v[16:19]
	v_mfma_f32_16x16x32_bf16 v[44:47], v[166:169], v[182:185], v[44:47]
	v_mfma_f32_16x16x32_bf16 v[40:43], v[174:177], v[182:185], v[40:43]
	v_mfma_f32_16x16x32_bf16 v[28:31], v[166:169], v[190:193], v[28:31]
	v_mfma_f32_16x16x32_bf16 v[24:27], v[174:177], v[190:193], v[24:27]
	v_mfma_f32_16x16x32_bf16 v[12:15], v[166:169], v[198:201], v[12:15]
	v_mfma_f32_16x16x32_bf16 v[8:11], v[174:177], v[198:201], v[8:11]
	v_mfma_f32_16x16x32_bf16 v[4:7], v[166:169], v[206:209], v[4:7]
	v_mfma_f32_16x16x32_bf16 v[0:3], v[174:177], v[206:209], v[0:3]
	v_mfma_f32_16x16x32_bf16 v[44:47], v[170:173], v[186:189], v[44:47]
	v_mfma_f32_16x16x32_bf16 v[40:43], v[178:181], v[186:189], v[40:43]
	v_mfma_f32_16x16x32_bf16 v[28:31], v[170:173], v[194:197], v[28:31]
	v_mfma_f32_16x16x32_bf16 v[24:27], v[178:181], v[194:197], v[24:27]
	v_mfma_f32_16x16x32_bf16 v[12:15], v[170:173], v[202:205], v[12:15]
	v_mfma_f32_16x16x32_bf16 v[8:11], v[178:181], v[202:205], v[8:11]
	v_mfma_f32_16x16x32_bf16 v[4:7], v[170:173], v[210:213], v[4:7]
	v_mfma_f32_16x16x32_bf16 v[0:3], v[178:181], v[210:213], v[0:3]
	s_barrier
	v_add_u32_e32 v158, s77, v141
	v_add_u32_e32 v163, s76, v141
	ds_read_b128 v[146:149], v158
	ds_read_b128 v[150:153], v158 offset:1024
	ds_read_b128 v[154:157], v158 offset:2048
	ds_read_b128 v[158:161], v158 offset:3072
	ds_read_b128 v[166:169], v163
	ds_read_b128 v[170:173], v163 offset:1024
	ds_read_b128 v[174:177], v163 offset:2048
	ds_read_b128 v[178:181], v163 offset:3072
	s_mov_b32 m0, s31
	ds_read_b128 v[182:185], v145 offset:32768
	ds_read_b128 v[186:189], v145 offset:33792
	ds_read_b128 v[190:193], v145 offset:34816
	ds_read_b128 v[194:197], v145 offset:35840
	ds_read_b128 v[198:201], v145 offset:36864
	ds_read_b128 v[202:205], v145 offset:37888
	ds_read_b128 v[206:209], v145 offset:38912
	ds_read_b128 v[210:213], v145 offset:39936
	global_load_lds_dwordx4 v128, s[58:59]
	s_mov_b32 m0, s33
	s_nop 0
	global_load_lds_dwordx4 v132, s[58:59]
	s_waitcnt vmcnt(8)
	s_waitcnt lgkmcnt(0)
	s_barrier
	s_waitcnt lgkmcnt(0)
	v_mfma_f32_16x16x32_bf16 v[124:127], v[146:149], v[182:185], v[124:127]
	v_mfma_f32_16x16x32_bf16 v[120:123], v[154:157], v[182:185], v[120:123]
	v_mfma_f32_16x16x32_bf16 v[116:119], v[146:149], v[190:193], v[116:119]
	v_mfma_f32_16x16x32_bf16 v[112:115], v[154:157], v[190:193], v[112:115]
	v_mfma_f32_16x16x32_bf16 v[100:103], v[146:149], v[198:201], v[100:103]
	v_mfma_f32_16x16x32_bf16 v[96:99], v[154:157], v[198:201], v[96:99]
	v_mfma_f32_16x16x32_bf16 v[84:87], v[146:149], v[206:209], v[84:87]
	v_mfma_f32_16x16x32_bf16 v[80:83], v[154:157], v[206:209], v[80:83]
	v_mfma_f32_16x16x32_bf16 v[124:127], v[150:153], v[186:189], v[124:127]
	v_mfma_f32_16x16x32_bf16 v[120:123], v[158:161], v[186:189], v[120:123]
	v_mfma_f32_16x16x32_bf16 v[116:119], v[150:153], v[194:197], v[116:119]
	v_mfma_f32_16x16x32_bf16 v[112:115], v[158:161], v[194:197], v[112:115]
	v_mfma_f32_16x16x32_bf16 v[100:103], v[150:153], v[202:205], v[100:103]
	v_mfma_f32_16x16x32_bf16 v[96:99], v[158:161], v[202:205], v[96:99]
	v_mfma_f32_16x16x32_bf16 v[84:87], v[150:153], v[210:213], v[84:87]
	v_mfma_f32_16x16x32_bf16 v[80:83], v[158:161], v[210:213], v[80:83]
	v_mfma_f32_16x16x32_bf16 v[108:111], v[166:169], v[182:185], v[108:111]
	v_mfma_f32_16x16x32_bf16 v[104:107], v[174:177], v[182:185], v[104:107]
	v_mfma_f32_16x16x32_bf16 v[92:95], v[166:169], v[190:193], v[92:95]
	v_mfma_f32_16x16x32_bf16 v[88:91], v[174:177], v[190:193], v[88:91]
	v_mfma_f32_16x16x32_bf16 v[76:79], v[166:169], v[198:201], v[76:79]
	v_mfma_f32_16x16x32_bf16 v[72:75], v[174:177], v[198:201], v[72:75]
	v_mfma_f32_16x16x32_bf16 v[68:71], v[166:169], v[206:209], v[68:71]
	v_mfma_f32_16x16x32_bf16 v[64:67], v[174:177], v[206:209], v[64:67]
	v_mfma_f32_16x16x32_bf16 v[108:111], v[170:173], v[186:189], v[108:111]
	v_mfma_f32_16x16x32_bf16 v[104:107], v[178:181], v[186:189], v[104:107]
	v_mfma_f32_16x16x32_bf16 v[92:95], v[170:173], v[194:197], v[92:95]
	v_mfma_f32_16x16x32_bf16 v[88:91], v[178:181], v[194:197], v[88:91]
	v_mfma_f32_16x16x32_bf16 v[76:79], v[170:173], v[202:205], v[76:79]
	v_mfma_f32_16x16x32_bf16 v[72:75], v[178:181], v[202:205], v[72:75]
	v_mfma_f32_16x16x32_bf16 v[68:71], v[170:173], v[210:213], v[68:71]
	v_mfma_f32_16x16x32_bf16 v[64:67], v[178:181], v[210:213], v[64:67]
	s_barrier
; #define PG8_STAGE(bufoff, gbase, voff) do { _Pragma("unroll") for (int _i = 0; _i < 2; ++_i) \
;         __builtin_amdgcn_global_load_lds((const unsigned*)((const char*)(gbase) + (voff)[_i]), (PG8_LAS unsigned*)(lds + (bufoff) + ldsw + _i * 8192), 16, 0, 0); } while (0)
; #define PG8_LDA(dst, b, h) do { _Pragma("unroll") for (int m = 0; m < 4; ++m) _Pragma("unroll") for (int k = 0; k < 2; ++k) dst[m][k] = *(const PG8_LAS bf16x8*)(lds + PG8_SA(b, h) + aoff + m * 2048 + k * 1024); } while (0)
; #define PG8_MMA(ai, bj, At, Bt) do { __builtin_amdgcn_s_setprio(1); _Pragma("unroll") for (int m = 0; m < 4; ++m) _Pragma("unroll") for (int n = 0; n < 2; ++n) _Pragma("unroll") for (int k = 0; k < 2; ++k) \
;         acc[ai][bj][m][n] = __builtin_amdgcn_mfma_f32_16x16x32_bf16(Bt[n][k], At[m][k], acc[ai][bj][m][n], 0, 0, 0); __builtin_amdgcn_s_setprio(0); } while (0)
; #define PG8_WAIT_V(n) asm volatile("s_waitcnt vmcnt(" #n ")" ::: "memory")
; #define PG8_WAIT_L(n) asm volatile("s_waitcnt lgkmcnt(" #n ")" ::: "memory")
; #define PG8_BAR __builtin_amdgcn_s_barrier()
; #define PG8_SCHED __builtin_amdgcn_sched_barrier(0)
; template <class Epi, class Sched, bool ALIGN_EPI = false, bool SP2 = false>
; __device__ __forceinline__ void gemm_phase(PG8_LAS unsigned char* lds, const Gemm g, const Sched& S, const Epi& E) {
;     ...
;             PG8_LDA(At, 1, 1); PG8_STAGE(PG8_SB(1, 0), b3, voffB); PG8_STAGE(PG8_SB(1, 1), b3 + hstepB, voffB); PG8_STAGE(PG8_SA(1, 0), a3, voffA);
;             PG8_WAIT_V(8); PG8_WAIT_L(0); PG8_BAR; PG8_MMA(1, 0, At, B0); PG8_MMA(1, 1, At, B1); PG8_BAR; PG8_SCHED;
	s_mov_b32 m0, s49
	v_lshl_add_u64 v[214:215], v[214:215], 0, s[16:17]
	ds_read_b128 v[182:185], v145 offset:49152
	ds_read_b128 v[186:189], v145 offset:50176
	ds_read_b128 v[190:193], v145 offset:51200
	ds_read_b128 v[194:197], v145 offset:52224
	ds_read_b128 v[198:201], v145 offset:53248
	ds_read_b128 v[202:205], v145 offset:54272
	ds_read_b128 v[206:209], v145 offset:55296
	ds_read_b128 v[210:213], v145 offset:56320
	global_load_lds_dwordx4 v[214:215], off
	v_lshl_add_u64 v[214:215], v[216:217], 0, s[16:17]
	s_mov_b32 m0, s45
	s_nop 0
	global_load_lds_dwordx4 v[214:215], off
	s_mov_b32 m0, s47
	s_nop 0
	global_load_lds_dwordx4 v130, s[56:57]
	s_mov_b32 m0, s19
	s_nop 0
	global_load_lds_dwordx4 v134, s[56:57]
	v_lshl_add_u64 v[214:215], v[218:219], 0, s[16:17]
	s_mov_b32 m0, s35
	s_nop 0
	global_load_lds_dwordx4 v[214:215], off
	v_lshl_add_u64 v[214:215], v[220:221], 0, s[16:17]
	s_mov_b32 m0, s70
	s_nop 0
	global_load_lds_dwordx4 v[214:215], off
	s_waitcnt vmcnt(8)
	s_waitcnt lgkmcnt(0)
	s_barrier
	s_waitcnt lgkmcnt(0)
	v_mfma_f32_16x16x32_bf16 v[60:63], v[146:149], v[182:185], v[60:63]
	v_mfma_f32_16x16x32_bf16 v[56:59], v[154:157], v[182:185], v[56:59]
	v_mfma_f32_16x16x32_bf16 v[52:55], v[146:149], v[190:193], v[52:55]
	v_mfma_f32_16x16x32_bf16 v[48:51], v[154:157], v[190:193], v[48:51]
	v_mfma_f32_16x16x32_bf16 v[36:39], v[146:149], v[198:201], v[36:39]
	v_mfma_f32_16x16x32_bf16 v[32:35], v[154:157], v[198:201], v[32:35]
	v_mfma_f32_16x16x32_bf16 v[20:23], v[146:149], v[206:209], v[20:23]
	v_mfma_f32_16x16x32_bf16 v[16:19], v[154:157], v[206:209], v[16:19]
	v_mfma_f32_16x16x32_bf16 v[60:63], v[150:153], v[186:189], v[60:63]
	v_mfma_f32_16x16x32_bf16 v[56:59], v[158:161], v[186:189], v[56:59]
	v_mfma_f32_16x16x32_bf16 v[52:55], v[150:153], v[194:197], v[52:55]
	v_mfma_f32_16x16x32_bf16 v[48:51], v[158:161], v[194:197], v[48:51]
	v_mfma_f32_16x16x32_bf16 v[36:39], v[150:153], v[202:205], v[36:39]
	v_mfma_f32_16x16x32_bf16 v[32:35], v[158:161], v[202:205], v[32:35]
	v_mfma_f32_16x16x32_bf16 v[20:23], v[150:153], v[210:213], v[20:23]
	v_mfma_f32_16x16x32_bf16 v[16:19], v[158:161], v[210:213], v[16:19]
	v_mfma_f32_16x16x32_bf16 v[44:47], v[166:169], v[182:185], v[44:47]
	v_mfma_f32_16x16x32_bf16 v[40:43], v[174:177], v[182:185], v[40:43]
	v_mfma_f32_16x16x32_bf16 v[28:31], v[166:169], v[190:193], v[28:31]
	v_mfma_f32_16x16x32_bf16 v[24:27], v[174:177], v[190:193], v[24:27]
	v_mfma_f32_16x16x32_bf16 v[12:15], v[166:169], v[198:201], v[12:15]
	v_mfma_f32_16x16x32_bf16 v[8:11], v[174:177], v[198:201], v[8:11]
	v_mfma_f32_16x16x32_bf16 v[4:7], v[166:169], v[206:209], v[4:7]
	v_mfma_f32_16x16x32_bf16 v[0:3], v[174:177], v[206:209], v[0:3]
	v_mfma_f32_16x16x32_bf16 v[44:47], v[170:173], v[186:189], v[44:47]
	v_mfma_f32_16x16x32_bf16 v[40:43], v[178:181], v[186:189], v[40:43]
	v_mfma_f32_16x16x32_bf16 v[28:31], v[170:173], v[194:197], v[28:31]
	v_mfma_f32_16x16x32_bf16 v[24:27], v[178:181], v[194:197], v[24:27]
	v_mfma_f32_16x16x32_bf16 v[12:15], v[170:173], v[202:205], v[12:15]
	v_mfma_f32_16x16x32_bf16 v[8:11], v[178:181], v[202:205], v[8:11]
	v_mfma_f32_16x16x32_bf16 v[4:7], v[170:173], v[210:213], v[4:7]
	v_mfma_f32_16x16x32_bf16 v[0:3], v[178:181], v[210:213], v[0:3]
	s_barrier
	s_movk_i32 s19, 0x100
	s_andn2_b64 vcc, exec, s[54:55]
	s_mov_b64 s[56:57], -1
	s_mov_b64 s[54:55], 0
	s_cbranch_vccz .LBB0_947
	s_and_b64 vcc, exec, s[40:41]
	s_cbranch_vccz .LBB0_950
	s_barrier

; #define PG8_STAGE(bufoff, gbase, voff) do { _Pragma("unroll") for (int _i = 0; _i < 2; ++_i) \
;         __builtin_amdgcn_global_load_lds((const unsigned*)((const char*)(gbase) + (voff)[_i]), (PG8_LAS unsigned*)(lds + (bufoff) + ldsw + _i * 8192), 16, 0, 0); } while (0)
; #define PG8_LDA(dst, b, h) do { _Pragma("unroll") for (int m = 0; m < 4; ++m) _Pragma("unroll") for (int k = 0; k < 2; ++k) dst[m][k] = *(const PG8_LAS bf16x8*)(lds + PG8_SA(b, h) + aoff + m * 2048 + k * 1024); } while (0)
; #define PG8_LDB(dst, b, h) do { _Pragma("unroll") for (int n = 0; n < 2; ++n) _Pragma("unroll") for (int k = 0; k < 2; ++k) dst[n][k] = *(const PG8_LAS bf16x8*)(lds + PG8_SB(b, h) + boff + n * 2048 + k * 1024); } while (0)
; #define PG8_MMA(ai, bj, At, Bt) do { __builtin_amdgcn_s_setprio(1); _Pragma("unroll") for (int m = 0; m < 4; ++m) _Pragma("unroll") for (int n = 0; n < 2; ++n) _Pragma("unroll") for (int k = 0; k < 2; ++k) \
;         acc[ai][bj][m][n] = __builtin_amdgcn_mfma_f32_16x16x32_bf16(Bt[n][k], At[m][k], acc[ai][bj][m][n], 0, 0, 0); __builtin_amdgcn_s_setprio(0); } while (0)
; #define PG8_WAIT_V(n) asm volatile("s_waitcnt vmcnt(" #n ")" ::: "memory")
; #define PG8_WAIT_L(n) asm volatile("s_waitcnt lgkmcnt(" #n ")" ::: "memory")
; template <class Epi, class Sched, bool ALIGN_EPI = false, bool SP2 = false>
; __device__ __forceinline__ void gemm_phase(PG8_LAS unsigned char* lds, const Gemm g, const Sched& S, const Epi& E) {
;     ...
;             const bool last = (t == nt - 2);
;             const char* a1 = cA + (size_t)(t + 1) * kstep;
;             const char* a2 = last ? nA : cA + (size_t)(t + 2) * kstep; const char* b2 = last ? nB : cB + (size_t)(t + 2) * kstep;
;             const char* a3 = a2 + kstep; const char* b3 = b2 + kstep;
;             if (last && has_next) S.a_ready(nxt);
;             if constexpr (SP2) {
;             PG8_LDB(B0, 0, 0); PG8_LDB(B1, 0, 1); PG8_SCHED; PG8_LDA(At, 0, 0); PG8_STAGE(PG8_SA(1, 1), a1 + hstepA, voffA);
;             PG8_WAIT_V(8); PG8_WAIT_L(0); PG8_BAR; PG8_MMA(0, 0, At, B0); PG8_MMA(0, 1, At, B1); PG8_BAR; PG8_SCHED;
;             PG8_LDA(At, 0, 1); PG8_STAGE(PG8_SB(0, 0), b2, voffB); PG8_STAGE(PG8_SB(0, 1), b2 + hstepB, voffB); PG8_STAGE(PG8_SA(0, 0), a2, voffA);
;             PG8_WAIT_V(8); PG8_WAIT_L(0); PG8_BAR; PG8_MMA(1, 0, At, B0); PG8_MMA(1, 1, At, B1); PG8_BAR; PG8_SCHED;
.LBB0_1082:
	ds_read_b128 v[150:153], v147
	ds_read_b128 v[154:157], v147 offset:1024
	ds_read_b128 v[158:161], v147 offset:2048
	ds_read_b128 v[166:169], v147 offset:3072
	ds_read_b128 v[170:173], v148
	ds_read_b128 v[174:177], v148 offset:1024
	ds_read_b128 v[178:181], v148 offset:2048
	ds_read_b128 v[182:185], v148 offset:3072
	s_add_u32 s50, s48, 0xfff80080
	s_addc_u32 s51, s49, -1
	s_cmp_eq_u32 s66, 28
	s_cselect_b32 s53, s41, s51
	s_cselect_b32 s52, s62, s50
	s_cselect_b32 s51, s39, s65
	s_cselect_b32 s50, s63, s64
	s_add_i32 m0, s30, 0xc000
	ds_read_b128 v[186:189], v149
	ds_read_b128 v[190:193], v149 offset:1024
	ds_read_b128 v[194:197], v149 offset:2048
	ds_read_b128 v[198:201], v149 offset:3072
	ds_read_b128 v[202:205], v149 offset:4096
	ds_read_b128 v[206:209], v149 offset:5120
	ds_read_b128 v[210:213], v149 offset:6144
	ds_read_b128 v[214:217], v149 offset:7168
	global_load_lds_dwordx4 v136, s[48:49]
	s_add_i32 m0, s30, 0xe000
	s_nop 0
	global_load_lds_dwordx4 v138, s[48:49]
	s_waitcnt vmcnt(8)
	s_waitcnt lgkmcnt(0)
	s_barrier
	s_waitcnt lgkmcnt(0)
	v_mfma_f32_16x16x32_bf16 v[124:127], v[150:153], v[186:189], v[124:127]
	v_mfma_f32_16x16x32_bf16 v[120:123], v[158:161], v[186:189], v[120:123]
	v_mfma_f32_16x16x32_bf16 v[112:115], v[150:153], v[194:197], v[112:115]
	v_mfma_f32_16x16x32_bf16 v[104:107], v[158:161], v[194:197], v[104:107]
	v_mfma_f32_16x16x32_bf16 v[96:99], v[150:153], v[202:205], v[96:99]
	v_mfma_f32_16x16x32_bf16 v[88:91], v[158:161], v[202:205], v[88:91]
	v_mfma_f32_16x16x32_bf16 v[80:83], v[150:153], v[210:213], v[80:83]
	v_mfma_f32_16x16x32_bf16 v[72:75], v[158:161], v[210:213], v[72:75]
	v_mfma_f32_16x16x32_bf16 v[124:127], v[154:157], v[190:193], v[124:127]
	v_mfma_f32_16x16x32_bf16 v[120:123], v[166:169], v[190:193], v[120:123]
	v_mfma_f32_16x16x32_bf16 v[112:115], v[154:157], v[198:201], v[112:115]
	v_mfma_f32_16x16x32_bf16 v[104:107], v[166:169], v[198:201], v[104:107]
	v_mfma_f32_16x16x32_bf16 v[96:99], v[154:157], v[206:209], v[96:99]
	v_mfma_f32_16x16x32_bf16 v[88:91], v[166:169], v[206:209], v[88:91]
	v_mfma_f32_16x16x32_bf16 v[80:83], v[154:157], v[214:217], v[80:83]
	v_mfma_f32_16x16x32_bf16 v[72:75], v[166:169], v[214:217], v[72:75]
	v_mfma_f32_16x16x32_bf16 v[116:119], v[170:173], v[186:189], v[116:119]
	v_mfma_f32_16x16x32_bf16 v[108:111], v[178:181], v[186:189], v[108:111]
	v_mfma_f32_16x16x32_bf16 v[100:103], v[170:173], v[194:197], v[100:103]
	v_mfma_f32_16x16x32_bf16 v[92:95], v[178:181], v[194:197], v[92:95]
	v_mfma_f32_16x16x32_bf16 v[84:87], v[170:173], v[202:205], v[84:87]
	v_mfma_f32_16x16x32_bf16 v[76:79], v[178:181], v[202:205], v[76:79]
	v_mfma_f32_16x16x32_bf16 v[68:71], v[170:173], v[210:213], v[68:71]
	v_mfma_f32_16x16x32_bf16 v[64:67], v[178:181], v[210:213], v[64:67]
	v_mfma_f32_16x16x32_bf16 v[116:119], v[174:177], v[190:193], v[116:119]
	v_mfma_f32_16x16x32_bf16 v[108:111], v[182:185], v[190:193], v[108:111]
	v_mfma_f32_16x16x32_bf16 v[100:103], v[174:177], v[198:201], v[100:103]
	v_mfma_f32_16x16x32_bf16 v[92:95], v[182:185], v[198:201], v[92:95]
	v_mfma_f32_16x16x32_bf16 v[84:87], v[174:177], v[206:209], v[84:87]
	v_mfma_f32_16x16x32_bf16 v[76:79], v[182:185], v[206:209], v[76:79]
	v_mfma_f32_16x16x32_bf16 v[68:71], v[174:177], v[214:217], v[68:71]
	v_mfma_f32_16x16x32_bf16 v[64:67], v[182:185], v[214:217], v[64:67]
	s_barrier
	s_add_i32 s67, s55, s28
	v_lshl_add_u64 v[218:219], s[50:51], 0, v[132:133]
	s_mov_b32 m0, s67
	ds_read_b128 v[186:189], v149 offset:16384
	ds_read_b128 v[190:193], v149 offset:17408
	ds_read_b128 v[194:197], v149 offset:18432
	ds_read_b128 v[198:201], v149 offset:19456
	ds_read_b128 v[202:205], v149 offset:20480
	ds_read_b128 v[206:209], v149 offset:21504
	ds_read_b128 v[210:213], v149 offset:22528
	ds_read_b128 v[214:217], v149 offset:23552
	global_load_lds_dwordx4 v132, s[50:51]
	s_add_i32 m0, s67, 0x2000
	s_add_u32 s68, s50, 0x80000
	v_lshl_add_u64 v[220:221], s[50:51], 0, v[128:129]
	s_addc_u32 s69, s51, 0
	s_add_i32 s67, s56, s28
	global_load_lds_dwordx4 v128, s[50:51]
	s_mov_b32 m0, s67
	v_lshl_add_u64 v[224:225], s[52:53], 0, v[130:131]
	global_load_lds_dwordx4 v132, s[68:69]
	s_add_i32 m0, s67, 0x2000
	s_nop 0
	global_load_lds_dwordx4 v128, s[68:69]
	v_lshl_add_u64 v[222:223], s[52:53], 0, v[134:135]
	s_mov_b32 m0, s30
	s_nop 0
	global_load_lds_dwordx4 v134, s[52:53]
	s_mov_b32 m0, s31
	s_nop 0
	global_load_lds_dwordx4 v130, s[52:53]
	s_waitcnt vmcnt(8)
	s_waitcnt lgkmcnt(0)
	s_barrier
	s_waitcnt lgkmcnt(0)
	v_mfma_f32_16x16x32_bf16 v[60:63], v[150:153], v[186:189], v[60:63]
	v_mfma_f32_16x16x32_bf16 v[56:59], v[158:161], v[186:189], v[56:59]
	v_mfma_f32_16x16x32_bf16 v[48:51], v[150:153], v[194:197], v[48:51]
	v_mfma_f32_16x16x32_bf16 v[40:43], v[158:161], v[194:197], v[40:43]
	v_mfma_f32_16x16x32_bf16 v[32:35], v[150:153], v[202:205], v[32:35]
	v_mfma_f32_16x16x32_bf16 v[24:27], v[158:161], v[202:205], v[24:27]
	v_mfma_f32_16x16x32_bf16 v[16:19], v[150:153], v[210:213], v[16:19]
	v_mfma_f32_16x16x32_bf16 v[8:11], v[158:161], v[210:213], v[8:11]
	v_mfma_f32_16x16x32_bf16 v[60:63], v[154:157], v[190:193], v[60:63]
	v_mfma_f32_16x16x32_bf16 v[56:59], v[166:169], v[190:193], v[56:59]
	v_mfma_f32_16x16x32_bf16 v[48:51], v[154:157], v[198:201], v[48:51]
	v_mfma_f32_16x16x32_bf16 v[40:43], v[166:169], v[198:201], v[40:43]
	v_mfma_f32_16x16x32_bf16 v[32:35], v[154:157], v[206:209], v[32:35]
	v_mfma_f32_16x16x32_bf16 v[24:27], v[166:169], v[206:209], v[24:27]
	v_mfma_f32_16x16x32_bf16 v[16:19], v[154:157], v[214:217], v[16:19]
	v_mfma_f32_16x16x32_bf16 v[8:11], v[166:169], v[214:217], v[8:11]
	v_mfma_f32_16x16x32_bf16 v[52:55], v[170:173], v[186:189], v[52:55]
	v_mfma_f32_16x16x32_bf16 v[44:47], v[178:181], v[186:189], v[44:47]
	v_mfma_f32_16x16x32_bf16 v[36:39], v[170:173], v[194:197], v[36:39]
	v_mfma_f32_16x16x32_bf16 v[28:31], v[178:181], v[194:197], v[28:31]
	v_mfma_f32_16x16x32_bf16 v[20:23], v[170:173], v[202:205], v[20:23]
	v_mfma_f32_16x16x32_bf16 v[12:15], v[178:181], v[202:205], v[12:15]
	v_mfma_f32_16x16x32_bf16 v[4:7], v[170:173], v[210:213], v[4:7]
	v_mfma_f32_16x16x32_bf16 v[0:3], v[178:181], v[210:213], v[0:3]
	v_mfma_f32_16x16x32_bf16 v[52:55], v[174:177], v[190:193], v[52:55]
	v_mfma_f32_16x16x32_bf16 v[44:47], v[182:185], v[190:193], v[44:47]
	v_mfma_f32_16x16x32_bf16 v[36:39], v[174:177], v[198:201], v[36:39]
	v_mfma_f32_16x16x32_bf16 v[28:31], v[182:185], v[198:201], v[28:31]
	v_mfma_f32_16x16x32_bf16 v[20:23], v[174:177], v[206:209], v[20:23]
	v_mfma_f32_16x16x32_bf16 v[12:15], v[182:185], v[206:209], v[12:15]
	v_mfma_f32_16x16x32_bf16 v[4:7], v[174:177], v[214:217], v[4:7]
	v_mfma_f32_16x16x32_bf16 v[0:3], v[182:185], v[214:217], v[0:3]
	s_barrier
; #define PG8_STAGE(bufoff, gbase, voff) do { _Pragma("unroll") for (int _i = 0; _i < 2; ++_i) \
;         __builtin_amdgcn_global_load_lds((const unsigned*)((const char*)(gbase) + (voff)[_i]), (PG8_LAS unsigned*)(lds + (bufoff) + ldsw + _i * 8192), 16, 0, 0); } while (0)
; #define PG8_LDA(dst, b, h) do { _Pragma("unroll") for (int m = 0; m < 4; ++m) _Pragma("unroll") for (int k = 0; k < 2; ++k) dst[m][k] = *(const PG8_LAS bf16x8*)(lds + PG8_SA(b, h) + aoff + m * 2048 + k * 1024); } while (0)
; #define PG8_LDB(dst, b, h) do { _Pragma("unroll") for (int n = 0; n < 2; ++n) _Pragma("unroll") for (int k = 0; k < 2; ++k) dst[n][k] = *(const PG8_LAS bf16x8*)(lds + PG8_SB(b, h) + boff + n * 2048 + k * 1024); } while (0)
; #define PG8_MMA(ai, bj, At, Bt) do { __builtin_amdgcn_s_setprio(1); _Pragma("unroll") for (int m = 0; m < 4; ++m) _Pragma("unroll") for (int n = 0; n < 2; ++n) _Pragma("unroll") for (int k = 0; k < 2; ++k) \
;         acc[ai][bj][m][n] = __builtin_amdgcn_mfma_f32_16x16x32_bf16(Bt[n][k], At[m][k], acc[ai][bj][m][n], 0, 0, 0); __builtin_amdgcn_s_setprio(0); } while (0)
; #define PG8_WAIT_V(n) asm volatile("s_waitcnt vmcnt(" #n ")" ::: "memory")
; #define PG8_WAIT_L(n) asm volatile("s_waitcnt lgkmcnt(" #n ")" ::: "memory")
; #define PG8_BAR __builtin_amdgcn_s_barrier()
; #define PG8_SCHED __builtin_amdgcn_sched_barrier(0)
; template <class Epi, class Sched, bool ALIGN_EPI = false, bool SP2 = false>
; __device__ __forceinline__ void gemm_phase(PG8_LAS unsigned char* lds, const Gemm g, const Sched& S, const Epi& E) {
;     ...
;         for (int t = 0; t < nt; t += 2) {
;     ...
;             PG8_LDB(B0, 1, 0); PG8_LDB(B1, 1, 1); PG8_SCHED; PG8_LDA(At, 1, 0); PG8_STAGE(PG8_SA(0, 1), a2 + hstepA, voffA);
;             PG8_WAIT_V(8); PG8_WAIT_L(0); PG8_BAR; PG8_MMA(0, 0, At, B0); PG8_MMA(0, 1, At, B1); PG8_BAR; PG8_SCHED;
;             PG8_LDA(At, 1, 1); PG8_STAGE(PG8_SB(1, 0), b3, voffB); PG8_STAGE(PG8_SB(1, 1), b3 + hstepB, voffB); PG8_STAGE(PG8_SA(1, 0), a3, voffA);
;             PG8_WAIT_V(8); PG8_WAIT_L(0); PG8_BAR; PG8_MMA(1, 0, At, B0); PG8_MMA(1, 1, At, B1); PG8_BAR; PG8_SCHED;
	s_add_i32 s67, 0, 0x18000
	v_add_u32_e32 v163, s67, v145
	s_add_i32 s68, 0, 0x1c000
	ds_read_b128 v[150:153], v163
	ds_read_b128 v[154:157], v163 offset:1024
	ds_read_b128 v[158:161], v163 offset:2048
	ds_read_b128 v[166:169], v163 offset:3072
	v_add_u32_e32 v163, s68, v145
	ds_read_b128 v[170:173], v163
	ds_read_b128 v[174:177], v163 offset:1024
	ds_read_b128 v[178:181], v163 offset:2048
	ds_read_b128 v[182:185], v163 offset:3072
	s_add_u32 s52, s52, 0x80000
	s_addc_u32 s53, s53, 0
	s_mov_b32 m0, s33
	ds_read_b128 v[186:189], v149 offset:32768
	ds_read_b128 v[190:193], v149 offset:33792
	ds_read_b128 v[194:197], v149 offset:34816
	ds_read_b128 v[198:201], v149 offset:35840
	ds_read_b128 v[202:205], v149 offset:36864
	ds_read_b128 v[206:209], v149 offset:37888
	ds_read_b128 v[210:213], v149 offset:38912
	ds_read_b128 v[214:217], v149 offset:39936
	global_load_lds_dwordx4 v134, s[52:53]
	s_mov_b32 m0, s34
	s_nop 0
	global_load_lds_dwordx4 v130, s[52:53]
	s_waitcnt vmcnt(8)
	s_waitcnt lgkmcnt(0)
	s_barrier
	s_waitcnt lgkmcnt(0)
	v_mfma_f32_16x16x32_bf16 v[124:127], v[150:153], v[186:189], v[124:127]
	v_mfma_f32_16x16x32_bf16 v[120:123], v[158:161], v[186:189], v[120:123]
	v_mfma_f32_16x16x32_bf16 v[112:115], v[150:153], v[194:197], v[112:115]
	v_mfma_f32_16x16x32_bf16 v[104:107], v[158:161], v[194:197], v[104:107]
	v_mfma_f32_16x16x32_bf16 v[96:99], v[150:153], v[202:205], v[96:99]
	v_mfma_f32_16x16x32_bf16 v[88:91], v[158:161], v[202:205], v[88:91]
	v_mfma_f32_16x16x32_bf16 v[80:83], v[150:153], v[210:213], v[80:83]
	v_mfma_f32_16x16x32_bf16 v[72:75], v[158:161], v[210:213], v[72:75]
	v_mfma_f32_16x16x32_bf16 v[124:127], v[154:157], v[190:193], v[124:127]
	v_mfma_f32_16x16x32_bf16 v[120:123], v[166:169], v[190:193], v[120:123]
	v_mfma_f32_16x16x32_bf16 v[112:115], v[154:157], v[198:201], v[112:115]
	v_mfma_f32_16x16x32_bf16 v[104:107], v[166:169], v[198:201], v[104:107]
	v_mfma_f32_16x16x32_bf16 v[96:99], v[154:157], v[206:209], v[96:99]
	v_mfma_f32_16x16x32_bf16 v[88:91], v[166:169], v[206:209], v[88:91]
	v_mfma_f32_16x16x32_bf16 v[80:83], v[154:157], v[214:217], v[80:83]
	v_mfma_f32_16x16x32_bf16 v[72:75], v[166:169], v[214:217], v[72:75]
	v_mfma_f32_16x16x32_bf16 v[116:119], v[170:173], v[186:189], v[116:119]
	v_mfma_f32_16x16x32_bf16 v[108:111], v[178:181], v[186:189], v[108:111]
	v_mfma_f32_16x16x32_bf16 v[100:103], v[170:173], v[194:197], v[100:103]
	v_mfma_f32_16x16x32_bf16 v[92:95], v[178:181], v[194:197], v[92:95]
	v_mfma_f32_16x16x32_bf16 v[84:87], v[170:173], v[202:205], v[84:87]
	v_mfma_f32_16x16x32_bf16 v[76:79], v[178:181], v[202:205], v[76:79]
	v_mfma_f32_16x16x32_bf16 v[68:71], v[170:173], v[210:213], v[68:71]
	v_mfma_f32_16x16x32_bf16 v[64:67], v[178:181], v[210:213], v[64:67]
	v_mfma_f32_16x16x32_bf16 v[116:119], v[174:177], v[190:193], v[116:119]
	v_mfma_f32_16x16x32_bf16 v[108:111], v[182:185], v[190:193], v[108:111]
	v_mfma_f32_16x16x32_bf16 v[100:103], v[174:177], v[198:201], v[100:103]
	v_mfma_f32_16x16x32_bf16 v[92:95], v[182:185], v[198:201], v[92:95]
	v_mfma_f32_16x16x32_bf16 v[84:87], v[174:177], v[206:209], v[84:87]
	v_mfma_f32_16x16x32_bf16 v[76:79], v[182:185], v[206:209], v[76:79]
	v_mfma_f32_16x16x32_bf16 v[68:71], v[174:177], v[214:217], v[68:71]
	v_mfma_f32_16x16x32_bf16 v[64:67], v[182:185], v[214:217], v[64:67]
	s_barrier
	s_add_i32 s52, s67, s28
	v_lshl_add_u64 v[218:219], v[218:219], 0, s[10:11]
	s_mov_b32 m0, s52
	ds_read_b128 v[186:189], v149 offset:49152
	ds_read_b128 v[190:193], v149 offset:50176
	ds_read_b128 v[194:197], v149 offset:51200
	ds_read_b128 v[198:201], v149 offset:52224
	ds_read_b128 v[202:205], v149 offset:53248
	ds_read_b128 v[206:209], v149 offset:54272
	ds_read_b128 v[210:213], v149 offset:55296
	ds_read_b128 v[214:217], v149 offset:56320
	global_load_lds_dwordx4 v[218:219], off
	s_add_i32 m0, s52, 0x2000
	s_add_u32 s50, s50, 0x80080
	v_lshl_add_u64 v[218:219], v[220:221], 0, s[10:11]
	s_addc_u32 s51, s51, 0
	s_add_i32 s52, s68, s28
	global_load_lds_dwordx4 v[218:219], off
	s_mov_b32 m0, s52
	s_nop 0
	global_load_lds_dwordx4 v132, s[50:51]
	s_add_i32 m0, s52, 0x2000
	s_nop 0
	global_load_lds_dwordx4 v128, s[50:51]
	v_lshl_add_u64 v[218:219], v[222:223], 0, s[10:11]
	s_mov_b32 m0, s47
	s_nop 0
	global_load_lds_dwordx4 v[218:219], off
	v_lshl_add_u64 v[218:219], v[224:225], 0, s[10:11]
	s_mov_b32 m0, s54
	s_nop 0
	global_load_lds_dwordx4 v[218:219], off
	s_waitcnt vmcnt(8)
	s_waitcnt lgkmcnt(0)
	s_barrier
	s_waitcnt lgkmcnt(0)
	v_mfma_f32_16x16x32_bf16 v[60:63], v[150:153], v[186:189], v[60:63]
	v_mfma_f32_16x16x32_bf16 v[56:59], v[158:161], v[186:189], v[56:59]
	v_mfma_f32_16x16x32_bf16 v[48:51], v[150:153], v[194:197], v[48:51]
	v_mfma_f32_16x16x32_bf16 v[40:43], v[158:161], v[194:197], v[40:43]
	v_mfma_f32_16x16x32_bf16 v[32:35], v[150:153], v[202:205], v[32:35]
	v_mfma_f32_16x16x32_bf16 v[24:27], v[158:161], v[202:205], v[24:27]
	v_mfma_f32_16x16x32_bf16 v[16:19], v[150:153], v[210:213], v[16:19]
	v_mfma_f32_16x16x32_bf16 v[8:11], v[158:161], v[210:213], v[8:11]
	v_mfma_f32_16x16x32_bf16 v[60:63], v[154:157], v[190:193], v[60:63]
	v_mfma_f32_16x16x32_bf16 v[56:59], v[166:169], v[190:193], v[56:59]
	v_mfma_f32_16x16x32_bf16 v[48:51], v[154:157], v[198:201], v[48:51]
	v_mfma_f32_16x16x32_bf16 v[40:43], v[166:169], v[198:201], v[40:43]
	v_mfma_f32_16x16x32_bf16 v[32:35], v[154:157], v[206:209], v[32:35]
	v_mfma_f32_16x16x32_bf16 v[24:27], v[166:169], v[206:209], v[24:27]
	v_mfma_f32_16x16x32_bf16 v[16:19], v[154:157], v[214:217], v[16:19]
	v_mfma_f32_16x16x32_bf16 v[8:11], v[166:169], v[214:217], v[8:11]
	v_mfma_f32_16x16x32_bf16 v[52:55], v[170:173], v[186:189], v[52:55]
	v_mfma_f32_16x16x32_bf16 v[44:47], v[178:181], v[186:189], v[44:47]
	v_mfma_f32_16x16x32_bf16 v[36:39], v[170:173], v[194:197], v[36:39]
	v_mfma_f32_16x16x32_bf16 v[28:31], v[178:181], v[194:197], v[28:31]
	v_mfma_f32_16x16x32_bf16 v[20:23], v[170:173], v[202:205], v[20:23]
	v_mfma_f32_16x16x32_bf16 v[12:15], v[178:181], v[202:205], v[12:15]
	v_mfma_f32_16x16x32_bf16 v[4:7], v[170:173], v[210:213], v[4:7]
	v_mfma_f32_16x16x32_bf16 v[0:3], v[178:181], v[210:213], v[0:3]
	v_mfma_f32_16x16x32_bf16 v[52:55], v[174:177], v[190:193], v[52:55]
	v_mfma_f32_16x16x32_bf16 v[44:47], v[182:185], v[190:193], v[44:47]
	v_mfma_f32_16x16x32_bf16 v[36:39], v[174:177], v[198:201], v[36:39]
	v_mfma_f32_16x16x32_bf16 v[28:31], v[182:185], v[198:201], v[28:31]
	v_mfma_f32_16x16x32_bf16 v[20:23], v[174:177], v[206:209], v[20:23]
	v_mfma_f32_16x16x32_bf16 v[12:15], v[182:185], v[206:209], v[12:15]
	v_mfma_f32_16x16x32_bf16 v[4:7], v[174:177], v[214:217], v[4:7]
	v_mfma_f32_16x16x32_bf16 v[0:3], v[182:185], v[214:217], v[0:3]
	s_barrier
	s_add_i32 s66, s66, 2
	s_add_u32 s48, s48, 0x100
	s_addc_u32 s49, s49, 0
	s_add_u32 s64, s64, 0x100
	s_addc_u32 s65, s65, 0
	s_cmp_gt_u32 s66, 29
	s_cbranch_scc0 .LBB0_1082
	s_and_b64 vcc, exec, s[16:17]
	s_cbranch_vccz .LBB0_1085
	s_barrier

; #define PG8_STAGE(bufoff, gbase, voff) do { _Pragma("unroll") for (int _i = 0; _i < 2; ++_i) \
;         __builtin_amdgcn_global_load_lds((const unsigned*)((const char*)(gbase) + (voff)[_i]), (PG8_LAS unsigned*)(lds + (bufoff) + ldsw + _i * 8192), 16, 0, 0); } while (0)
; #define PG8_LDA(dst, b, h) do { _Pragma("unroll") for (int m = 0; m < 4; ++m) _Pragma("unroll") for (int k = 0; k < 2; ++k) dst[m][k] = *(const PG8_LAS bf16x8*)(lds + PG8_SA(b, h) + aoff + m * 2048 + k * 1024); } while (0)
; #define PG8_LDB(dst, b, h) do { _Pragma("unroll") for (int n = 0; n < 2; ++n) _Pragma("unroll") for (int k = 0; k < 2; ++k) dst[n][k] = *(const PG8_LAS bf16x8*)(lds + PG8_SB(b, h) + boff + n * 2048 + k * 1024); } while (0)
; #define PG8_MMA(ai, bj, At, Bt) do { __builtin_amdgcn_s_setprio(1); _Pragma("unroll") for (int m = 0; m < 4; ++m) _Pragma("unroll") for (int n = 0; n < 2; ++n) _Pragma("unroll") for (int k = 0; k < 2; ++k) \
;         acc[ai][bj][m][n] = __builtin_amdgcn_mfma_f32_16x16x32_bf16(Bt[n][k], At[m][k], acc[ai][bj][m][n], 0, 0, 0); __builtin_amdgcn_s_setprio(0); } while (0)
; #define PG8_WAIT_V(n) asm volatile("s_waitcnt vmcnt(" #n ")" ::: "memory")
; #define PG8_WAIT_L(n) asm volatile("s_waitcnt lgkmcnt(" #n ")" ::: "memory")
; template <class Epi, class Sched, bool ALIGN_EPI = false, bool SP2 = false>
; __device__ __forceinline__ void gemm_phase(PG8_LAS unsigned char* lds, const Gemm g, const Sched& S, const Epi& E) {
;     ...
;             const bool last = (t == nt - 2);
;             const char* a1 = cA + (size_t)(t + 1) * kstep;
;             const char* a2 = last ? nA : cA + (size_t)(t + 2) * kstep; const char* b2 = last ? nB : cB + (size_t)(t + 2) * kstep;
;             const char* a3 = a2 + kstep; const char* b3 = b2 + kstep;
;             if (last && has_next) S.a_ready(nxt);
;             if constexpr (SP2) {
;             PG8_LDB(B0, 0, 0); PG8_LDB(B1, 0, 1); PG8_SCHED; PG8_LDA(At, 0, 0); PG8_STAGE(PG8_SA(1, 1), a1 + hstepA, voffA);
;             PG8_WAIT_V(8); PG8_WAIT_L(0); PG8_BAR; PG8_MMA(0, 0, At, B0); PG8_MMA(0, 1, At, B1); PG8_BAR; PG8_SCHED;
;             PG8_LDA(At, 0, 1); PG8_STAGE(PG8_SB(0, 0), b2, voffB); PG8_STAGE(PG8_SB(0, 1), b2 + hstepB, voffB); PG8_STAGE(PG8_SA(0, 0), a2, voffA);
;             PG8_WAIT_V(8); PG8_WAIT_L(0); PG8_BAR; PG8_MMA(1, 0, At, B0); PG8_MMA(1, 1, At, B1); PG8_BAR; PG8_SCHED;
.LBB0_1161:
	ds_read_b128 v[166:169], v157
	ds_read_b128 v[170:173], v157 offset:1024
	ds_read_b128 v[174:177], v157 offset:2048
	ds_read_b128 v[178:181], v157 offset:3072
	ds_read_b128 v[182:185], v158
	ds_read_b128 v[186:189], v158 offset:1024
	ds_read_b128 v[190:193], v158 offset:2048
	ds_read_b128 v[194:197], v158 offset:3072
	s_add_u32 s50, s48, 0xffe00080
	s_addc_u32 s51, s49, -1
	s_cmpk_eq_i32 s65, 0x7c
	s_cselect_b32 s53, s41, s51
	s_cselect_b32 s52, s61, s50
	s_cselect_b32 s51, s39, s64
	s_cselect_b32 s50, s62, s63
	s_add_i32 m0, s29, 0xc000
	ds_read_b128 v[198:201], v159
	ds_read_b128 v[202:205], v159 offset:1024
	ds_read_b128 v[206:209], v159 offset:2048
	ds_read_b128 v[210:213], v159 offset:3072
	ds_read_b128 v[214:217], v159 offset:4096
	ds_read_b128 v[218:221], v159 offset:5120
	ds_read_b128 v[222:225], v159 offset:6144
	ds_read_b128 v[226:229], v159 offset:7168
	global_load_lds_dwordx4 v136, s[48:49]
	s_add_i32 m0, s29, 0xe000
	s_nop 0
	global_load_lds_dwordx4 v138, s[48:49]
	s_waitcnt vmcnt(8)
	s_waitcnt lgkmcnt(0)
	s_barrier
	s_waitcnt lgkmcnt(0)
	v_mfma_f32_16x16x32_bf16 v[124:127], v[166:169], v[198:201], v[124:127]
	v_mfma_f32_16x16x32_bf16 v[120:123], v[174:177], v[198:201], v[120:123]
	v_mfma_f32_16x16x32_bf16 v[116:119], v[166:169], v[206:209], v[116:119]
	v_mfma_f32_16x16x32_bf16 v[108:111], v[174:177], v[206:209], v[108:111]
	v_mfma_f32_16x16x32_bf16 v[100:103], v[166:169], v[214:217], v[100:103]
	v_mfma_f32_16x16x32_bf16 v[92:95], v[174:177], v[214:217], v[92:95]
	v_mfma_f32_16x16x32_bf16 v[80:83], v[166:169], v[222:225], v[80:83]
	v_mfma_f32_16x16x32_bf16 v[72:75], v[174:177], v[222:225], v[72:75]
	v_mfma_f32_16x16x32_bf16 v[124:127], v[170:173], v[202:205], v[124:127]
	v_mfma_f32_16x16x32_bf16 v[120:123], v[178:181], v[202:205], v[120:123]
	v_mfma_f32_16x16x32_bf16 v[116:119], v[170:173], v[210:213], v[116:119]
	v_mfma_f32_16x16x32_bf16 v[108:111], v[178:181], v[210:213], v[108:111]
	v_mfma_f32_16x16x32_bf16 v[100:103], v[170:173], v[218:221], v[100:103]
	v_mfma_f32_16x16x32_bf16 v[92:95], v[178:181], v[218:221], v[92:95]
	v_mfma_f32_16x16x32_bf16 v[80:83], v[170:173], v[226:229], v[80:83]
	v_mfma_f32_16x16x32_bf16 v[72:75], v[178:181], v[226:229], v[72:75]
	v_mfma_f32_16x16x32_bf16 v[112:115], v[182:185], v[198:201], v[112:115]
	v_mfma_f32_16x16x32_bf16 v[104:107], v[190:193], v[198:201], v[104:107]
	v_mfma_f32_16x16x32_bf16 v[96:99], v[182:185], v[206:209], v[96:99]
	v_mfma_f32_16x16x32_bf16 v[88:91], v[190:193], v[206:209], v[88:91]
	v_mfma_f32_16x16x32_bf16 v[84:87], v[182:185], v[214:217], v[84:87]
	v_mfma_f32_16x16x32_bf16 v[76:79], v[190:193], v[214:217], v[76:79]
	v_mfma_f32_16x16x32_bf16 v[68:71], v[182:185], v[222:225], v[68:71]
	v_mfma_f32_16x16x32_bf16 v[64:67], v[190:193], v[222:225], v[64:67]
	v_mfma_f32_16x16x32_bf16 v[112:115], v[186:189], v[202:205], v[112:115]
	v_mfma_f32_16x16x32_bf16 v[104:107], v[194:197], v[202:205], v[104:107]
	v_mfma_f32_16x16x32_bf16 v[96:99], v[186:189], v[210:213], v[96:99]
	v_mfma_f32_16x16x32_bf16 v[88:91], v[194:197], v[210:213], v[88:91]
	v_mfma_f32_16x16x32_bf16 v[84:87], v[186:189], v[218:221], v[84:87]
	v_mfma_f32_16x16x32_bf16 v[76:79], v[194:197], v[218:221], v[76:79]
	v_mfma_f32_16x16x32_bf16 v[68:71], v[186:189], v[226:229], v[68:71]
	v_mfma_f32_16x16x32_bf16 v[64:67], v[194:197], v[226:229], v[64:67]
	s_barrier
	s_add_i32 s66, s54, s28
	v_lshl_add_u64 v[144:145], s[50:51], 0, v[130:131]
	s_mov_b32 m0, s66
	ds_read_b128 v[198:201], v159 offset:16384
	ds_read_b128 v[202:205], v159 offset:17408
	ds_read_b128 v[206:209], v159 offset:18432
	ds_read_b128 v[210:213], v159 offset:19456
	ds_read_b128 v[214:217], v159 offset:20480
	ds_read_b128 v[218:221], v159 offset:21504
	ds_read_b128 v[222:225], v159 offset:22528
	ds_read_b128 v[226:229], v159 offset:23552
	global_load_lds_dwordx4 v130, s[50:51]
	s_add_i32 m0, s66, 0x2000
	s_add_u32 s66, s50, 0x200000
	v_lshl_add_u64 v[160:161], s[50:51], 0, v[134:135]
	s_addc_u32 s67, s51, 0
	s_add_i32 s68, s55, s28
	global_load_lds_dwordx4 v134, s[50:51]
	s_mov_b32 m0, s68
	v_lshl_add_u64 v[232:233], s[52:53], 0, v[132:133]
	global_load_lds_dwordx4 v130, s[66:67]
	s_add_i32 m0, s68, 0x2000
	s_nop 0
	global_load_lds_dwordx4 v134, s[66:67]
	v_lshl_add_u64 v[230:231], s[52:53], 0, v[128:129]
	s_mov_b32 m0, s29
	s_nop 0
	global_load_lds_dwordx4 v128, s[52:53]
	s_mov_b32 m0, s30
	s_nop 0
	global_load_lds_dwordx4 v132, s[52:53]
	s_waitcnt vmcnt(8)
	s_waitcnt lgkmcnt(0)
	s_barrier
	s_waitcnt lgkmcnt(0)
	v_mfma_f32_16x16x32_bf16 v[60:63], v[166:169], v[198:201], v[60:63]
	v_mfma_f32_16x16x32_bf16 v[56:59], v[174:177], v[198:201], v[56:59]
	v_mfma_f32_16x16x32_bf16 v[52:55], v[166:169], v[206:209], v[52:55]
	v_mfma_f32_16x16x32_bf16 v[44:47], v[174:177], v[206:209], v[44:47]
	v_mfma_f32_16x16x32_bf16 v[36:39], v[166:169], v[214:217], v[36:39]
	v_mfma_f32_16x16x32_bf16 v[28:31], v[174:177], v[214:217], v[28:31]
	v_mfma_f32_16x16x32_bf16 v[20:23], v[166:169], v[222:225], v[20:23]
	v_mfma_f32_16x16x32_bf16 v[12:15], v[174:177], v[222:225], v[12:15]
	v_mfma_f32_16x16x32_bf16 v[60:63], v[170:173], v[202:205], v[60:63]
	v_mfma_f32_16x16x32_bf16 v[56:59], v[178:181], v[202:205], v[56:59]
	v_mfma_f32_16x16x32_bf16 v[52:55], v[170:173], v[210:213], v[52:55]
	v_mfma_f32_16x16x32_bf16 v[44:47], v[178:181], v[210:213], v[44:47]
	v_mfma_f32_16x16x32_bf16 v[36:39], v[170:173], v[218:221], v[36:39]
	v_mfma_f32_16x16x32_bf16 v[28:31], v[178:181], v[218:221], v[28:31]
	v_mfma_f32_16x16x32_bf16 v[20:23], v[170:173], v[226:229], v[20:23]
	v_mfma_f32_16x16x32_bf16 v[12:15], v[178:181], v[226:229], v[12:15]
	v_mfma_f32_16x16x32_bf16 v[48:51], v[182:185], v[198:201], v[48:51]
	v_mfma_f32_16x16x32_bf16 v[40:43], v[190:193], v[198:201], v[40:43]
	v_mfma_f32_16x16x32_bf16 v[32:35], v[182:185], v[206:209], v[32:35]
	v_mfma_f32_16x16x32_bf16 v[24:27], v[190:193], v[206:209], v[24:27]
	v_mfma_f32_16x16x32_bf16 v[16:19], v[182:185], v[214:217], v[16:19]
	v_mfma_f32_16x16x32_bf16 v[8:11], v[190:193], v[214:217], v[8:11]
	v_mfma_f32_16x16x32_bf16 v[4:7], v[182:185], v[222:225], v[4:7]
	v_mfma_f32_16x16x32_bf16 v[0:3], v[190:193], v[222:225], v[0:3]
	v_mfma_f32_16x16x32_bf16 v[48:51], v[186:189], v[202:205], v[48:51]
	v_mfma_f32_16x16x32_bf16 v[40:43], v[194:197], v[202:205], v[40:43]
	v_mfma_f32_16x16x32_bf16 v[32:35], v[186:189], v[210:213], v[32:35]
	v_mfma_f32_16x16x32_bf16 v[24:27], v[194:197], v[210:213], v[24:27]
	v_mfma_f32_16x16x32_bf16 v[16:19], v[186:189], v[218:221], v[16:19]
	v_mfma_f32_16x16x32_bf16 v[8:11], v[194:197], v[218:221], v[8:11]
	v_mfma_f32_16x16x32_bf16 v[4:7], v[186:189], v[226:229], v[4:7]
	v_mfma_f32_16x16x32_bf16 v[0:3], v[194:197], v[226:229], v[0:3]
	s_barrier
; #define PG8_STAGE(bufoff, gbase, voff) do { _Pragma("unroll") for (int _i = 0; _i < 2; ++_i) \
;         __builtin_amdgcn_global_load_lds((const unsigned*)((const char*)(gbase) + (voff)[_i]), (PG8_LAS unsigned*)(lds + (bufoff) + ldsw + _i * 8192), 16, 0, 0); } while (0)
; #define PG8_LDA(dst, b, h) do { _Pragma("unroll") for (int m = 0; m < 4; ++m) _Pragma("unroll") for (int k = 0; k < 2; ++k) dst[m][k] = *(const PG8_LAS bf16x8*)(lds + PG8_SA(b, h) + aoff + m * 2048 + k * 1024); } while (0)
; #define PG8_LDB(dst, b, h) do { _Pragma("unroll") for (int n = 0; n < 2; ++n) _Pragma("unroll") for (int k = 0; k < 2; ++k) dst[n][k] = *(const PG8_LAS bf16x8*)(lds + PG8_SB(b, h) + boff + n * 2048 + k * 1024); } while (0)
; #define PG8_MMA(ai, bj, At, Bt) do { __builtin_amdgcn_s_setprio(1); _Pragma("unroll") for (int m = 0; m < 4; ++m) _Pragma("unroll") for (int n = 0; n < 2; ++n) _Pragma("unroll") for (int k = 0; k < 2; ++k) \
;         acc[ai][bj][m][n] = __builtin_amdgcn_mfma_f32_16x16x32_bf16(Bt[n][k], At[m][k], acc[ai][bj][m][n], 0, 0, 0); __builtin_amdgcn_s_setprio(0); } while (0)
; #define PG8_WAIT_V(n) asm volatile("s_waitcnt vmcnt(" #n ")" ::: "memory")
; #define PG8_WAIT_L(n) asm volatile("s_waitcnt lgkmcnt(" #n ")" ::: "memory")
; #define PG8_BAR __builtin_amdgcn_s_barrier()
; #define PG8_SCHED __builtin_amdgcn_sched_barrier(0)
; template <class Epi, class Sched, bool ALIGN_EPI = false, bool SP2 = false>
; __device__ __forceinline__ void gemm_phase(PG8_LAS unsigned char* lds, const Gemm g, const Sched& S, const Epi& E) {
;     ...
;         for (int t = 0; t < nt; t += 2) {
;     ...
;             PG8_LDB(B0, 1, 0); PG8_LDB(B1, 1, 1); PG8_SCHED; PG8_LDA(At, 1, 0); PG8_STAGE(PG8_SA(0, 1), a2 + hstepA, voffA);
;             PG8_WAIT_V(8); PG8_WAIT_L(0); PG8_BAR; PG8_MMA(0, 0, At, B0); PG8_MMA(0, 1, At, B1); PG8_BAR; PG8_SCHED;
;             PG8_LDA(At, 1, 1); PG8_STAGE(PG8_SB(1, 0), b3, voffB); PG8_STAGE(PG8_SB(1, 1), b3 + hstepB, voffB); PG8_STAGE(PG8_SA(1, 0), a3, voffA);
;             PG8_WAIT_V(8); PG8_WAIT_L(0); PG8_BAR; PG8_MMA(1, 0, At, B0); PG8_MMA(1, 1, At, B1); PG8_BAR; PG8_SCHED;
	s_add_i32 s66, 0, 0x18000
	v_add_u32_e32 v163, s66, v155
	s_add_i32 s67, 0, 0x1c000
	ds_read_b128 v[166:169], v163
	ds_read_b128 v[170:173], v163 offset:1024
	ds_read_b128 v[174:177], v163 offset:2048
	ds_read_b128 v[178:181], v163 offset:3072
	v_add_u32_e32 v163, s67, v155
	ds_read_b128 v[182:185], v163
	ds_read_b128 v[186:189], v163 offset:1024
	ds_read_b128 v[190:193], v163 offset:2048
	ds_read_b128 v[194:197], v163 offset:3072
	s_add_u32 s52, s52, 0x200000
	s_addc_u32 s53, s53, 0
	s_mov_b32 m0, s31
	ds_read_b128 v[198:201], v159 offset:32768
	ds_read_b128 v[202:205], v159 offset:33792
	ds_read_b128 v[206:209], v159 offset:34816
	ds_read_b128 v[210:213], v159 offset:35840
	ds_read_b128 v[214:217], v159 offset:36864
	ds_read_b128 v[218:221], v159 offset:37888
	ds_read_b128 v[222:225], v159 offset:38912
	ds_read_b128 v[226:229], v159 offset:39936
	global_load_lds_dwordx4 v128, s[52:53]
	s_mov_b32 m0, s33
	s_nop 0
	global_load_lds_dwordx4 v132, s[52:53]
	s_waitcnt vmcnt(8)
	s_waitcnt lgkmcnt(0)
	s_barrier
	s_waitcnt lgkmcnt(0)
	v_mfma_f32_16x16x32_bf16 v[124:127], v[166:169], v[198:201], v[124:127]
	v_mfma_f32_16x16x32_bf16 v[120:123], v[174:177], v[198:201], v[120:123]
	v_mfma_f32_16x16x32_bf16 v[116:119], v[166:169], v[206:209], v[116:119]
	v_mfma_f32_16x16x32_bf16 v[108:111], v[174:177], v[206:209], v[108:111]
	v_mfma_f32_16x16x32_bf16 v[100:103], v[166:169], v[214:217], v[100:103]
	v_mfma_f32_16x16x32_bf16 v[92:95], v[174:177], v[214:217], v[92:95]
	v_mfma_f32_16x16x32_bf16 v[80:83], v[166:169], v[222:225], v[80:83]
	v_mfma_f32_16x16x32_bf16 v[72:75], v[174:177], v[222:225], v[72:75]
	v_mfma_f32_16x16x32_bf16 v[124:127], v[170:173], v[202:205], v[124:127]
	v_mfma_f32_16x16x32_bf16 v[120:123], v[178:181], v[202:205], v[120:123]
	v_mfma_f32_16x16x32_bf16 v[116:119], v[170:173], v[210:213], v[116:119]
	v_mfma_f32_16x16x32_bf16 v[108:111], v[178:181], v[210:213], v[108:111]
	v_mfma_f32_16x16x32_bf16 v[100:103], v[170:173], v[218:221], v[100:103]
	v_mfma_f32_16x16x32_bf16 v[92:95], v[178:181], v[218:221], v[92:95]
	v_mfma_f32_16x16x32_bf16 v[80:83], v[170:173], v[226:229], v[80:83]
	v_mfma_f32_16x16x32_bf16 v[72:75], v[178:181], v[226:229], v[72:75]
	v_mfma_f32_16x16x32_bf16 v[112:115], v[182:185], v[198:201], v[112:115]
	v_mfma_f32_16x16x32_bf16 v[104:107], v[190:193], v[198:201], v[104:107]
	v_mfma_f32_16x16x32_bf16 v[96:99], v[182:185], v[206:209], v[96:99]
	v_mfma_f32_16x16x32_bf16 v[88:91], v[190:193], v[206:209], v[88:91]
	v_mfma_f32_16x16x32_bf16 v[84:87], v[182:185], v[214:217], v[84:87]
	v_mfma_f32_16x16x32_bf16 v[76:79], v[190:193], v[214:217], v[76:79]
	v_mfma_f32_16x16x32_bf16 v[68:71], v[182:185], v[222:225], v[68:71]
	v_mfma_f32_16x16x32_bf16 v[64:67], v[190:193], v[222:225], v[64:67]
	v_mfma_f32_16x16x32_bf16 v[112:115], v[186:189], v[202:205], v[112:115]
	v_mfma_f32_16x16x32_bf16 v[104:107], v[194:197], v[202:205], v[104:107]
	v_mfma_f32_16x16x32_bf16 v[96:99], v[186:189], v[210:213], v[96:99]
	v_mfma_f32_16x16x32_bf16 v[88:91], v[194:197], v[210:213], v[88:91]
	v_mfma_f32_16x16x32_bf16 v[84:87], v[186:189], v[218:221], v[84:87]
	v_mfma_f32_16x16x32_bf16 v[76:79], v[194:197], v[218:221], v[76:79]
	v_mfma_f32_16x16x32_bf16 v[68:71], v[186:189], v[226:229], v[68:71]
	v_mfma_f32_16x16x32_bf16 v[64:67], v[194:197], v[226:229], v[64:67]
	s_barrier
	s_add_i32 s52, s66, s28
	v_lshl_add_u64 v[144:145], v[144:145], 0, s[10:11]
	s_mov_b32 m0, s52
	ds_read_b128 v[198:201], v159 offset:49152
	ds_read_b128 v[202:205], v159 offset:50176
	ds_read_b128 v[206:209], v159 offset:51200
	ds_read_b128 v[210:213], v159 offset:52224
	ds_read_b128 v[214:217], v159 offset:53248
	ds_read_b128 v[218:221], v159 offset:54272
	ds_read_b128 v[222:225], v159 offset:55296
	ds_read_b128 v[226:229], v159 offset:56320
	global_load_lds_dwordx4 v[144:145], off
	s_add_i32 m0, s52, 0x2000
	s_add_u32 s50, s50, 0x200080
	v_lshl_add_u64 v[144:145], v[160:161], 0, s[10:11]
	s_addc_u32 s51, s51, 0
	s_add_i32 s52, s67, s28
	global_load_lds_dwordx4 v[144:145], off
	s_mov_b32 m0, s52
	s_nop 0
	global_load_lds_dwordx4 v130, s[50:51]
	s_add_i32 m0, s52, 0x2000
	s_nop 0
	global_load_lds_dwordx4 v134, s[50:51]
	v_lshl_add_u64 v[144:145], v[230:231], 0, s[10:11]
	s_mov_b32 m0, s35
	s_nop 0
	global_load_lds_dwordx4 v[144:145], off
	v_lshl_add_u64 v[144:145], v[232:233], 0, s[10:11]
	s_mov_b32 m0, s47
	s_nop 0
	global_load_lds_dwordx4 v[144:145], off
	s_waitcnt vmcnt(8)
	s_waitcnt lgkmcnt(0)
	s_barrier
	s_waitcnt lgkmcnt(0)
	v_mfma_f32_16x16x32_bf16 v[60:63], v[166:169], v[198:201], v[60:63]
	v_mfma_f32_16x16x32_bf16 v[56:59], v[174:177], v[198:201], v[56:59]
	v_mfma_f32_16x16x32_bf16 v[52:55], v[166:169], v[206:209], v[52:55]
	v_mfma_f32_16x16x32_bf16 v[44:47], v[174:177], v[206:209], v[44:47]
	v_mfma_f32_16x16x32_bf16 v[36:39], v[166:169], v[214:217], v[36:39]
	v_mfma_f32_16x16x32_bf16 v[28:31], v[174:177], v[214:217], v[28:31]
	v_mfma_f32_16x16x32_bf16 v[20:23], v[166:169], v[222:225], v[20:23]
	v_mfma_f32_16x16x32_bf16 v[12:15], v[174:177], v[222:225], v[12:15]
	v_mfma_f32_16x16x32_bf16 v[60:63], v[170:173], v[202:205], v[60:63]
	v_mfma_f32_16x16x32_bf16 v[56:59], v[178:181], v[202:205], v[56:59]
	v_mfma_f32_16x16x32_bf16 v[52:55], v[170:173], v[210:213], v[52:55]
	v_mfma_f32_16x16x32_bf16 v[44:47], v[178:181], v[210:213], v[44:47]
	v_mfma_f32_16x16x32_bf16 v[36:39], v[170:173], v[218:221], v[36:39]
	v_mfma_f32_16x16x32_bf16 v[28:31], v[178:181], v[218:221], v[28:31]
	v_mfma_f32_16x16x32_bf16 v[20:23], v[170:173], v[226:229], v[20:23]
	v_mfma_f32_16x16x32_bf16 v[12:15], v[178:181], v[226:229], v[12:15]
	v_mfma_f32_16x16x32_bf16 v[48:51], v[182:185], v[198:201], v[48:51]
	v_mfma_f32_16x16x32_bf16 v[40:43], v[190:193], v[198:201], v[40:43]
	v_mfma_f32_16x16x32_bf16 v[32:35], v[182:185], v[206:209], v[32:35]
	v_mfma_f32_16x16x32_bf16 v[24:27], v[190:193], v[206:209], v[24:27]
	v_mfma_f32_16x16x32_bf16 v[16:19], v[182:185], v[214:217], v[16:19]
	v_mfma_f32_16x16x32_bf16 v[8:11], v[190:193], v[214:217], v[8:11]
	v_mfma_f32_16x16x32_bf16 v[4:7], v[182:185], v[222:225], v[4:7]
	v_mfma_f32_16x16x32_bf16 v[0:3], v[190:193], v[222:225], v[0:3]
	v_mfma_f32_16x16x32_bf16 v[48:51], v[186:189], v[202:205], v[48:51]
	v_mfma_f32_16x16x32_bf16 v[40:43], v[194:197], v[202:205], v[40:43]
	v_mfma_f32_16x16x32_bf16 v[32:35], v[186:189], v[210:213], v[32:35]
	v_mfma_f32_16x16x32_bf16 v[24:27], v[194:197], v[210:213], v[24:27]
	v_mfma_f32_16x16x32_bf16 v[16:19], v[186:189], v[218:221], v[16:19]
	v_mfma_f32_16x16x32_bf16 v[8:11], v[194:197], v[218:221], v[8:11]
	v_mfma_f32_16x16x32_bf16 v[4:7], v[186:189], v[226:229], v[4:7]
	v_mfma_f32_16x16x32_bf16 v[0:3], v[194:197], v[226:229], v[0:3]
	s_barrier
	s_add_i32 s65, s65, 2
	s_add_u32 s48, s48, 0x100
	s_addc_u32 s49, s49, 0
	s_add_u32 s63, s63, 0x100
	s_addc_u32 s64, s64, 0
	s_cmpk_gt_u32 s65, 0x7d
	s_cbranch_scc0 .LBB0_1161
	s_and_b64 vcc, exec, s[16:17]
	s_cbranch_vccz .LBB0_1164
	s_barrier

; #define PG8_STAGE(bufoff, gbase, voff) do { _Pragma("unroll") for (int _i = 0; _i < 2; ++_i) \
;         __builtin_amdgcn_global_load_lds((const unsigned*)((const char*)(gbase) + (voff)[_i]), (PG8_LAS unsigned*)(lds + (bufoff) + ldsw + _i * 8192), 16, 0, 0); } while (0)
; #define PG8_LDA(dst, b, h) do { _Pragma("unroll") for (int m = 0; m < 4; ++m) _Pragma("unroll") for (int k = 0; k < 2; ++k) dst[m][k] = *(const PG8_LAS bf16x8*)(lds + PG8_SA(b, h) + aoff + m * 2048 + k * 1024); } while (0)
; #define PG8_LDB(dst, b, h) do { _Pragma("unroll") for (int n = 0; n < 2; ++n) _Pragma("unroll") for (int k = 0; k < 2; ++k) dst[n][k] = *(const PG8_LAS bf16x8*)(lds + PG8_SB(b, h) + boff + n * 2048 + k * 1024); } while (0)
; #define PG8_MMA(ai, bj, At, Bt) do { __builtin_amdgcn_s_setprio(1); _Pragma("unroll") for (int m = 0; m < 4; ++m) _Pragma("unroll") for (int n = 0; n < 2; ++n) _Pragma("unroll") for (int k = 0; k < 2; ++k) \
;         acc[ai][bj][m][n] = __builtin_amdgcn_mfma_f32_16x16x32_bf16(Bt[n][k], At[m][k], acc[ai][bj][m][n], 0, 0, 0); __builtin_amdgcn_s_setprio(0); } while (0)
; #define PG8_WAIT_V(n) asm volatile("s_waitcnt vmcnt(" #n ")" ::: "memory")
; #define PG8_WAIT_L(n) asm volatile("s_waitcnt lgkmcnt(" #n ")" ::: "memory")
; template <class Epi, class Sched, bool ALIGN_EPI = false, bool SP2 = false>
; __device__ __forceinline__ void gemm_phase(PG8_LAS unsigned char* lds, const Gemm g, const Sched& S, const Epi& E) {
;     ...
;             const bool last = (t == nt - 2);
;             const char* a1 = cA + (size_t)(t + 1) * kstep;
;             const char* a2 = last ? nA : cA + (size_t)(t + 2) * kstep; const char* b2 = last ? nB : cB + (size_t)(t + 2) * kstep;
;             const char* a3 = a2 + kstep; const char* b3 = b2 + kstep;
;             if (last && has_next) S.a_ready(nxt);
;             if constexpr (SP2) {
;             PG8_LDB(B0, 0, 0); PG8_LDB(B1, 0, 1); PG8_SCHED; PG8_LDA(At, 0, 0); PG8_STAGE(PG8_SA(1, 1), a1 + hstepA, voffA);
;             PG8_WAIT_V(8); PG8_WAIT_L(0); PG8_BAR; PG8_MMA(0, 0, At, B0); PG8_MMA(0, 1, At, B1); PG8_BAR; PG8_SCHED;
;             PG8_LDA(At, 0, 1); PG8_STAGE(PG8_SB(0, 0), b2, voffB); PG8_STAGE(PG8_SB(0, 1), b2 + hstepB, voffB); PG8_STAGE(PG8_SA(0, 0), a2, voffA);
;             PG8_WAIT_V(8); PG8_WAIT_L(0); PG8_BAR; PG8_MMA(1, 0, At, B0); PG8_MMA(1, 1, At, B1); PG8_BAR; PG8_SCHED;
.LBB0_1181:
	ds_read_b128 v[150:153], v146
	ds_read_b128 v[154:157], v146 offset:1024
	ds_read_b128 v[158:161], v146 offset:2048
	ds_read_b128 v[166:169], v146 offset:3072
	ds_read_b128 v[170:173], v147
	ds_read_b128 v[174:177], v147 offset:1024
	ds_read_b128 v[178:181], v147 offset:2048
	ds_read_b128 v[182:185], v147 offset:3072
	s_add_u32 s43, s46, 0xffe00080
	s_addc_u32 s48, s47, -1
	s_cmp_eq_u32 s41, 12
	s_cselect_b32 s51, s1, s48
	s_cselect_b32 s50, s0, s43
	s_cselect_b32 s49, s45, s39
	s_cselect_b32 s48, s44, s19
	s_mov_b32 m0, s55
	ds_read_b128 v[186:189], v148
	ds_read_b128 v[190:193], v148 offset:1024
	ds_read_b128 v[194:197], v148 offset:2048
	ds_read_b128 v[198:201], v148 offset:3072
	ds_read_b128 v[202:205], v148 offset:4096
	ds_read_b128 v[206:209], v148 offset:5120
	ds_read_b128 v[210:213], v148 offset:6144
	ds_read_b128 v[214:217], v148 offset:7168
	global_load_lds_dwordx4 v136, s[46:47]
	s_mov_b32 m0, s56
	s_nop 0
	global_load_lds_dwordx4 v138, s[46:47]
	s_waitcnt vmcnt(8)
	s_waitcnt lgkmcnt(0)
	s_barrier
	s_waitcnt lgkmcnt(0)
	v_mfma_f32_16x16x32_bf16 v[124:127], v[150:153], v[186:189], v[124:127]
	v_mfma_f32_16x16x32_bf16 v[120:123], v[158:161], v[186:189], v[120:123]
	v_mfma_f32_16x16x32_bf16 v[116:119], v[150:153], v[194:197], v[116:119]
	v_mfma_f32_16x16x32_bf16 v[112:115], v[158:161], v[194:197], v[112:115]
	v_mfma_f32_16x16x32_bf16 v[100:103], v[150:153], v[202:205], v[100:103]
	v_mfma_f32_16x16x32_bf16 v[96:99], v[158:161], v[202:205], v[96:99]
	v_mfma_f32_16x16x32_bf16 v[84:87], v[150:153], v[210:213], v[84:87]
	v_mfma_f32_16x16x32_bf16 v[80:83], v[158:161], v[210:213], v[80:83]
	v_mfma_f32_16x16x32_bf16 v[124:127], v[154:157], v[190:193], v[124:127]
	v_mfma_f32_16x16x32_bf16 v[120:123], v[166:169], v[190:193], v[120:123]
	v_mfma_f32_16x16x32_bf16 v[116:119], v[154:157], v[198:201], v[116:119]
	v_mfma_f32_16x16x32_bf16 v[112:115], v[166:169], v[198:201], v[112:115]
	v_mfma_f32_16x16x32_bf16 v[100:103], v[154:157], v[206:209], v[100:103]
	v_mfma_f32_16x16x32_bf16 v[96:99], v[166:169], v[206:209], v[96:99]
	v_mfma_f32_16x16x32_bf16 v[84:87], v[154:157], v[214:217], v[84:87]
	v_mfma_f32_16x16x32_bf16 v[80:83], v[166:169], v[214:217], v[80:83]
	v_mfma_f32_16x16x32_bf16 v[108:111], v[170:173], v[186:189], v[108:111]
	v_mfma_f32_16x16x32_bf16 v[104:107], v[178:181], v[186:189], v[104:107]
	v_mfma_f32_16x16x32_bf16 v[92:95], v[170:173], v[194:197], v[92:95]
	v_mfma_f32_16x16x32_bf16 v[88:91], v[178:181], v[194:197], v[88:91]
	v_mfma_f32_16x16x32_bf16 v[76:79], v[170:173], v[202:205], v[76:79]
	v_mfma_f32_16x16x32_bf16 v[72:75], v[178:181], v[202:205], v[72:75]
	v_mfma_f32_16x16x32_bf16 v[68:71], v[170:173], v[210:213], v[68:71]
	v_mfma_f32_16x16x32_bf16 v[64:67], v[178:181], v[210:213], v[64:67]
	v_mfma_f32_16x16x32_bf16 v[108:111], v[174:177], v[190:193], v[108:111]
	v_mfma_f32_16x16x32_bf16 v[104:107], v[182:185], v[190:193], v[104:107]
	v_mfma_f32_16x16x32_bf16 v[92:95], v[174:177], v[198:201], v[92:95]
	v_mfma_f32_16x16x32_bf16 v[88:91], v[182:185], v[198:201], v[88:91]
	v_mfma_f32_16x16x32_bf16 v[76:79], v[174:177], v[206:209], v[76:79]
	v_mfma_f32_16x16x32_bf16 v[72:75], v[182:185], v[206:209], v[72:75]
	v_mfma_f32_16x16x32_bf16 v[68:71], v[174:177], v[214:217], v[68:71]
	v_mfma_f32_16x16x32_bf16 v[64:67], v[182:185], v[214:217], v[64:67]
	s_barrier
	s_add_i32 s43, s53, s30
	v_lshl_add_u64 v[218:219], s[48:49], 0, v[130:131]
	s_mov_b32 m0, s43
	ds_read_b128 v[186:189], v148 offset:16384
	ds_read_b128 v[190:193], v148 offset:17408
	ds_read_b128 v[194:197], v148 offset:18432
	ds_read_b128 v[198:201], v148 offset:19456
	ds_read_b128 v[202:205], v148 offset:20480
	ds_read_b128 v[206:209], v148 offset:21504
	ds_read_b128 v[210:213], v148 offset:22528
	ds_read_b128 v[214:217], v148 offset:23552
	global_load_lds_dwordx4 v130, s[48:49]
	s_add_i32 m0, s43, 0x2000
	s_add_u32 s58, s48, 0x200000
	v_lshl_add_u64 v[220:221], s[48:49], 0, v[134:135]
	s_addc_u32 s59, s49, 0
	s_add_i32 s43, s54, s30
	global_load_lds_dwordx4 v134, s[48:49]
	s_mov_b32 m0, s43
	v_lshl_add_u64 v[224:225], s[50:51], 0, v[132:133]
	global_load_lds_dwordx4 v130, s[58:59]
	s_add_i32 m0, s43, 0x2000
	s_nop 0
	global_load_lds_dwordx4 v134, s[58:59]
	v_lshl_add_u64 v[222:223], s[50:51], 0, v[128:129]
	s_mov_b32 m0, s21
	s_nop 0
	global_load_lds_dwordx4 v128, s[50:51]
	s_mov_b32 m0, s23
	s_nop 0
	global_load_lds_dwordx4 v132, s[50:51]
	s_waitcnt vmcnt(8)
	s_waitcnt lgkmcnt(0)
	s_barrier
	s_waitcnt lgkmcnt(0)
	v_mfma_f32_16x16x32_bf16 v[60:63], v[150:153], v[186:189], v[60:63]
	v_mfma_f32_16x16x32_bf16 v[56:59], v[158:161], v[186:189], v[56:59]
	v_mfma_f32_16x16x32_bf16 v[52:55], v[150:153], v[194:197], v[52:55]
	v_mfma_f32_16x16x32_bf16 v[48:51], v[158:161], v[194:197], v[48:51]
	v_mfma_f32_16x16x32_bf16 v[36:39], v[150:153], v[202:205], v[36:39]
	v_mfma_f32_16x16x32_bf16 v[32:35], v[158:161], v[202:205], v[32:35]
	v_mfma_f32_16x16x32_bf16 v[20:23], v[150:153], v[210:213], v[20:23]
	v_mfma_f32_16x16x32_bf16 v[16:19], v[158:161], v[210:213], v[16:19]
	v_mfma_f32_16x16x32_bf16 v[60:63], v[154:157], v[190:193], v[60:63]
	v_mfma_f32_16x16x32_bf16 v[56:59], v[166:169], v[190:193], v[56:59]
	v_mfma_f32_16x16x32_bf16 v[52:55], v[154:157], v[198:201], v[52:55]
	v_mfma_f32_16x16x32_bf16 v[48:51], v[166:169], v[198:201], v[48:51]
	v_mfma_f32_16x16x32_bf16 v[36:39], v[154:157], v[206:209], v[36:39]
	v_mfma_f32_16x16x32_bf16 v[32:35], v[166:169], v[206:209], v[32:35]
	v_mfma_f32_16x16x32_bf16 v[20:23], v[154:157], v[214:217], v[20:23]
	v_mfma_f32_16x16x32_bf16 v[16:19], v[166:169], v[214:217], v[16:19]
	v_mfma_f32_16x16x32_bf16 v[44:47], v[170:173], v[186:189], v[44:47]
	v_mfma_f32_16x16x32_bf16 v[40:43], v[178:181], v[186:189], v[40:43]
	v_mfma_f32_16x16x32_bf16 v[28:31], v[170:173], v[194:197], v[28:31]
	v_mfma_f32_16x16x32_bf16 v[24:27], v[178:181], v[194:197], v[24:27]
	v_mfma_f32_16x16x32_bf16 v[12:15], v[170:173], v[202:205], v[12:15]
	v_mfma_f32_16x16x32_bf16 v[8:11], v[178:181], v[202:205], v[8:11]
	v_mfma_f32_16x16x32_bf16 v[4:7], v[170:173], v[210:213], v[4:7]
	v_mfma_f32_16x16x32_bf16 v[0:3], v[178:181], v[210:213], v[0:3]
	v_mfma_f32_16x16x32_bf16 v[44:47], v[174:177], v[190:193], v[44:47]
	v_mfma_f32_16x16x32_bf16 v[40:43], v[182:185], v[190:193], v[40:43]
	v_mfma_f32_16x16x32_bf16 v[28:31], v[174:177], v[198:201], v[28:31]
	v_mfma_f32_16x16x32_bf16 v[24:27], v[182:185], v[198:201], v[24:27]
	v_mfma_f32_16x16x32_bf16 v[12:15], v[174:177], v[206:209], v[12:15]
	v_mfma_f32_16x16x32_bf16 v[8:11], v[182:185], v[206:209], v[8:11]
	v_mfma_f32_16x16x32_bf16 v[4:7], v[174:177], v[214:217], v[4:7]
	v_mfma_f32_16x16x32_bf16 v[0:3], v[182:185], v[214:217], v[0:3]
	s_barrier
; #define PG8_STAGE(bufoff, gbase, voff) do { _Pragma("unroll") for (int _i = 0; _i < 2; ++_i) \
;         __builtin_amdgcn_global_load_lds((const unsigned*)((const char*)(gbase) + (voff)[_i]), (PG8_LAS unsigned*)(lds + (bufoff) + ldsw + _i * 8192), 16, 0, 0); } while (0)
; #define PG8_LDA(dst, b, h) do { _Pragma("unroll") for (int m = 0; m < 4; ++m) _Pragma("unroll") for (int k = 0; k < 2; ++k) dst[m][k] = *(const PG8_LAS bf16x8*)(lds + PG8_SA(b, h) + aoff + m * 2048 + k * 1024); } while (0)
; #define PG8_LDB(dst, b, h) do { _Pragma("unroll") for (int n = 0; n < 2; ++n) _Pragma("unroll") for (int k = 0; k < 2; ++k) dst[n][k] = *(const PG8_LAS bf16x8*)(lds + PG8_SB(b, h) + boff + n * 2048 + k * 1024); } while (0)
; #define PG8_MMA(ai, bj, At, Bt) do { __builtin_amdgcn_s_setprio(1); _Pragma("unroll") for (int m = 0; m < 4; ++m) _Pragma("unroll") for (int n = 0; n < 2; ++n) _Pragma("unroll") for (int k = 0; k < 2; ++k) \
;         acc[ai][bj][m][n] = __builtin_amdgcn_mfma_f32_16x16x32_bf16(Bt[n][k], At[m][k], acc[ai][bj][m][n], 0, 0, 0); __builtin_amdgcn_s_setprio(0); } while (0)
; #define PG8_WAIT_V(n) asm volatile("s_waitcnt vmcnt(" #n ")" ::: "memory")
; #define PG8_WAIT_L(n) asm volatile("s_waitcnt lgkmcnt(" #n ")" ::: "memory")
; #define PG8_BAR __builtin_amdgcn_s_barrier()
; #define PG8_SCHED __builtin_amdgcn_sched_barrier(0)
; template <class Epi, class Sched, bool ALIGN_EPI = false, bool SP2 = false>
; __device__ __forceinline__ void gemm_phase(PG8_LAS unsigned char* lds, const Gemm g, const Sched& S, const Epi& E) {
;     ...
;         for (int t = 0; t < nt; t += 2) {
;     ...
;             PG8_LDB(B0, 1, 0); PG8_LDB(B1, 1, 1); PG8_SCHED; PG8_LDA(At, 1, 0); PG8_STAGE(PG8_SA(0, 1), a2 + hstepA, voffA);
;             PG8_WAIT_V(8); PG8_WAIT_L(0); PG8_BAR; PG8_MMA(0, 0, At, B0); PG8_MMA(0, 1, At, B1); PG8_BAR; PG8_SCHED;
;             PG8_LDA(At, 1, 1); PG8_STAGE(PG8_SB(1, 0), b3, voffB); PG8_STAGE(PG8_SB(1, 1), b3 + hstepB, voffB); PG8_STAGE(PG8_SA(1, 0), a3, voffA);
;             PG8_WAIT_V(8); PG8_WAIT_L(0); PG8_BAR; PG8_MMA(1, 0, At, B0); PG8_MMA(1, 1, At, B1); PG8_BAR; PG8_SCHED;
	s_add_i32 s43, 0, 0x18000
	v_add_u32_e32 v163, s43, v145
	s_add_i32 s57, 0, 0x1c000
	ds_read_b128 v[150:153], v163
	ds_read_b128 v[154:157], v163 offset:1024
	ds_read_b128 v[158:161], v163 offset:2048
	ds_read_b128 v[166:169], v163 offset:3072
	v_add_u32_e32 v163, s57, v145
	ds_read_b128 v[170:173], v163
	ds_read_b128 v[174:177], v163 offset:1024
	ds_read_b128 v[178:181], v163 offset:2048
	ds_read_b128 v[182:185], v163 offset:3072
	s_add_u32 s50, s50, 0x200000
	s_addc_u32 s51, s51, 0
	s_mov_b32 m0, s31
	ds_read_b128 v[186:189], v148 offset:32768
	ds_read_b128 v[190:193], v148 offset:33792
	ds_read_b128 v[194:197], v148 offset:34816
	ds_read_b128 v[198:201], v148 offset:35840
	ds_read_b128 v[202:205], v148 offset:36864
	ds_read_b128 v[206:209], v148 offset:37888
	ds_read_b128 v[210:213], v148 offset:38912
	ds_read_b128 v[214:217], v148 offset:39936
	global_load_lds_dwordx4 v128, s[50:51]
	s_mov_b32 m0, s33
	s_nop 0
	global_load_lds_dwordx4 v132, s[50:51]
	s_waitcnt vmcnt(8)
	s_waitcnt lgkmcnt(0)
	s_barrier
	s_waitcnt lgkmcnt(0)
	v_mfma_f32_16x16x32_bf16 v[124:127], v[150:153], v[186:189], v[124:127]
	v_mfma_f32_16x16x32_bf16 v[120:123], v[158:161], v[186:189], v[120:123]
	v_mfma_f32_16x16x32_bf16 v[116:119], v[150:153], v[194:197], v[116:119]
	v_mfma_f32_16x16x32_bf16 v[112:115], v[158:161], v[194:197], v[112:115]
	v_mfma_f32_16x16x32_bf16 v[100:103], v[150:153], v[202:205], v[100:103]
	v_mfma_f32_16x16x32_bf16 v[96:99], v[158:161], v[202:205], v[96:99]
	v_mfma_f32_16x16x32_bf16 v[84:87], v[150:153], v[210:213], v[84:87]
	v_mfma_f32_16x16x32_bf16 v[80:83], v[158:161], v[210:213], v[80:83]
	v_mfma_f32_16x16x32_bf16 v[124:127], v[154:157], v[190:193], v[124:127]
	v_mfma_f32_16x16x32_bf16 v[120:123], v[166:169], v[190:193], v[120:123]
	v_mfma_f32_16x16x32_bf16 v[116:119], v[154:157], v[198:201], v[116:119]
	v_mfma_f32_16x16x32_bf16 v[112:115], v[166:169], v[198:201], v[112:115]
	v_mfma_f32_16x16x32_bf16 v[100:103], v[154:157], v[206:209], v[100:103]
	v_mfma_f32_16x16x32_bf16 v[96:99], v[166:169], v[206:209], v[96:99]
	v_mfma_f32_16x16x32_bf16 v[84:87], v[154:157], v[214:217], v[84:87]
	v_mfma_f32_16x16x32_bf16 v[80:83], v[166:169], v[214:217], v[80:83]
	v_mfma_f32_16x16x32_bf16 v[108:111], v[170:173], v[186:189], v[108:111]
	v_mfma_f32_16x16x32_bf16 v[104:107], v[178:181], v[186:189], v[104:107]
	v_mfma_f32_16x16x32_bf16 v[92:95], v[170:173], v[194:197], v[92:95]
	v_mfma_f32_16x16x32_bf16 v[88:91], v[178:181], v[194:197], v[88:91]
	v_mfma_f32_16x16x32_bf16 v[76:79], v[170:173], v[202:205], v[76:79]
	v_mfma_f32_16x16x32_bf16 v[72:75], v[178:181], v[202:205], v[72:75]
	v_mfma_f32_16x16x32_bf16 v[68:71], v[170:173], v[210:213], v[68:71]
	v_mfma_f32_16x16x32_bf16 v[64:67], v[178:181], v[210:213], v[64:67]
	v_mfma_f32_16x16x32_bf16 v[108:111], v[174:177], v[190:193], v[108:111]
	v_mfma_f32_16x16x32_bf16 v[104:107], v[182:185], v[190:193], v[104:107]
	v_mfma_f32_16x16x32_bf16 v[92:95], v[174:177], v[198:201], v[92:95]
	v_mfma_f32_16x16x32_bf16 v[88:91], v[182:185], v[198:201], v[88:91]
	v_mfma_f32_16x16x32_bf16 v[76:79], v[174:177], v[206:209], v[76:79]
	v_mfma_f32_16x16x32_bf16 v[72:75], v[182:185], v[206:209], v[72:75]
	v_mfma_f32_16x16x32_bf16 v[68:71], v[174:177], v[214:217], v[68:71]
	v_mfma_f32_16x16x32_bf16 v[64:67], v[182:185], v[214:217], v[64:67]
	s_barrier
	s_add_i32 s43, s43, s30
	v_lshl_add_u64 v[218:219], v[218:219], 0, s[16:17]
	s_mov_b32 m0, s43
	ds_read_b128 v[186:189], v148 offset:49152
	ds_read_b128 v[190:193], v148 offset:50176
	ds_read_b128 v[194:197], v148 offset:51200
	ds_read_b128 v[198:201], v148 offset:52224
	ds_read_b128 v[202:205], v148 offset:53248
	ds_read_b128 v[206:209], v148 offset:54272
	ds_read_b128 v[210:213], v148 offset:55296
	ds_read_b128 v[214:217], v148 offset:56320
	global_load_lds_dwordx4 v[218:219], off
	s_add_i32 m0, s43, 0x2000
	s_add_u32 s48, s48, 0x200080
	v_lshl_add_u64 v[218:219], v[220:221], 0, s[16:17]
	s_addc_u32 s49, s49, 0
	s_add_i32 s43, s57, s30
	global_load_lds_dwordx4 v[218:219], off
	s_mov_b32 m0, s43
	s_nop 0
	global_load_lds_dwordx4 v130, s[48:49]
	s_add_i32 m0, s43, 0x2000
	s_nop 0
	global_load_lds_dwordx4 v134, s[48:49]
	v_lshl_add_u64 v[218:219], v[222:223], 0, s[16:17]
	s_mov_b32 m0, s35
	s_nop 0
	global_load_lds_dwordx4 v[218:219], off
	v_lshl_add_u64 v[218:219], v[224:225], 0, s[16:17]
	s_mov_b32 m0, s52
	s_nop 0
	global_load_lds_dwordx4 v[218:219], off
	s_waitcnt vmcnt(8)
	s_waitcnt lgkmcnt(0)
	s_barrier
	s_waitcnt lgkmcnt(0)
	v_mfma_f32_16x16x32_bf16 v[60:63], v[150:153], v[186:189], v[60:63]
	v_mfma_f32_16x16x32_bf16 v[56:59], v[158:161], v[186:189], v[56:59]
	v_mfma_f32_16x16x32_bf16 v[52:55], v[150:153], v[194:197], v[52:55]
	v_mfma_f32_16x16x32_bf16 v[48:51], v[158:161], v[194:197], v[48:51]
	v_mfma_f32_16x16x32_bf16 v[36:39], v[150:153], v[202:205], v[36:39]
	v_mfma_f32_16x16x32_bf16 v[32:35], v[158:161], v[202:205], v[32:35]
	v_mfma_f32_16x16x32_bf16 v[20:23], v[150:153], v[210:213], v[20:23]
	v_mfma_f32_16x16x32_bf16 v[16:19], v[158:161], v[210:213], v[16:19]
	v_mfma_f32_16x16x32_bf16 v[60:63], v[154:157], v[190:193], v[60:63]
	v_mfma_f32_16x16x32_bf16 v[56:59], v[166:169], v[190:193], v[56:59]
	v_mfma_f32_16x16x32_bf16 v[52:55], v[154:157], v[198:201], v[52:55]
	v_mfma_f32_16x16x32_bf16 v[48:51], v[166:169], v[198:201], v[48:51]
	v_mfma_f32_16x16x32_bf16 v[36:39], v[154:157], v[206:209], v[36:39]
	v_mfma_f32_16x16x32_bf16 v[32:35], v[166:169], v[206:209], v[32:35]
	v_mfma_f32_16x16x32_bf16 v[20:23], v[154:157], v[214:217], v[20:23]
	v_mfma_f32_16x16x32_bf16 v[16:19], v[166:169], v[214:217], v[16:19]
	v_mfma_f32_16x16x32_bf16 v[44:47], v[170:173], v[186:189], v[44:47]
	v_mfma_f32_16x16x32_bf16 v[40:43], v[178:181], v[186:189], v[40:43]
	v_mfma_f32_16x16x32_bf16 v[28:31], v[170:173], v[194:197], v[28:31]
	v_mfma_f32_16x16x32_bf16 v[24:27], v[178:181], v[194:197], v[24:27]
	v_mfma_f32_16x16x32_bf16 v[12:15], v[170:173], v[202:205], v[12:15]
	v_mfma_f32_16x16x32_bf16 v[8:11], v[178:181], v[202:205], v[8:11]
	v_mfma_f32_16x16x32_bf16 v[4:7], v[170:173], v[210:213], v[4:7]
	v_mfma_f32_16x16x32_bf16 v[0:3], v[178:181], v[210:213], v[0:3]
	v_mfma_f32_16x16x32_bf16 v[44:47], v[174:177], v[190:193], v[44:47]
	v_mfma_f32_16x16x32_bf16 v[40:43], v[182:185], v[190:193], v[40:43]
	v_mfma_f32_16x16x32_bf16 v[28:31], v[174:177], v[198:201], v[28:31]
	v_mfma_f32_16x16x32_bf16 v[24:27], v[182:185], v[198:201], v[24:27]
	v_mfma_f32_16x16x32_bf16 v[12:15], v[174:177], v[206:209], v[12:15]
	v_mfma_f32_16x16x32_bf16 v[8:11], v[182:185], v[206:209], v[8:11]
	v_mfma_f32_16x16x32_bf16 v[4:7], v[174:177], v[214:217], v[4:7]
	v_mfma_f32_16x16x32_bf16 v[0:3], v[182:185], v[214:217], v[0:3]
	s_barrier
	s_add_i32 s41, s41, 2
	s_add_u32 s46, s46, 0x100
	s_addc_u32 s47, s47, 0
	s_add_u32 s19, s19, 0x100
	s_addc_u32 s39, s39, 0
	s_cmp_gt_u32 s41, 13
	s_cbranch_scc0 .LBB0_1181
	s_and_b64 vcc, exec, s[36:37]
	s_cbranch_vccz .LBB0_1184
	s_barrier

; #define PG8_STAGE(bufoff, gbase, voff) do { _Pragma("unroll") for (int _i = 0; _i < 2; ++_i) \
;         __builtin_amdgcn_global_load_lds((const unsigned*)((const char*)(gbase) + (voff)[_i]), (PG8_LAS unsigned*)(lds + (bufoff) + ldsw + _i * 8192), 16, 0, 0); } while (0)
; #define PG8_LDA(dst, b, h) do { _Pragma("unroll") for (int m = 0; m < 4; ++m) _Pragma("unroll") for (int k = 0; k < 2; ++k) dst[m][k] = *(const PG8_LAS bf16x8*)(lds + PG8_SA(b, h) + aoff + m * 2048 + k * 1024); } while (0)
; #define PG8_LDB(dst, b, h) do { _Pragma("unroll") for (int n = 0; n < 2; ++n) _Pragma("unroll") for (int k = 0; k < 2; ++k) dst[n][k] = *(const PG8_LAS bf16x8*)(lds + PG8_SB(b, h) + boff + n * 2048 + k * 1024); } while (0)
; #define PG8_MMA(ai, bj, At, Bt) do { __builtin_amdgcn_s_setprio(1); _Pragma("unroll") for (int m = 0; m < 4; ++m) _Pragma("unroll") for (int n = 0; n < 2; ++n) _Pragma("unroll") for (int k = 0; k < 2; ++k) \
;         acc[ai][bj][m][n] = __builtin_amdgcn_mfma_f32_16x16x32_bf16(Bt[n][k], At[m][k], acc[ai][bj][m][n], 0, 0, 0); __builtin_amdgcn_s_setprio(0); } while (0)
; #define PG8_WAIT_V(n) asm volatile("s_waitcnt vmcnt(" #n ")" ::: "memory")
; #define PG8_WAIT_L(n) asm volatile("s_waitcnt lgkmcnt(" #n ")" ::: "memory")
; #define PG8_BAR __builtin_amdgcn_s_barrier()
; #define PG8_SCHED __builtin_amdgcn_sched_barrier(0)
; template <class Epi, class Sched, bool ALIGN_EPI = false, bool SP2 = false>
; __device__ __forceinline__ void gemm_phase(PG8_LAS unsigned char* lds, const Gemm g, const Sched& S, const Epi& E) {
;     ...
;             const bool last = (t == nt - 2);
;             const char* a1 = cA + (size_t)(t + 1) * kstep;
;             const char* a2 = last ? nA : cA + (size_t)(t + 2) * kstep; const char* b2 = last ? nB : cB + (size_t)(t + 2) * kstep;
;             const char* a3 = a2 + kstep; const char* b3 = b2 + kstep;
;             if (last && has_next) S.a_ready(nxt);
;             if constexpr (SP2) {
;             PG8_LDB(B0, 0, 0); PG8_LDB(B1, 0, 1); PG8_SCHED; PG8_LDA(At, 0, 0); PG8_STAGE(PG8_SA(1, 1), a1 + hstepA, voffA);
;             PG8_WAIT_V(8); PG8_WAIT_L(0); PG8_BAR; PG8_MMA(0, 0, At, B0); PG8_MMA(0, 1, At, B1); PG8_BAR; PG8_SCHED;
;             PG8_LDA(At, 0, 1); PG8_STAGE(PG8_SB(0, 0), b2, voffB); PG8_STAGE(PG8_SB(0, 1), b2 + hstepB, voffB); PG8_STAGE(PG8_SA(0, 0), a2, voffA);
.LBB0_1262:
	s_add_u32 s51, s44, s50
	s_addc_u32 s56, s45, 0
	s_add_u32 s54, s51, 0x100
	s_addc_u32 s55, s56, 0
	s_and_b64 s[52:53], s[48:49], exec
	s_cselect_b32 s53, s23, s55
	s_cselect_b32 s52, s69, s54
	s_add_u32 s50, s42, s50
	s_addc_u32 s54, s43, 0
	s_add_u32 s50, s50, 0x100
	s_addc_u32 s54, s54, 0
	s_and_b64 s[48:49], s[48:49], exec
	s_cselect_b32 s55, s21, s54
	s_cselect_b32 s54, s70, s50
	s_add_u32 s58, s51, 0x10080
	ds_read_b128 v[148:151], v145
	ds_read_b128 v[152:155], v145 offset:1024
	ds_read_b128 v[156:159], v145 offset:2048
	ds_read_b128 v[166:169], v145 offset:3072
	ds_read_b128 v[170:173], v146
	ds_read_b128 v[174:177], v146 offset:1024
	ds_read_b128 v[178:181], v146 offset:2048
	ds_read_b128 v[182:185], v146 offset:3072
	s_addc_u32 s59, s56, 0
	s_add_i32 s80, s63, s28
	s_add_i32 m0, s33, 0xc000
	s_add_i32 s81, s33, 0xe000
	s_add_i32 s77, s80, 0x2000
	s_add_u32 s56, s54, 0x10000
	s_addc_u32 s57, s55, 0
	s_add_i32 s79, s64, s28
	s_add_i32 s78, s79, 0x2000
	s_add_i32 s76, 0, 0x18000
	s_add_i32 s75, 0, 0x1c000
	s_add_u32 s50, s52, 0x10000
	s_addc_u32 s51, s53, 0
	s_add_i32 s74, s76, s28
	s_add_i32 s72, s74, 0x2000
	s_add_u32 s48, s54, 0x10080
	s_addc_u32 s49, s55, 0
	s_add_i32 s73, s75, s28
	s_add_i32 s71, s73, 0x2000
	ds_read_b128 v[186:189], v147
	ds_read_b128 v[190:193], v147 offset:1024
	ds_read_b128 v[194:197], v147 offset:2048
	ds_read_b128 v[198:201], v147 offset:3072
	ds_read_b128 v[202:205], v147 offset:4096
	ds_read_b128 v[206:209], v147 offset:5120
	ds_read_b128 v[210:213], v147 offset:6144
	ds_read_b128 v[214:217], v147 offset:7168
	global_load_lds_dwordx4 v134, s[58:59]
	s_mov_b32 m0, s81
	s_nop 0
	global_load_lds_dwordx4 v130, s[58:59]
	s_waitcnt vmcnt(8)
	s_waitcnt lgkmcnt(0)
	s_barrier
	s_waitcnt lgkmcnt(0)
	v_mfma_f32_16x16x32_bf16 v[124:127], v[148:151], v[186:189], v[124:127]
	v_mfma_f32_16x16x32_bf16 v[120:123], v[156:159], v[186:189], v[120:123]
	v_mfma_f32_16x16x32_bf16 v[116:119], v[148:151], v[194:197], v[116:119]
	v_mfma_f32_16x16x32_bf16 v[108:111], v[156:159], v[194:197], v[108:111]
	v_mfma_f32_16x16x32_bf16 v[100:103], v[148:151], v[202:205], v[100:103]
	v_mfma_f32_16x16x32_bf16 v[92:95], v[156:159], v[202:205], v[92:95]
	v_mfma_f32_16x16x32_bf16 v[84:87], v[148:151], v[210:213], v[84:87]
	v_mfma_f32_16x16x32_bf16 v[76:79], v[156:159], v[210:213], v[76:79]
	v_mfma_f32_16x16x32_bf16 v[124:127], v[152:155], v[190:193], v[124:127]
	v_mfma_f32_16x16x32_bf16 v[120:123], v[166:169], v[190:193], v[120:123]
	v_mfma_f32_16x16x32_bf16 v[116:119], v[152:155], v[198:201], v[116:119]
	v_mfma_f32_16x16x32_bf16 v[108:111], v[166:169], v[198:201], v[108:111]
	v_mfma_f32_16x16x32_bf16 v[100:103], v[152:155], v[206:209], v[100:103]
	v_mfma_f32_16x16x32_bf16 v[92:95], v[166:169], v[206:209], v[92:95]
	v_mfma_f32_16x16x32_bf16 v[84:87], v[152:155], v[214:217], v[84:87]
	v_mfma_f32_16x16x32_bf16 v[76:79], v[166:169], v[214:217], v[76:79]
	v_mfma_f32_16x16x32_bf16 v[112:115], v[170:173], v[186:189], v[112:115]
	v_mfma_f32_16x16x32_bf16 v[104:107], v[178:181], v[186:189], v[104:107]
	v_mfma_f32_16x16x32_bf16 v[96:99], v[170:173], v[194:197], v[96:99]
	v_mfma_f32_16x16x32_bf16 v[88:91], v[178:181], v[194:197], v[88:91]
	v_mfma_f32_16x16x32_bf16 v[80:83], v[170:173], v[202:205], v[80:83]
	v_mfma_f32_16x16x32_bf16 v[72:75], v[178:181], v[202:205], v[72:75]
	v_mfma_f32_16x16x32_bf16 v[68:71], v[170:173], v[210:213], v[68:71]
	v_mfma_f32_16x16x32_bf16 v[64:67], v[178:181], v[210:213], v[64:67]
	v_mfma_f32_16x16x32_bf16 v[112:115], v[174:177], v[190:193], v[112:115]
	v_mfma_f32_16x16x32_bf16 v[104:107], v[182:185], v[190:193], v[104:107]
	v_mfma_f32_16x16x32_bf16 v[96:99], v[174:177], v[198:201], v[96:99]
	v_mfma_f32_16x16x32_bf16 v[88:91], v[182:185], v[198:201], v[88:91]
	v_mfma_f32_16x16x32_bf16 v[80:83], v[174:177], v[206:209], v[80:83]
	v_mfma_f32_16x16x32_bf16 v[72:75], v[182:185], v[206:209], v[72:75]
	v_mfma_f32_16x16x32_bf16 v[68:71], v[174:177], v[214:217], v[68:71]
	v_mfma_f32_16x16x32_bf16 v[64:67], v[182:185], v[214:217], v[64:67]
	s_barrier
	s_mov_b32 m0, s80
	v_lshl_add_u64 v[140:141], s[54:55], 0, v[132:133]
	ds_read_b128 v[186:189], v147 offset:16384
	ds_read_b128 v[190:193], v147 offset:17408
	ds_read_b128 v[194:197], v147 offset:18432
	ds_read_b128 v[198:201], v147 offset:19456
	ds_read_b128 v[202:205], v147 offset:20480
	ds_read_b128 v[206:209], v147 offset:21504
	ds_read_b128 v[210:213], v147 offset:22528
	ds_read_b128 v[214:217], v147 offset:23552
	global_load_lds_dwordx4 v132, s[54:55]
	v_lshl_add_u64 v[160:161], s[54:55], 0, v[128:129]
	s_mov_b32 m0, s77
	s_nop 0
	global_load_lds_dwordx4 v128, s[54:55]
	s_mov_b32 m0, s79
	v_lshl_add_u64 v[220:221], s[52:53], 0, v[130:131]
	global_load_lds_dwordx4 v132, s[56:57]
	s_mov_b32 m0, s78
	s_nop 0
	global_load_lds_dwordx4 v128, s[56:57]
	v_lshl_add_u64 v[218:219], s[52:53], 0, v[134:135]
	s_mov_b32 m0, s33
	s_nop 0
	global_load_lds_dwordx4 v134, s[52:53]
	s_mov_b32 m0, s34
	s_nop 0
	global_load_lds_dwordx4 v130, s[52:53]
	s_waitcnt vmcnt(8)
	s_waitcnt lgkmcnt(0)
	s_barrier
; #define PG8_STAGE(bufoff, gbase, voff) do { _Pragma("unroll") for (int _i = 0; _i < 2; ++_i) \
;         __builtin_amdgcn_global_load_lds((const unsigned*)((const char*)(gbase) + (voff)[_i]), (PG8_LAS unsigned*)(lds + (bufoff) + ldsw + _i * 8192), 16, 0, 0); } while (0)
; #define PG8_LDA(dst, b, h) do { _Pragma("unroll") for (int m = 0; m < 4; ++m) _Pragma("unroll") for (int k = 0; k < 2; ++k) dst[m][k] = *(const PG8_LAS bf16x8*)(lds + PG8_SA(b, h) + aoff + m * 2048 + k * 1024); } while (0)
; #define PG8_LDB(dst, b, h) do { _Pragma("unroll") for (int n = 0; n < 2; ++n) _Pragma("unroll") for (int k = 0; k < 2; ++k) dst[n][k] = *(const PG8_LAS bf16x8*)(lds + PG8_SB(b, h) + boff + n * 2048 + k * 1024); } while (0)
; #define PG8_MMA(ai, bj, At, Bt) do { __builtin_amdgcn_s_setprio(1); _Pragma("unroll") for (int m = 0; m < 4; ++m) _Pragma("unroll") for (int n = 0; n < 2; ++n) _Pragma("unroll") for (int k = 0; k < 2; ++k) \
;         acc[ai][bj][m][n] = __builtin_amdgcn_mfma_f32_16x16x32_bf16(Bt[n][k], At[m][k], acc[ai][bj][m][n], 0, 0, 0); __builtin_amdgcn_s_setprio(0); } while (0)
; #define PG8_WAIT_V(n) asm volatile("s_waitcnt vmcnt(" #n ")" ::: "memory")
; #define PG8_WAIT_L(n) asm volatile("s_waitcnt lgkmcnt(" #n ")" ::: "memory")
; #define PG8_BAR __builtin_amdgcn_s_barrier()
; #define PG8_SCHED __builtin_amdgcn_sched_barrier(0)
; template <class Epi, class Sched, bool ALIGN_EPI = false, bool SP2 = false>
; __device__ __forceinline__ void gemm_phase(PG8_LAS unsigned char* lds, const Gemm g, const Sched& S, const Epi& E) {
;     ...
;             PG8_WAIT_V(8); PG8_WAIT_L(0); PG8_BAR; PG8_MMA(1, 0, At, B0); PG8_MMA(1, 1, At, B1); PG8_BAR; PG8_SCHED;
;             PG8_LDB(B0, 1, 0); PG8_LDB(B1, 1, 1); PG8_SCHED; PG8_LDA(At, 1, 0); PG8_STAGE(PG8_SA(0, 1), a2 + hstepA, voffA);
;             PG8_WAIT_V(8); PG8_WAIT_L(0); PG8_BAR; PG8_MMA(0, 0, At, B0); PG8_MMA(0, 1, At, B1); PG8_BAR; PG8_SCHED;
	s_waitcnt lgkmcnt(0)
	v_mfma_f32_16x16x32_bf16 v[60:63], v[148:151], v[186:189], v[60:63]
	v_mfma_f32_16x16x32_bf16 v[56:59], v[156:159], v[186:189], v[56:59]
	v_mfma_f32_16x16x32_bf16 v[52:55], v[148:151], v[194:197], v[52:55]
	v_mfma_f32_16x16x32_bf16 v[44:47], v[156:159], v[194:197], v[44:47]
	v_mfma_f32_16x16x32_bf16 v[36:39], v[148:151], v[202:205], v[36:39]
	v_mfma_f32_16x16x32_bf16 v[28:31], v[156:159], v[202:205], v[28:31]
	v_mfma_f32_16x16x32_bf16 v[20:23], v[148:151], v[210:213], v[20:23]
	v_mfma_f32_16x16x32_bf16 v[12:15], v[156:159], v[210:213], v[12:15]
	v_mfma_f32_16x16x32_bf16 v[60:63], v[152:155], v[190:193], v[60:63]
	v_mfma_f32_16x16x32_bf16 v[56:59], v[166:169], v[190:193], v[56:59]
	v_mfma_f32_16x16x32_bf16 v[52:55], v[152:155], v[198:201], v[52:55]
	v_mfma_f32_16x16x32_bf16 v[44:47], v[166:169], v[198:201], v[44:47]
	v_mfma_f32_16x16x32_bf16 v[36:39], v[152:155], v[206:209], v[36:39]
	v_mfma_f32_16x16x32_bf16 v[28:31], v[166:169], v[206:209], v[28:31]
	v_mfma_f32_16x16x32_bf16 v[20:23], v[152:155], v[214:217], v[20:23]
	v_mfma_f32_16x16x32_bf16 v[12:15], v[166:169], v[214:217], v[12:15]
	v_mfma_f32_16x16x32_bf16 v[48:51], v[170:173], v[186:189], v[48:51]
	v_mfma_f32_16x16x32_bf16 v[40:43], v[178:181], v[186:189], v[40:43]
	v_mfma_f32_16x16x32_bf16 v[32:35], v[170:173], v[194:197], v[32:35]
	v_mfma_f32_16x16x32_bf16 v[24:27], v[178:181], v[194:197], v[24:27]
	v_mfma_f32_16x16x32_bf16 v[16:19], v[170:173], v[202:205], v[16:19]
	v_mfma_f32_16x16x32_bf16 v[8:11], v[178:181], v[202:205], v[8:11]
	v_mfma_f32_16x16x32_bf16 v[4:7], v[170:173], v[210:213], v[4:7]
	v_mfma_f32_16x16x32_bf16 v[0:3], v[178:181], v[210:213], v[0:3]
	v_mfma_f32_16x16x32_bf16 v[48:51], v[174:177], v[190:193], v[48:51]
	v_mfma_f32_16x16x32_bf16 v[40:43], v[182:185], v[190:193], v[40:43]
	v_mfma_f32_16x16x32_bf16 v[32:35], v[174:177], v[198:201], v[32:35]
	v_mfma_f32_16x16x32_bf16 v[24:27], v[182:185], v[198:201], v[24:27]
	v_mfma_f32_16x16x32_bf16 v[16:19], v[174:177], v[206:209], v[16:19]
	v_mfma_f32_16x16x32_bf16 v[8:11], v[182:185], v[206:209], v[8:11]
	v_mfma_f32_16x16x32_bf16 v[4:7], v[174:177], v[214:217], v[4:7]
	v_mfma_f32_16x16x32_bf16 v[0:3], v[182:185], v[214:217], v[0:3]
	s_barrier
	v_add_u32_e32 v163, s76, v143
	ds_read_b128 v[148:151], v163
	ds_read_b128 v[152:155], v163 offset:1024
	ds_read_b128 v[156:159], v163 offset:2048
	ds_read_b128 v[166:169], v163 offset:3072
	v_add_u32_e32 v163, s75, v143
	ds_read_b128 v[170:173], v163
	ds_read_b128 v[174:177], v163 offset:1024
	ds_read_b128 v[178:181], v163 offset:2048
	ds_read_b128 v[182:185], v163 offset:3072
	s_mov_b32 m0, s35
	ds_read_b128 v[186:189], v147 offset:32768
	ds_read_b128 v[190:193], v147 offset:33792
	ds_read_b128 v[194:197], v147 offset:34816
	ds_read_b128 v[198:201], v147 offset:35840
	ds_read_b128 v[202:205], v147 offset:36864
	ds_read_b128 v[206:209], v147 offset:37888
	ds_read_b128 v[210:213], v147 offset:38912
	ds_read_b128 v[214:217], v147 offset:39936
	global_load_lds_dwordx4 v134, s[50:51]
	s_mov_b32 m0, s41
	s_nop 0
	global_load_lds_dwordx4 v130, s[50:51]
	s_waitcnt vmcnt(8)
	s_waitcnt lgkmcnt(0)
	s_barrier
	s_waitcnt lgkmcnt(0)
	v_mfma_f32_16x16x32_bf16 v[124:127], v[148:151], v[186:189], v[124:127]
	v_mfma_f32_16x16x32_bf16 v[120:123], v[156:159], v[186:189], v[120:123]
	v_mfma_f32_16x16x32_bf16 v[116:119], v[148:151], v[194:197], v[116:119]
	v_mfma_f32_16x16x32_bf16 v[108:111], v[156:159], v[194:197], v[108:111]
	v_mfma_f32_16x16x32_bf16 v[100:103], v[148:151], v[202:205], v[100:103]
	v_mfma_f32_16x16x32_bf16 v[92:95], v[156:159], v[202:205], v[92:95]
	v_mfma_f32_16x16x32_bf16 v[84:87], v[148:151], v[210:213], v[84:87]
	v_mfma_f32_16x16x32_bf16 v[76:79], v[156:159], v[210:213], v[76:79]
	v_mfma_f32_16x16x32_bf16 v[124:127], v[152:155], v[190:193], v[124:127]
	v_mfma_f32_16x16x32_bf16 v[120:123], v[166:169], v[190:193], v[120:123]
	v_mfma_f32_16x16x32_bf16 v[116:119], v[152:155], v[198:201], v[116:119]
	v_mfma_f32_16x16x32_bf16 v[108:111], v[166:169], v[198:201], v[108:111]
	v_mfma_f32_16x16x32_bf16 v[100:103], v[152:155], v[206:209], v[100:103]
	v_mfma_f32_16x16x32_bf16 v[92:95], v[166:169], v[206:209], v[92:95]
	v_mfma_f32_16x16x32_bf16 v[84:87], v[152:155], v[214:217], v[84:87]
	v_mfma_f32_16x16x32_bf16 v[76:79], v[166:169], v[214:217], v[76:79]
	v_mfma_f32_16x16x32_bf16 v[112:115], v[170:173], v[186:189], v[112:115]
	v_mfma_f32_16x16x32_bf16 v[104:107], v[178:181], v[186:189], v[104:107]
	v_mfma_f32_16x16x32_bf16 v[96:99], v[170:173], v[194:197], v[96:99]
	v_mfma_f32_16x16x32_bf16 v[88:91], v[178:181], v[194:197], v[88:91]
	v_mfma_f32_16x16x32_bf16 v[80:83], v[170:173], v[202:205], v[80:83]
	v_mfma_f32_16x16x32_bf16 v[72:75], v[178:181], v[202:205], v[72:75]
	v_mfma_f32_16x16x32_bf16 v[68:71], v[170:173], v[210:213], v[68:71]
	v_mfma_f32_16x16x32_bf16 v[64:67], v[178:181], v[210:213], v[64:67]
	v_mfma_f32_16x16x32_bf16 v[112:115], v[174:177], v[190:193], v[112:115]
	v_mfma_f32_16x16x32_bf16 v[104:107], v[182:185], v[190:193], v[104:107]
	v_mfma_f32_16x16x32_bf16 v[96:99], v[174:177], v[198:201], v[96:99]
	v_mfma_f32_16x16x32_bf16 v[88:91], v[182:185], v[198:201], v[88:91]
	v_mfma_f32_16x16x32_bf16 v[80:83], v[174:177], v[206:209], v[80:83]
	v_mfma_f32_16x16x32_bf16 v[72:75], v[182:185], v[206:209], v[72:75]
	v_mfma_f32_16x16x32_bf16 v[68:71], v[174:177], v[214:217], v[68:71]
	v_mfma_f32_16x16x32_bf16 v[64:67], v[182:185], v[214:217], v[64:67]
	s_barrier
; #define PG8_STAGE(bufoff, gbase, voff) do { _Pragma("unroll") for (int _i = 0; _i < 2; ++_i) \
;         __builtin_amdgcn_global_load_lds((const unsigned*)((const char*)(gbase) + (voff)[_i]), (PG8_LAS unsigned*)(lds + (bufoff) + ldsw + _i * 8192), 16, 0, 0); } while (0)
; #define PG8_LDA(dst, b, h) do { _Pragma("unroll") for (int m = 0; m < 4; ++m) _Pragma("unroll") for (int k = 0; k < 2; ++k) dst[m][k] = *(const PG8_LAS bf16x8*)(lds + PG8_SA(b, h) + aoff + m * 2048 + k * 1024); } while (0)
; #define PG8_MMA(ai, bj, At, Bt) do { __builtin_amdgcn_s_setprio(1); _Pragma("unroll") for (int m = 0; m < 4; ++m) _Pragma("unroll") for (int n = 0; n < 2; ++n) _Pragma("unroll") for (int k = 0; k < 2; ++k) \
;         acc[ai][bj][m][n] = __builtin_amdgcn_mfma_f32_16x16x32_bf16(Bt[n][k], At[m][k], acc[ai][bj][m][n], 0, 0, 0); __builtin_amdgcn_s_setprio(0); } while (0)
; #define PG8_WAIT_V(n) asm volatile("s_waitcnt vmcnt(" #n ")" ::: "memory")
; #define PG8_WAIT_L(n) asm volatile("s_waitcnt lgkmcnt(" #n ")" ::: "memory")
; #define PG8_BAR __builtin_amdgcn_s_barrier()
; #define PG8_SCHED __builtin_amdgcn_sched_barrier(0)
; template <class Epi, class Sched, bool ALIGN_EPI = false, bool SP2 = false>
; __device__ __forceinline__ void gemm_phase(PG8_LAS unsigned char* lds, const Gemm g, const Sched& S, const Epi& E) {
;     ...
;             PG8_LDA(At, 1, 1); PG8_STAGE(PG8_SB(1, 0), b3, voffB); PG8_STAGE(PG8_SB(1, 1), b3 + hstepB, voffB); PG8_STAGE(PG8_SA(1, 0), a3, voffA);
;             PG8_WAIT_V(8); PG8_WAIT_L(0); PG8_BAR; PG8_MMA(1, 0, At, B0); PG8_MMA(1, 1, At, B1); PG8_BAR; PG8_SCHED;
	s_mov_b32 m0, s74
	v_lshl_add_u64 v[140:141], v[140:141], 0, s[8:9]
	ds_read_b128 v[186:189], v147 offset:49152
	ds_read_b128 v[190:193], v147 offset:50176
	ds_read_b128 v[194:197], v147 offset:51200
	ds_read_b128 v[198:201], v147 offset:52224
	ds_read_b128 v[202:205], v147 offset:53248
	ds_read_b128 v[206:209], v147 offset:54272
	ds_read_b128 v[210:213], v147 offset:55296
	ds_read_b128 v[214:217], v147 offset:56320
	global_load_lds_dwordx4 v[140:141], off
	v_lshl_add_u64 v[140:141], v[160:161], 0, s[8:9]
	s_mov_b32 m0, s72
	s_nop 0
	global_load_lds_dwordx4 v[140:141], off
	s_mov_b32 m0, s73
	s_nop 0
	global_load_lds_dwordx4 v132, s[48:49]
	s_mov_b32 m0, s71
	s_nop 0
	global_load_lds_dwordx4 v128, s[48:49]
	v_lshl_add_u64 v[140:141], v[218:219], 0, s[8:9]
	s_mov_b32 m0, s61
	s_nop 0
	global_load_lds_dwordx4 v[140:141], off
	v_lshl_add_u64 v[140:141], v[220:221], 0, s[8:9]
	s_mov_b32 m0, s62
	s_nop 0
	global_load_lds_dwordx4 v[140:141], off
	s_waitcnt vmcnt(8)
	s_waitcnt lgkmcnt(0)
	s_barrier
	s_waitcnt lgkmcnt(0)
	v_mfma_f32_16x16x32_bf16 v[60:63], v[148:151], v[186:189], v[60:63]
	v_mfma_f32_16x16x32_bf16 v[56:59], v[156:159], v[186:189], v[56:59]
	v_mfma_f32_16x16x32_bf16 v[52:55], v[148:151], v[194:197], v[52:55]
	v_mfma_f32_16x16x32_bf16 v[44:47], v[156:159], v[194:197], v[44:47]
	v_mfma_f32_16x16x32_bf16 v[36:39], v[148:151], v[202:205], v[36:39]
	v_mfma_f32_16x16x32_bf16 v[28:31], v[156:159], v[202:205], v[28:31]
	v_mfma_f32_16x16x32_bf16 v[20:23], v[148:151], v[210:213], v[20:23]
	v_mfma_f32_16x16x32_bf16 v[12:15], v[156:159], v[210:213], v[12:15]
	v_mfma_f32_16x16x32_bf16 v[60:63], v[152:155], v[190:193], v[60:63]
	v_mfma_f32_16x16x32_bf16 v[56:59], v[166:169], v[190:193], v[56:59]
	v_mfma_f32_16x16x32_bf16 v[52:55], v[152:155], v[198:201], v[52:55]
	v_mfma_f32_16x16x32_bf16 v[44:47], v[166:169], v[198:201], v[44:47]
	v_mfma_f32_16x16x32_bf16 v[36:39], v[152:155], v[206:209], v[36:39]
	v_mfma_f32_16x16x32_bf16 v[28:31], v[166:169], v[206:209], v[28:31]
	v_mfma_f32_16x16x32_bf16 v[20:23], v[152:155], v[214:217], v[20:23]
	v_mfma_f32_16x16x32_bf16 v[12:15], v[166:169], v[214:217], v[12:15]
	v_mfma_f32_16x16x32_bf16 v[48:51], v[170:173], v[186:189], v[48:51]
	v_mfma_f32_16x16x32_bf16 v[40:43], v[178:181], v[186:189], v[40:43]
	v_mfma_f32_16x16x32_bf16 v[32:35], v[170:173], v[194:197], v[32:35]
	v_mfma_f32_16x16x32_bf16 v[24:27], v[178:181], v[194:197], v[24:27]
	v_mfma_f32_16x16x32_bf16 v[16:19], v[170:173], v[202:205], v[16:19]
	v_mfma_f32_16x16x32_bf16 v[8:11], v[178:181], v[202:205], v[8:11]
	v_mfma_f32_16x16x32_bf16 v[4:7], v[170:173], v[210:213], v[4:7]
	v_mfma_f32_16x16x32_bf16 v[0:3], v[178:181], v[210:213], v[0:3]
	v_mfma_f32_16x16x32_bf16 v[48:51], v[174:177], v[190:193], v[48:51]
	v_mfma_f32_16x16x32_bf16 v[40:43], v[182:185], v[190:193], v[40:43]
	v_mfma_f32_16x16x32_bf16 v[32:35], v[174:177], v[198:201], v[32:35]
	v_mfma_f32_16x16x32_bf16 v[24:27], v[182:185], v[198:201], v[24:27]
	v_mfma_f32_16x16x32_bf16 v[16:19], v[174:177], v[206:209], v[16:19]
	v_mfma_f32_16x16x32_bf16 v[8:11], v[182:185], v[206:209], v[8:11]
	v_mfma_f32_16x16x32_bf16 v[4:7], v[174:177], v[214:217], v[4:7]
	v_mfma_f32_16x16x32_bf16 v[0:3], v[182:185], v[214:217], v[0:3]
	s_barrier
	s_movk_i32 s50, 0x100
	s_andn2_b64 vcc, exec, s[46:47]
	s_mov_b64 s[48:49], -1
	s_mov_b64 s[46:47], 0
	s_cbranch_vccz .LBB0_1262
	s_and_b64 vcc, exec, s[10:11]
	s_cbranch_vccz .LBB0_1265
	s_barrier

; #define PG8_STAGE(bufoff, gbase, voff) do { _Pragma("unroll") for (int _i = 0; _i < 2; ++_i) \
;         __builtin_amdgcn_global_load_lds((const unsigned*)((const char*)(gbase) + (voff)[_i]), (PG8_LAS unsigned*)(lds + (bufoff) + ldsw + _i * 8192), 16, 0, 0); } while (0)
; #define PG8_LDA(dst, b, h) do { _Pragma("unroll") for (int m = 0; m < 4; ++m) _Pragma("unroll") for (int k = 0; k < 2; ++k) dst[m][k] = *(const PG8_LAS bf16x8*)(lds + PG8_SA(b, h) + aoff + m * 2048 + k * 1024); } while (0)
; #define PG8_LDB(dst, b, h) do { _Pragma("unroll") for (int n = 0; n < 2; ++n) _Pragma("unroll") for (int k = 0; k < 2; ++k) dst[n][k] = *(const PG8_LAS bf16x8*)(lds + PG8_SB(b, h) + boff + n * 2048 + k * 1024); } while (0)
; #define PG8_MMA(ai, bj, At, Bt) do { __builtin_amdgcn_s_setprio(1); _Pragma("unroll") for (int m = 0; m < 4; ++m) _Pragma("unroll") for (int n = 0; n < 2; ++n) _Pragma("unroll") for (int k = 0; k < 2; ++k) \
;         acc[ai][bj][m][n] = __builtin_amdgcn_mfma_f32_16x16x32_bf16(Bt[n][k], At[m][k], acc[ai][bj][m][n], 0, 0, 0); __builtin_amdgcn_s_setprio(0); } while (0)
; #define PG8_WAIT_V(n) asm volatile("s_waitcnt vmcnt(" #n ")" ::: "memory")
; #define PG8_WAIT_L(n) asm volatile("s_waitcnt lgkmcnt(" #n ")" ::: "memory")
; template <class Epi, class Sched, bool ALIGN_EPI = false, bool SP2 = false>
; __device__ __forceinline__ void gemm_phase(PG8_LAS unsigned char* lds, const Gemm g, const Sched& S, const Epi& E) {
;     ...
;             const bool last = (t == nt - 2);
;             const char* a1 = cA + (size_t)(t + 1) * kstep;
;             const char* a2 = last ? nA : cA + (size_t)(t + 2) * kstep; const char* b2 = last ? nB : cB + (size_t)(t + 2) * kstep;
;             const char* a3 = a2 + kstep; const char* b3 = b2 + kstep;
;             if (last && has_next) S.a_ready(nxt);
;             if constexpr (SP2) {
;             PG8_LDB(B0, 0, 0); PG8_LDB(B1, 0, 1); PG8_SCHED; PG8_LDA(At, 0, 0); PG8_STAGE(PG8_SA(1, 1), a1 + hstepA, voffA);
;             PG8_WAIT_V(8); PG8_WAIT_L(0); PG8_BAR; PG8_MMA(0, 0, At, B0); PG8_MMA(0, 1, At, B1); PG8_BAR; PG8_SCHED;
;             PG8_LDA(At, 0, 1); PG8_STAGE(PG8_SB(0, 0), b2, voffB); PG8_STAGE(PG8_SB(0, 1), b2 + hstepB, voffB); PG8_STAGE(PG8_SA(0, 0), a2, voffA);
;             PG8_WAIT_V(8); PG8_WAIT_L(0); PG8_BAR; PG8_MMA(1, 0, At, B0); PG8_MMA(1, 1, At, B1); PG8_BAR; PG8_SCHED;
.LBB0_1333:
	ds_read_b128 v[144:147], v153
	ds_read_b128 v[156:159], v153 offset:1024
	ds_read_b128 v[166:169], v153 offset:2048
	ds_read_b128 v[170:173], v153 offset:3072
	ds_read_b128 v[174:177], v154
	ds_read_b128 v[178:181], v154 offset:1024
	ds_read_b128 v[182:185], v154 offset:2048
	ds_read_b128 v[186:189], v154 offset:3072
	s_add_u32 s46, s44, 0xfff80080
	s_addc_u32 s47, s45, -1
	s_cmp_eq_u32 s62, 28
	s_cselect_b32 s49, s37, s47
	s_cselect_b32 s48, s58, s46
	s_cselect_b32 s47, s23, s61
	s_cselect_b32 s46, s59, s60
	s_add_i32 m0, s30, 0xc000
	ds_read_b128 v[190:193], v155
	ds_read_b128 v[194:197], v155 offset:1024
	ds_read_b128 v[198:201], v155 offset:2048
	ds_read_b128 v[202:205], v155 offset:3072
	ds_read_b128 v[206:209], v155 offset:4096
	ds_read_b128 v[210:213], v155 offset:5120
	ds_read_b128 v[214:217], v155 offset:6144
	ds_read_b128 v[218:221], v155 offset:7168
	global_load_lds_dwordx4 v136, s[44:45]
	s_add_i32 m0, s30, 0xe000
	s_nop 0
	global_load_lds_dwordx4 v138, s[44:45]
	s_waitcnt vmcnt(8)
	s_waitcnt lgkmcnt(0)
	s_barrier
	s_waitcnt lgkmcnt(0)
	v_mfma_f32_16x16x32_bf16 v[124:127], v[144:147], v[190:193], v[124:127]
	v_mfma_f32_16x16x32_bf16 v[120:123], v[166:169], v[190:193], v[120:123]
	v_mfma_f32_16x16x32_bf16 v[108:111], v[144:147], v[198:201], v[108:111]
	v_mfma_f32_16x16x32_bf16 v[104:107], v[166:169], v[198:201], v[104:107]
	v_mfma_f32_16x16x32_bf16 v[92:95], v[144:147], v[206:209], v[92:95]
	v_mfma_f32_16x16x32_bf16 v[88:91], v[166:169], v[206:209], v[88:91]
	v_mfma_f32_16x16x32_bf16 v[76:79], v[144:147], v[214:217], v[76:79]
	v_mfma_f32_16x16x32_bf16 v[72:75], v[166:169], v[214:217], v[72:75]
	v_mfma_f32_16x16x32_bf16 v[124:127], v[156:159], v[194:197], v[124:127]
	v_mfma_f32_16x16x32_bf16 v[120:123], v[170:173], v[194:197], v[120:123]
	v_mfma_f32_16x16x32_bf16 v[108:111], v[156:159], v[202:205], v[108:111]
	v_mfma_f32_16x16x32_bf16 v[104:107], v[170:173], v[202:205], v[104:107]
	v_mfma_f32_16x16x32_bf16 v[92:95], v[156:159], v[210:213], v[92:95]
	v_mfma_f32_16x16x32_bf16 v[88:91], v[170:173], v[210:213], v[88:91]
	v_mfma_f32_16x16x32_bf16 v[76:79], v[156:159], v[218:221], v[76:79]
	v_mfma_f32_16x16x32_bf16 v[72:75], v[170:173], v[218:221], v[72:75]
	v_mfma_f32_16x16x32_bf16 v[116:119], v[174:177], v[190:193], v[116:119]
	v_mfma_f32_16x16x32_bf16 v[112:115], v[182:185], v[190:193], v[112:115]
	v_mfma_f32_16x16x32_bf16 v[100:103], v[174:177], v[198:201], v[100:103]
	v_mfma_f32_16x16x32_bf16 v[96:99], v[182:185], v[198:201], v[96:99]
	v_mfma_f32_16x16x32_bf16 v[84:87], v[174:177], v[206:209], v[84:87]
	v_mfma_f32_16x16x32_bf16 v[80:83], v[182:185], v[206:209], v[80:83]
	v_mfma_f32_16x16x32_bf16 v[68:71], v[174:177], v[214:217], v[68:71]
	v_mfma_f32_16x16x32_bf16 v[64:67], v[182:185], v[214:217], v[64:67]
	v_mfma_f32_16x16x32_bf16 v[116:119], v[178:181], v[194:197], v[116:119]
	v_mfma_f32_16x16x32_bf16 v[112:115], v[186:189], v[194:197], v[112:115]
	v_mfma_f32_16x16x32_bf16 v[100:103], v[178:181], v[202:205], v[100:103]
	v_mfma_f32_16x16x32_bf16 v[96:99], v[186:189], v[202:205], v[96:99]
	v_mfma_f32_16x16x32_bf16 v[84:87], v[178:181], v[210:213], v[84:87]
	v_mfma_f32_16x16x32_bf16 v[80:83], v[186:189], v[210:213], v[80:83]
	v_mfma_f32_16x16x32_bf16 v[68:71], v[178:181], v[218:221], v[68:71]
	v_mfma_f32_16x16x32_bf16 v[64:67], v[186:189], v[218:221], v[64:67]
	s_barrier
	s_add_i32 s63, s51, s28
	v_lshl_add_u64 v[148:149], s[46:47], 0, v[132:133]
	s_mov_b32 m0, s63
	ds_read_b128 v[190:193], v155 offset:16384
	ds_read_b128 v[194:197], v155 offset:17408
	ds_read_b128 v[198:201], v155 offset:18432
	ds_read_b128 v[202:205], v155 offset:19456
	ds_read_b128 v[206:209], v155 offset:20480
	ds_read_b128 v[210:213], v155 offset:21504
	ds_read_b128 v[214:217], v155 offset:22528
	ds_read_b128 v[218:221], v155 offset:23552
	global_load_lds_dwordx4 v132, s[46:47]
	s_add_i32 m0, s63, 0x2000
	s_add_u32 s64, s46, 0x80000
	v_lshl_add_u64 v[160:161], s[46:47], 0, v[128:129]
	s_addc_u32 s65, s47, 0
	s_add_i32 s63, s52, s28
	global_load_lds_dwordx4 v128, s[46:47]
	s_mov_b32 m0, s63
	v_lshl_add_u64 v[224:225], s[48:49], 0, v[130:131]
	global_load_lds_dwordx4 v132, s[64:65]
	s_add_i32 m0, s63, 0x2000
	s_nop 0
	global_load_lds_dwordx4 v128, s[64:65]
	v_lshl_add_u64 v[222:223], s[48:49], 0, v[134:135]
	s_mov_b32 m0, s30
	s_nop 0
	global_load_lds_dwordx4 v134, s[48:49]
	s_mov_b32 m0, s31
	s_nop 0
	global_load_lds_dwordx4 v130, s[48:49]
	s_waitcnt vmcnt(8)
	s_waitcnt lgkmcnt(0)
	s_barrier
	s_waitcnt lgkmcnt(0)
	v_mfma_f32_16x16x32_bf16 v[60:63], v[144:147], v[190:193], v[60:63]
	v_mfma_f32_16x16x32_bf16 v[56:59], v[166:169], v[190:193], v[56:59]
	v_mfma_f32_16x16x32_bf16 v[44:47], v[144:147], v[198:201], v[44:47]
	v_mfma_f32_16x16x32_bf16 v[40:43], v[166:169], v[198:201], v[40:43]
	v_mfma_f32_16x16x32_bf16 v[28:31], v[144:147], v[206:209], v[28:31]
	v_mfma_f32_16x16x32_bf16 v[24:27], v[166:169], v[206:209], v[24:27]
	v_mfma_f32_16x16x32_bf16 v[12:15], v[144:147], v[214:217], v[12:15]
	v_mfma_f32_16x16x32_bf16 v[8:11], v[166:169], v[214:217], v[8:11]
	v_mfma_f32_16x16x32_bf16 v[60:63], v[156:159], v[194:197], v[60:63]
	v_mfma_f32_16x16x32_bf16 v[56:59], v[170:173], v[194:197], v[56:59]
	v_mfma_f32_16x16x32_bf16 v[44:47], v[156:159], v[202:205], v[44:47]
	v_mfma_f32_16x16x32_bf16 v[40:43], v[170:173], v[202:205], v[40:43]
	v_mfma_f32_16x16x32_bf16 v[28:31], v[156:159], v[210:213], v[28:31]
	v_mfma_f32_16x16x32_bf16 v[24:27], v[170:173], v[210:213], v[24:27]
	v_mfma_f32_16x16x32_bf16 v[12:15], v[156:159], v[218:221], v[12:15]
	v_mfma_f32_16x16x32_bf16 v[8:11], v[170:173], v[218:221], v[8:11]
	v_mfma_f32_16x16x32_bf16 v[52:55], v[174:177], v[190:193], v[52:55]
	v_mfma_f32_16x16x32_bf16 v[48:51], v[182:185], v[190:193], v[48:51]
	v_mfma_f32_16x16x32_bf16 v[36:39], v[174:177], v[198:201], v[36:39]
	v_mfma_f32_16x16x32_bf16 v[32:35], v[182:185], v[198:201], v[32:35]
	v_mfma_f32_16x16x32_bf16 v[20:23], v[174:177], v[206:209], v[20:23]
	v_mfma_f32_16x16x32_bf16 v[16:19], v[182:185], v[206:209], v[16:19]
	v_mfma_f32_16x16x32_bf16 v[4:7], v[174:177], v[214:217], v[4:7]
	v_mfma_f32_16x16x32_bf16 v[0:3], v[182:185], v[214:217], v[0:3]
	v_mfma_f32_16x16x32_bf16 v[52:55], v[178:181], v[194:197], v[52:55]
	v_mfma_f32_16x16x32_bf16 v[48:51], v[186:189], v[194:197], v[48:51]
	v_mfma_f32_16x16x32_bf16 v[36:39], v[178:181], v[202:205], v[36:39]
	v_mfma_f32_16x16x32_bf16 v[32:35], v[186:189], v[202:205], v[32:35]
	v_mfma_f32_16x16x32_bf16 v[20:23], v[178:181], v[210:213], v[20:23]
	v_mfma_f32_16x16x32_bf16 v[16:19], v[186:189], v[210:213], v[16:19]
	v_mfma_f32_16x16x32_bf16 v[4:7], v[178:181], v[218:221], v[4:7]
	v_mfma_f32_16x16x32_bf16 v[0:3], v[186:189], v[218:221], v[0:3]
	s_barrier
; #define PG8_STAGE(bufoff, gbase, voff) do { _Pragma("unroll") for (int _i = 0; _i < 2; ++_i) \
;         __builtin_amdgcn_global_load_lds((const unsigned*)((const char*)(gbase) + (voff)[_i]), (PG8_LAS unsigned*)(lds + (bufoff) + ldsw + _i * 8192), 16, 0, 0); } while (0)
; #define PG8_LDA(dst, b, h) do { _Pragma("unroll") for (int m = 0; m < 4; ++m) _Pragma("unroll") for (int k = 0; k < 2; ++k) dst[m][k] = *(const PG8_LAS bf16x8*)(lds + PG8_SA(b, h) + aoff + m * 2048 + k * 1024); } while (0)
; #define PG8_LDB(dst, b, h) do { _Pragma("unroll") for (int n = 0; n < 2; ++n) _Pragma("unroll") for (int k = 0; k < 2; ++k) dst[n][k] = *(const PG8_LAS bf16x8*)(lds + PG8_SB(b, h) + boff + n * 2048 + k * 1024); } while (0)
; #define PG8_MMA(ai, bj, At, Bt) do { __builtin_amdgcn_s_setprio(1); _Pragma("unroll") for (int m = 0; m < 4; ++m) _Pragma("unroll") for (int n = 0; n < 2; ++n) _Pragma("unroll") for (int k = 0; k < 2; ++k) \
;         acc[ai][bj][m][n] = __builtin_amdgcn_mfma_f32_16x16x32_bf16(Bt[n][k], At[m][k], acc[ai][bj][m][n], 0, 0, 0); __builtin_amdgcn_s_setprio(0); } while (0)
; #define PG8_WAIT_V(n) asm volatile("s_waitcnt vmcnt(" #n ")" ::: "memory")
; #define PG8_WAIT_L(n) asm volatile("s_waitcnt lgkmcnt(" #n ")" ::: "memory")
; #define PG8_BAR __builtin_amdgcn_s_barrier()
; #define PG8_SCHED __builtin_amdgcn_sched_barrier(0)
; template <class Epi, class Sched, bool ALIGN_EPI = false, bool SP2 = false>
; __device__ __forceinline__ void gemm_phase(PG8_LAS unsigned char* lds, const Gemm g, const Sched& S, const Epi& E) {
;     ...
;         for (int t = 0; t < nt; t += 2) {
;     ...
;             PG8_LDB(B0, 1, 0); PG8_LDB(B1, 1, 1); PG8_SCHED; PG8_LDA(At, 1, 0); PG8_STAGE(PG8_SA(0, 1), a2 + hstepA, voffA);
;             PG8_WAIT_V(8); PG8_WAIT_L(0); PG8_BAR; PG8_MMA(0, 0, At, B0); PG8_MMA(0, 1, At, B1); PG8_BAR; PG8_SCHED;
;             PG8_LDA(At, 1, 1); PG8_STAGE(PG8_SB(1, 0), b3, voffB); PG8_STAGE(PG8_SB(1, 1), b3 + hstepB, voffB); PG8_STAGE(PG8_SA(1, 0), a3, voffA);
;             PG8_WAIT_V(8); PG8_WAIT_L(0); PG8_BAR; PG8_MMA(1, 0, At, B0); PG8_MMA(1, 1, At, B1); PG8_BAR; PG8_SCHED;
	s_add_i32 s63, 0, 0x18000
	v_add_u32_e32 v163, s63, v151
	s_add_i32 s64, 0, 0x1c000
	ds_read_b128 v[144:147], v163
	ds_read_b128 v[156:159], v163 offset:1024
	ds_read_b128 v[166:169], v163 offset:2048
	ds_read_b128 v[170:173], v163 offset:3072
	v_add_u32_e32 v163, s64, v151
	ds_read_b128 v[174:177], v163
	ds_read_b128 v[178:181], v163 offset:1024
	ds_read_b128 v[182:185], v163 offset:2048
	ds_read_b128 v[186:189], v163 offset:3072
	s_add_u32 s48, s48, 0x80000
	s_addc_u32 s49, s49, 0
	s_mov_b32 m0, s33
	ds_read_b128 v[190:193], v155 offset:32768
	ds_read_b128 v[194:197], v155 offset:33792
	ds_read_b128 v[198:201], v155 offset:34816
	ds_read_b128 v[202:205], v155 offset:35840
	ds_read_b128 v[206:209], v155 offset:36864
	ds_read_b128 v[210:213], v155 offset:37888
	ds_read_b128 v[214:217], v155 offset:38912
	ds_read_b128 v[218:221], v155 offset:39936
	global_load_lds_dwordx4 v134, s[48:49]
	s_mov_b32 m0, s34
	s_nop 0
	global_load_lds_dwordx4 v130, s[48:49]
	s_waitcnt vmcnt(8)
	s_waitcnt lgkmcnt(0)
	s_barrier
	s_waitcnt lgkmcnt(0)
	v_mfma_f32_16x16x32_bf16 v[124:127], v[144:147], v[190:193], v[124:127]
	v_mfma_f32_16x16x32_bf16 v[120:123], v[166:169], v[190:193], v[120:123]
	v_mfma_f32_16x16x32_bf16 v[108:111], v[144:147], v[198:201], v[108:111]
	v_mfma_f32_16x16x32_bf16 v[104:107], v[166:169], v[198:201], v[104:107]
	v_mfma_f32_16x16x32_bf16 v[92:95], v[144:147], v[206:209], v[92:95]
	v_mfma_f32_16x16x32_bf16 v[88:91], v[166:169], v[206:209], v[88:91]
	v_mfma_f32_16x16x32_bf16 v[76:79], v[144:147], v[214:217], v[76:79]
	v_mfma_f32_16x16x32_bf16 v[72:75], v[166:169], v[214:217], v[72:75]
	v_mfma_f32_16x16x32_bf16 v[124:127], v[156:159], v[194:197], v[124:127]
	v_mfma_f32_16x16x32_bf16 v[120:123], v[170:173], v[194:197], v[120:123]
	v_mfma_f32_16x16x32_bf16 v[108:111], v[156:159], v[202:205], v[108:111]
	v_mfma_f32_16x16x32_bf16 v[104:107], v[170:173], v[202:205], v[104:107]
	v_mfma_f32_16x16x32_bf16 v[92:95], v[156:159], v[210:213], v[92:95]
	v_mfma_f32_16x16x32_bf16 v[88:91], v[170:173], v[210:213], v[88:91]
	v_mfma_f32_16x16x32_bf16 v[76:79], v[156:159], v[218:221], v[76:79]
	v_mfma_f32_16x16x32_bf16 v[72:75], v[170:173], v[218:221], v[72:75]
	v_mfma_f32_16x16x32_bf16 v[116:119], v[174:177], v[190:193], v[116:119]
	v_mfma_f32_16x16x32_bf16 v[112:115], v[182:185], v[190:193], v[112:115]
	v_mfma_f32_16x16x32_bf16 v[100:103], v[174:177], v[198:201], v[100:103]
	v_mfma_f32_16x16x32_bf16 v[96:99], v[182:185], v[198:201], v[96:99]
	v_mfma_f32_16x16x32_bf16 v[84:87], v[174:177], v[206:209], v[84:87]
	v_mfma_f32_16x16x32_bf16 v[80:83], v[182:185], v[206:209], v[80:83]
	v_mfma_f32_16x16x32_bf16 v[68:71], v[174:177], v[214:217], v[68:71]
	v_mfma_f32_16x16x32_bf16 v[64:67], v[182:185], v[214:217], v[64:67]
	v_mfma_f32_16x16x32_bf16 v[116:119], v[178:181], v[194:197], v[116:119]
	v_mfma_f32_16x16x32_bf16 v[112:115], v[186:189], v[194:197], v[112:115]
	v_mfma_f32_16x16x32_bf16 v[100:103], v[178:181], v[202:205], v[100:103]
	v_mfma_f32_16x16x32_bf16 v[96:99], v[186:189], v[202:205], v[96:99]
	v_mfma_f32_16x16x32_bf16 v[84:87], v[178:181], v[210:213], v[84:87]
	v_mfma_f32_16x16x32_bf16 v[80:83], v[186:189], v[210:213], v[80:83]
	v_mfma_f32_16x16x32_bf16 v[68:71], v[178:181], v[218:221], v[68:71]
	v_mfma_f32_16x16x32_bf16 v[64:67], v[186:189], v[218:221], v[64:67]
	s_barrier
	s_add_i32 s48, s63, s28
	v_lshl_add_u64 v[148:149], v[148:149], 0, s[10:11]
	s_mov_b32 m0, s48
	ds_read_b128 v[190:193], v155 offset:49152
	ds_read_b128 v[194:197], v155 offset:50176
	ds_read_b128 v[198:201], v155 offset:51200
	ds_read_b128 v[202:205], v155 offset:52224
	ds_read_b128 v[206:209], v155 offset:53248
	ds_read_b128 v[210:213], v155 offset:54272
	ds_read_b128 v[214:217], v155 offset:55296
	ds_read_b128 v[218:221], v155 offset:56320
	global_load_lds_dwordx4 v[148:149], off
	s_add_i32 m0, s48, 0x2000
	s_add_u32 s46, s46, 0x80080
	v_lshl_add_u64 v[148:149], v[160:161], 0, s[10:11]
	s_addc_u32 s47, s47, 0
	s_add_i32 s48, s64, s28
	global_load_lds_dwordx4 v[148:149], off
	s_mov_b32 m0, s48
	s_nop 0
	global_load_lds_dwordx4 v132, s[46:47]
	s_add_i32 m0, s48, 0x2000
	s_nop 0
	global_load_lds_dwordx4 v128, s[46:47]
	v_lshl_add_u64 v[148:149], v[222:223], 0, s[10:11]
	s_mov_b32 m0, s43
	s_nop 0
	global_load_lds_dwordx4 v[148:149], off
	v_lshl_add_u64 v[148:149], v[224:225], 0, s[10:11]
	s_mov_b32 m0, s50
	s_nop 0
	global_load_lds_dwordx4 v[148:149], off
	s_waitcnt vmcnt(8)
	s_waitcnt lgkmcnt(0)
	s_barrier
	s_waitcnt lgkmcnt(0)
	v_mfma_f32_16x16x32_bf16 v[60:63], v[144:147], v[190:193], v[60:63]
	v_mfma_f32_16x16x32_bf16 v[56:59], v[166:169], v[190:193], v[56:59]
	v_mfma_f32_16x16x32_bf16 v[44:47], v[144:147], v[198:201], v[44:47]
	v_mfma_f32_16x16x32_bf16 v[40:43], v[166:169], v[198:201], v[40:43]
	v_mfma_f32_16x16x32_bf16 v[28:31], v[144:147], v[206:209], v[28:31]
	v_mfma_f32_16x16x32_bf16 v[24:27], v[166:169], v[206:209], v[24:27]
	v_mfma_f32_16x16x32_bf16 v[12:15], v[144:147], v[214:217], v[12:15]
	v_mfma_f32_16x16x32_bf16 v[8:11], v[166:169], v[214:217], v[8:11]
	v_mfma_f32_16x16x32_bf16 v[60:63], v[156:159], v[194:197], v[60:63]
	v_mfma_f32_16x16x32_bf16 v[56:59], v[170:173], v[194:197], v[56:59]
	v_mfma_f32_16x16x32_bf16 v[44:47], v[156:159], v[202:205], v[44:47]
	v_mfma_f32_16x16x32_bf16 v[40:43], v[170:173], v[202:205], v[40:43]
	v_mfma_f32_16x16x32_bf16 v[28:31], v[156:159], v[210:213], v[28:31]
	v_mfma_f32_16x16x32_bf16 v[24:27], v[170:173], v[210:213], v[24:27]
	v_mfma_f32_16x16x32_bf16 v[12:15], v[156:159], v[218:221], v[12:15]
	v_mfma_f32_16x16x32_bf16 v[8:11], v[170:173], v[218:221], v[8:11]
	v_mfma_f32_16x16x32_bf16 v[52:55], v[174:177], v[190:193], v[52:55]
	v_mfma_f32_16x16x32_bf16 v[48:51], v[182:185], v[190:193], v[48:51]
	v_mfma_f32_16x16x32_bf16 v[36:39], v[174:177], v[198:201], v[36:39]
	v_mfma_f32_16x16x32_bf16 v[32:35], v[182:185], v[198:201], v[32:35]
	v_mfma_f32_16x16x32_bf16 v[20:23], v[174:177], v[206:209], v[20:23]
	v_mfma_f32_16x16x32_bf16 v[16:19], v[182:185], v[206:209], v[16:19]
	v_mfma_f32_16x16x32_bf16 v[4:7], v[174:177], v[214:217], v[4:7]
	v_mfma_f32_16x16x32_bf16 v[0:3], v[182:185], v[214:217], v[0:3]
	v_mfma_f32_16x16x32_bf16 v[52:55], v[178:181], v[194:197], v[52:55]
	v_mfma_f32_16x16x32_bf16 v[48:51], v[186:189], v[194:197], v[48:51]
	v_mfma_f32_16x16x32_bf16 v[36:39], v[178:181], v[202:205], v[36:39]
	v_mfma_f32_16x16x32_bf16 v[32:35], v[186:189], v[202:205], v[32:35]
	v_mfma_f32_16x16x32_bf16 v[20:23], v[178:181], v[210:213], v[20:23]
	v_mfma_f32_16x16x32_bf16 v[16:19], v[186:189], v[210:213], v[16:19]
	v_mfma_f32_16x16x32_bf16 v[4:7], v[178:181], v[218:221], v[4:7]
	v_mfma_f32_16x16x32_bf16 v[0:3], v[186:189], v[218:221], v[0:3]
	s_barrier
	s_add_i32 s62, s62, 2
	s_add_u32 s44, s44, 0x100
	s_addc_u32 s45, s45, 0
	s_add_u32 s60, s60, 0x100
	s_addc_u32 s61, s61, 0
	s_cmp_gt_u32 s62, 29
	s_cbranch_scc0 .LBB0_1333
	s_and_b64 vcc, exec, s[14:15]
	s_cbranch_vccz .LBB0_1336
	s_barrier
